# late fragment reads also in FFN-down and outproj dual-tile loops
# baseline (speedup 1.0000x reference)
.Lhw_outproj_tloop:
	s_cmpk_gt_u32 s16, 47
	s_cbranch_scc1 .Lhw_outproj_exit
	v_readlane_b32 s6, v246, 16
	s_lshr_b32 s2, s16, 2
	s_and_b32 s15, s16, 3
	s_add_i32 s6, s6, s2
	s_lshl_b32 s6, s6, 7
	s_lshl_b32 s15, s15, 8
	s_mul_i32 vcc_lo, s6, 0x800
	s_add_u32 s66, s42, vcc_lo
	s_addc_u32 s67, s43, 0
	s_mul_i32 vcc_lo, s15, 0x800
	s_add_u32 s62, s46, vcc_lo
	s_addc_u32 s63, s47, 0
	s_add_u32 s18, s62, 0x40000
	s_addc_u32 s19, s63, 0
	s_barrier
	s_add_u32 m0, s65, 0x0
	s_nop 0
	global_load_lds_dwordx4 v160, s[66:67]
	s_add_u32 m0, s65, 0x1000
	s_nop 0
	global_load_lds_dwordx4 v161, s[66:67]
	s_add_u32 m0, s65, 0x2000
	s_nop 0
	global_load_lds_dwordx4 v160, s[62:63]
	s_add_u32 m0, s65, 0x3000
	s_nop 0
	global_load_lds_dwordx4 v161, s[62:63]
	s_add_u32 m0, s65, 0x4000
	s_nop 0
	global_load_lds_dwordx4 v160, s[18:19]
	s_add_u32 m0, s65, 0x5000
	s_nop 0
	global_load_lds_dwordx4 v161, s[18:19]
	s_add_u32 s66, s66, 64
	s_addc_u32 s67, s67, 0
	s_add_u32 s62, s62, 64
	s_addc_u32 s63, s63, 0
	s_add_u32 s18, s18, 64
	s_addc_u32 s19, s19, 0
	s_add_u32 m0, s65, 0x6000
	s_nop 0
	global_load_lds_dwordx4 v160, s[66:67]
	s_add_u32 m0, s65, 0x7000
	s_nop 0
	global_load_lds_dwordx4 v161, s[66:67]
	s_add_u32 m0, s65, 0x8000
	s_nop 0
	global_load_lds_dwordx4 v160, s[62:63]
	s_add_u32 m0, s65, 0x9000
	s_nop 0
	global_load_lds_dwordx4 v161, s[62:63]
	s_add_u32 m0, s65, 0xa000
	s_nop 0
	global_load_lds_dwordx4 v160, s[18:19]
	s_add_u32 m0, s65, 0xb000
	s_nop 0
	global_load_lds_dwordx4 v161, s[18:19]
	s_add_u32 s66, s66, 64
	s_addc_u32 s67, s67, 0
	s_add_u32 s62, s62, 64
	s_addc_u32 s63, s63, 0
	s_add_u32 s18, s18, 64
	s_addc_u32 s19, s19, 0
	v_mov_b32_e32 v2, 0
	v_mov_b32_e32 v3, 0
	v_mov_b32_e32 v4, 0
	v_mov_b32_e32 v5, 0
	v_mov_b32_e32 v6, 0
	v_mov_b32_e32 v7, 0
	v_mov_b32_e32 v8, 0
	v_mov_b32_e32 v9, 0
	v_mov_b32_e32 v10, 0
	v_mov_b32_e32 v11, 0
	v_mov_b32_e32 v12, 0
	v_mov_b32_e32 v13, 0
	v_mov_b32_e32 v14, 0
	v_mov_b32_e32 v15, 0
	v_mov_b32_e32 v16, 0
	v_mov_b32_e32 v17, 0
	v_mov_b32_e32 v18, 0
	v_mov_b32_e32 v19, 0
	v_mov_b32_e32 v20, 0
	v_mov_b32_e32 v21, 0
	v_mov_b32_e32 v22, 0
	v_mov_b32_e32 v23, 0
	v_mov_b32_e32 v24, 0
	v_mov_b32_e32 v25, 0
	v_mov_b32_e32 v26, 0
	v_mov_b32_e32 v27, 0
	v_mov_b32_e32 v28, 0
	v_mov_b32_e32 v29, 0
	v_mov_b32_e32 v30, 0
	v_mov_b32_e32 v31, 0
	v_mov_b32_e32 v32, 0
	v_mov_b32_e32 v33, 0
	v_mov_b32_e32 v34, 0
	v_mov_b32_e32 v35, 0
	v_mov_b32_e32 v36, 0
	v_mov_b32_e32 v37, 0
	v_mov_b32_e32 v38, 0
	v_mov_b32_e32 v39, 0
	v_mov_b32_e32 v40, 0
	v_mov_b32_e32 v41, 0
	v_mov_b32_e32 v42, 0
	v_mov_b32_e32 v43, 0
	v_mov_b32_e32 v44, 0
	v_mov_b32_e32 v45, 0
	v_mov_b32_e32 v46, 0
	v_mov_b32_e32 v47, 0
	v_mov_b32_e32 v48, 0
	v_mov_b32_e32 v49, 0
	v_mov_b32_e32 v50, 0
	v_mov_b32_e32 v51, 0
	v_mov_b32_e32 v52, 0
	v_mov_b32_e32 v53, 0
	v_mov_b32_e32 v54, 0
	v_mov_b32_e32 v55, 0
	v_mov_b32_e32 v56, 0
	v_mov_b32_e32 v57, 0
	v_mov_b32_e32 v58, 0
	v_mov_b32_e32 v59, 0
	v_mov_b32_e32 v60, 0
	v_mov_b32_e32 v61, 0
	v_mov_b32_e32 v62, 0
	v_mov_b32_e32 v63, 0
	v_mov_b32_e32 v64, 0
	v_mov_b32_e32 v65, 0
	v_mov_b32_e32 v66, 0
	v_mov_b32_e32 v67, 0
	v_mov_b32_e32 v68, 0
	v_mov_b32_e32 v69, 0
	v_mov_b32_e32 v70, 0
	v_mov_b32_e32 v71, 0
	v_mov_b32_e32 v72, 0
	v_mov_b32_e32 v73, 0
	v_mov_b32_e32 v74, 0
	v_mov_b32_e32 v75, 0
	v_mov_b32_e32 v76, 0
	v_mov_b32_e32 v77, 0
	v_mov_b32_e32 v78, 0
	v_mov_b32_e32 v79, 0
	v_mov_b32_e32 v80, 0
	v_mov_b32_e32 v81, 0
	v_mov_b32_e32 v82, 0
	v_mov_b32_e32 v83, 0
	v_mov_b32_e32 v84, 0
	v_mov_b32_e32 v85, 0
	v_mov_b32_e32 v86, 0
	v_mov_b32_e32 v87, 0
	v_mov_b32_e32 v88, 0
	v_mov_b32_e32 v89, 0
	v_mov_b32_e32 v90, 0
	v_mov_b32_e32 v91, 0
	v_mov_b32_e32 v92, 0
	v_mov_b32_e32 v93, 0
	v_mov_b32_e32 v94, 0
	v_mov_b32_e32 v95, 0
	v_mov_b32_e32 v96, 0
	v_mov_b32_e32 v97, 0
	v_mov_b32_e32 v98, 0
	v_mov_b32_e32 v99, 0
	v_mov_b32_e32 v100, 0
	v_mov_b32_e32 v101, 0
	v_mov_b32_e32 v102, 0
	v_mov_b32_e32 v103, 0
	v_mov_b32_e32 v104, 0
	v_mov_b32_e32 v105, 0
	v_mov_b32_e32 v106, 0
	v_mov_b32_e32 v107, 0
	v_mov_b32_e32 v108, 0
	v_mov_b32_e32 v109, 0
	v_mov_b32_e32 v110, 0
	v_mov_b32_e32 v111, 0
	v_mov_b32_e32 v112, 0
	v_mov_b32_e32 v113, 0
	v_mov_b32_e32 v114, 0
	v_mov_b32_e32 v115, 0
	v_mov_b32_e32 v116, 0
	v_mov_b32_e32 v117, 0
	v_mov_b32_e32 v118, 0
	v_mov_b32_e32 v119, 0
	v_mov_b32_e32 v120, 0
	v_mov_b32_e32 v121, 0
	v_mov_b32_e32 v122, 0
	v_mov_b32_e32 v123, 0
	v_mov_b32_e32 v124, 0
	v_mov_b32_e32 v125, 0
	v_mov_b32_e32 v126, 0
	v_mov_b32_e32 v127, 0
	v_mov_b32_e32 v128, 0
	v_mov_b32_e32 v129, 0
	s_mov_b32 s59, 10
.Lhw_outproj_loop:
	s_waitcnt vmcnt(6)
	s_barrier
	ds_read_b128 v[130:133], v154 offset:16
	ds_read_b128 v[138:141], v156 offset:8208
	ds_read_b128 v[142:145], v156 offset:10256
	ds_read_b128 v[134:137], v154 offset:2064
	ds_read_b128 v[146:149], v158 offset:8208
	ds_read_b128 v[150:153], v158 offset:10256
	s_waitcnt lgkmcnt(4)
	v_mfma_f32_32x32x16_bf16 v[2:17], v[130:133], v[138:141], v[2:17]
	ds_read_b128 v[212:215], v155 offset:16
	s_add_u32 m0, s65, 0xc000
	s_waitcnt lgkmcnt(4)
	v_mfma_f32_32x32x16_bf16 v[18:33], v[130:133], v[142:145], v[18:33]
	ds_read_b128 v[220:223], v157 offset:8208
	global_load_lds_dwordx4 v160, s[66:67]
	s_waitcnt lgkmcnt(4)
	v_mfma_f32_32x32x16_bf16 v[34:49], v[134:137], v[138:141], v[34:49]
	ds_read_b128 v[224:227], v157 offset:10256
	s_add_u32 m0, s65, 0xd000
	s_waitcnt lgkmcnt(5)
	v_mfma_f32_32x32x16_bf16 v[50:65], v[134:137], v[142:145], v[50:65]
	ds_read_b128 v[216:219], v155 offset:2064
	global_load_lds_dwordx4 v161, s[66:67]
	s_waitcnt lgkmcnt(5)
	v_mfma_f32_32x32x16_bf16 v[66:81], v[130:133], v[146:149], v[66:81]
	ds_read_b128 v[228:231], v159 offset:8208
	s_add_u32 m0, s65, 0xe000
	s_waitcnt lgkmcnt(5)
	v_mfma_f32_32x32x16_bf16 v[82:97], v[130:133], v[150:153], v[82:97]
	ds_read_b128 v[232:235], v159 offset:10256
	global_load_lds_dwordx4 v160, s[62:63]
	s_waitcnt lgkmcnt(7)
	v_mfma_f32_32x32x16_bf16 v[98:113], v[134:137], v[146:149], v[98:113]
	s_add_u32 m0, s65, 0xf000
	s_waitcnt lgkmcnt(6)
	v_mfma_f32_32x32x16_bf16 v[114:129], v[134:137], v[150:153], v[114:129]
	global_load_lds_dwordx4 v161, s[62:63]
	s_waitcnt lgkmcnt(4)
	v_mfma_f32_32x32x16_bf16 v[2:17], v[212:215], v[220:223], v[2:17]
	s_add_u32 m0, s65, 0x10000
	s_waitcnt lgkmcnt(3)
	v_mfma_f32_32x32x16_bf16 v[18:33], v[212:215], v[224:227], v[18:33]
	global_load_lds_dwordx4 v160, s[18:19]
	s_waitcnt lgkmcnt(2)
	v_mfma_f32_32x32x16_bf16 v[34:49], v[216:219], v[220:223], v[34:49]
	s_add_u32 m0, s65, 0x11000
	s_waitcnt lgkmcnt(2)
	v_mfma_f32_32x32x16_bf16 v[50:65], v[216:219], v[224:227], v[50:65]
	global_load_lds_dwordx4 v161, s[18:19]
	s_waitcnt lgkmcnt(1)
	v_mfma_f32_32x32x16_bf16 v[66:81], v[212:215], v[228:231], v[66:81]
	s_add_u32 s66, s66, 64
	s_addc_u32 s67, s67, 0
	s_waitcnt lgkmcnt(0)
	v_mfma_f32_32x32x16_bf16 v[82:97], v[212:215], v[232:235], v[82:97]
	s_add_u32 s62, s62, 64
	s_addc_u32 s63, s63, 0
	s_waitcnt lgkmcnt(1)
	v_mfma_f32_32x32x16_bf16 v[98:113], v[216:219], v[228:231], v[98:113]
	s_add_u32 s18, s18, 64
	s_addc_u32 s19, s19, 0
	s_waitcnt lgkmcnt(0)
	v_mfma_f32_32x32x16_bf16 v[114:129], v[216:219], v[232:235], v[114:129]
	s_waitcnt vmcnt(6)
	s_barrier
	ds_read_b128 v[130:133], v154 offset:24592
	ds_read_b128 v[138:141], v156 offset:32784
	ds_read_b128 v[142:145], v156 offset:34832
	ds_read_b128 v[134:137], v154 offset:26640
	ds_read_b128 v[146:149], v158 offset:32784
	ds_read_b128 v[150:153], v158 offset:34832
	s_waitcnt lgkmcnt(4)
	v_mfma_f32_32x32x16_bf16 v[2:17], v[130:133], v[138:141], v[2:17]
	ds_read_b128 v[212:215], v155 offset:24592
	s_add_u32 m0, s65, 0x0
	s_waitcnt lgkmcnt(4)
	v_mfma_f32_32x32x16_bf16 v[18:33], v[130:133], v[142:145], v[18:33]
	ds_read_b128 v[220:223], v157 offset:32784
	global_load_lds_dwordx4 v160, s[66:67]
	s_waitcnt lgkmcnt(4)
	v_mfma_f32_32x32x16_bf16 v[34:49], v[134:137], v[138:141], v[34:49]
	ds_read_b128 v[224:227], v157 offset:34832
	s_add_u32 m0, s65, 0x1000
	s_waitcnt lgkmcnt(5)
	v_mfma_f32_32x32x16_bf16 v[50:65], v[134:137], v[142:145], v[50:65]
	ds_read_b128 v[216:219], v155 offset:26640
	global_load_lds_dwordx4 v161, s[66:67]
	s_waitcnt lgkmcnt(5)
	v_mfma_f32_32x32x16_bf16 v[66:81], v[130:133], v[146:149], v[66:81]
	ds_read_b128 v[228:231], v159 offset:32784
	s_add_u32 m0, s65, 0x2000
	s_waitcnt lgkmcnt(5)
	v_mfma_f32_32x32x16_bf16 v[82:97], v[130:133], v[150:153], v[82:97]
	ds_read_b128 v[232:235], v159 offset:34832
	global_load_lds_dwordx4 v160, s[62:63]
	s_waitcnt lgkmcnt(7)
	v_mfma_f32_32x32x16_bf16 v[98:113], v[134:137], v[146:149], v[98:113]
	s_add_u32 m0, s65, 0x3000
	s_waitcnt lgkmcnt(6)
	v_mfma_f32_32x32x16_bf16 v[114:129], v[134:137], v[150:153], v[114:129]
	global_load_lds_dwordx4 v161, s[62:63]
	s_waitcnt lgkmcnt(4)
	v_mfma_f32_32x32x16_bf16 v[2:17], v[212:215], v[220:223], v[2:17]
	s_add_u32 m0, s65, 0x4000
	s_waitcnt lgkmcnt(3)
	v_mfma_f32_32x32x16_bf16 v[18:33], v[212:215], v[224:227], v[18:33]
	global_load_lds_dwordx4 v160, s[18:19]
	s_waitcnt lgkmcnt(2)
	v_mfma_f32_32x32x16_bf16 v[34:49], v[216:219], v[220:223], v[34:49]
	s_add_u32 m0, s65, 0x5000
	s_waitcnt lgkmcnt(2)
	v_mfma_f32_32x32x16_bf16 v[50:65], v[216:219], v[224:227], v[50:65]
	global_load_lds_dwordx4 v161, s[18:19]
	s_waitcnt lgkmcnt(1)
	v_mfma_f32_32x32x16_bf16 v[66:81], v[212:215], v[228:231], v[66:81]
	s_add_u32 s66, s66, 64
	s_addc_u32 s67, s67, 0
	s_waitcnt lgkmcnt(0)
	v_mfma_f32_32x32x16_bf16 v[82:97], v[212:215], v[232:235], v[82:97]
	s_add_u32 s62, s62, 64
	s_addc_u32 s63, s63, 0
	s_waitcnt lgkmcnt(1)
	v_mfma_f32_32x32x16_bf16 v[98:113], v[216:219], v[228:231], v[98:113]
	s_add_u32 s18, s18, 64
	s_addc_u32 s19, s19, 0
	s_waitcnt lgkmcnt(0)
	v_mfma_f32_32x32x16_bf16 v[114:129], v[216:219], v[232:235], v[114:129]
	s_waitcnt vmcnt(6)
	s_barrier
	ds_read_b128 v[130:133], v154 offset:49168
	ds_read_b128 v[138:141], v156 offset:57360
	ds_read_b128 v[142:145], v156 offset:59408
	ds_read_b128 v[134:137], v154 offset:51216
	ds_read_b128 v[146:149], v158 offset:57360
	ds_read_b128 v[150:153], v158 offset:59408
	s_waitcnt lgkmcnt(4)
	v_mfma_f32_32x32x16_bf16 v[2:17], v[130:133], v[138:141], v[2:17]
	ds_read_b128 v[212:215], v155 offset:49168
	s_add_u32 m0, s65, 0x6000
	s_waitcnt lgkmcnt(4)
	v_mfma_f32_32x32x16_bf16 v[18:33], v[130:133], v[142:145], v[18:33]
	ds_read_b128 v[220:223], v157 offset:57360
	global_load_lds_dwordx4 v160, s[66:67]
	s_waitcnt lgkmcnt(4)
	v_mfma_f32_32x32x16_bf16 v[34:49], v[134:137], v[138:141], v[34:49]
	ds_read_b128 v[224:227], v157 offset:59408
	s_add_u32 m0, s65, 0x7000
	s_waitcnt lgkmcnt(5)
	v_mfma_f32_32x32x16_bf16 v[50:65], v[134:137], v[142:145], v[50:65]
	ds_read_b128 v[216:219], v155 offset:51216
	global_load_lds_dwordx4 v161, s[66:67]
	s_waitcnt lgkmcnt(5)
	v_mfma_f32_32x32x16_bf16 v[66:81], v[130:133], v[146:149], v[66:81]
	ds_read_b128 v[228:231], v159 offset:57360
	s_add_u32 m0, s65, 0x8000
	s_waitcnt lgkmcnt(5)
	v_mfma_f32_32x32x16_bf16 v[82:97], v[130:133], v[150:153], v[82:97]
	ds_read_b128 v[232:235], v159 offset:59408
	global_load_lds_dwordx4 v160, s[62:63]
	s_waitcnt lgkmcnt(7)
	v_mfma_f32_32x32x16_bf16 v[98:113], v[134:137], v[146:149], v[98:113]
	s_add_u32 m0, s65, 0x9000
	s_waitcnt lgkmcnt(6)
	v_mfma_f32_32x32x16_bf16 v[114:129], v[134:137], v[150:153], v[114:129]
	global_load_lds_dwordx4 v161, s[62:63]
	s_waitcnt lgkmcnt(4)
	v_mfma_f32_32x32x16_bf16 v[2:17], v[212:215], v[220:223], v[2:17]
	s_add_u32 m0, s65, 0xa000
	s_waitcnt lgkmcnt(3)
	v_mfma_f32_32x32x16_bf16 v[18:33], v[212:215], v[224:227], v[18:33]
	global_load_lds_dwordx4 v160, s[18:19]
	s_waitcnt lgkmcnt(2)
	v_mfma_f32_32x32x16_bf16 v[34:49], v[216:219], v[220:223], v[34:49]
	s_add_u32 m0, s65, 0xb000
	s_waitcnt lgkmcnt(2)
	v_mfma_f32_32x32x16_bf16 v[50:65], v[216:219], v[224:227], v[50:65]
	global_load_lds_dwordx4 v161, s[18:19]
	s_waitcnt lgkmcnt(1)
	v_mfma_f32_32x32x16_bf16 v[66:81], v[212:215], v[228:231], v[66:81]
	s_add_u32 s66, s66, 64
	s_addc_u32 s67, s67, 0
	s_waitcnt lgkmcnt(0)
	v_mfma_f32_32x32x16_bf16 v[82:97], v[212:215], v[232:235], v[82:97]
	s_add_u32 s62, s62, 64
	s_addc_u32 s63, s63, 0
	s_waitcnt lgkmcnt(1)
	v_mfma_f32_32x32x16_bf16 v[98:113], v[216:219], v[228:231], v[98:113]
	s_add_u32 s18, s18, 64
	s_addc_u32 s19, s19, 0
	s_waitcnt lgkmcnt(0)
	v_mfma_f32_32x32x16_bf16 v[114:129], v[216:219], v[232:235], v[114:129]
	s_sub_u32 s59, s59, 1
	s_cmp_lg_u32 s59, 0
	s_cbranch_scc1 .Lhw_outproj_loop
	s_waitcnt vmcnt(6)
	s_barrier
	ds_read_b128 v[130:133], v154 offset:16
	ds_read_b128 v[138:141], v156 offset:8208
	ds_read_b128 v[142:145], v156 offset:10256
	ds_read_b128 v[134:137], v154 offset:2064
	ds_read_b128 v[146:149], v158 offset:8208
	ds_read_b128 v[150:153], v158 offset:10256
	s_waitcnt lgkmcnt(4)
	v_mfma_f32_32x32x16_bf16 v[2:17], v[130:133], v[138:141], v[2:17]
	ds_read_b128 v[212:215], v155 offset:16
	s_waitcnt lgkmcnt(4)
	v_mfma_f32_32x32x16_bf16 v[18:33], v[130:133], v[142:145], v[18:33]
	ds_read_b128 v[220:223], v157 offset:8208
	s_waitcnt lgkmcnt(4)
	v_mfma_f32_32x32x16_bf16 v[34:49], v[134:137], v[138:141], v[34:49]
	ds_read_b128 v[224:227], v157 offset:10256
	s_waitcnt lgkmcnt(5)
	v_mfma_f32_32x32x16_bf16 v[50:65], v[134:137], v[142:145], v[50:65]
	ds_read_b128 v[216:219], v155 offset:2064
	s_waitcnt lgkmcnt(5)
	v_mfma_f32_32x32x16_bf16 v[66:81], v[130:133], v[146:149], v[66:81]
	ds_read_b128 v[228:231], v159 offset:8208
	s_waitcnt lgkmcnt(5)
	v_mfma_f32_32x32x16_bf16 v[82:97], v[130:133], v[150:153], v[82:97]
	ds_read_b128 v[232:235], v159 offset:10256
	s_waitcnt lgkmcnt(7)
	v_mfma_f32_32x32x16_bf16 v[98:113], v[134:137], v[146:149], v[98:113]
	s_waitcnt lgkmcnt(6)
	v_mfma_f32_32x32x16_bf16 v[114:129], v[134:137], v[150:153], v[114:129]
	s_waitcnt lgkmcnt(4)
	v_mfma_f32_32x32x16_bf16 v[2:17], v[212:215], v[220:223], v[2:17]
	s_waitcnt lgkmcnt(3)
	v_mfma_f32_32x32x16_bf16 v[18:33], v[212:215], v[224:227], v[18:33]
	s_waitcnt lgkmcnt(2)
	v_mfma_f32_32x32x16_bf16 v[34:49], v[216:219], v[220:223], v[34:49]
	s_waitcnt lgkmcnt(2)
	v_mfma_f32_32x32x16_bf16 v[50:65], v[216:219], v[224:227], v[50:65]
	s_waitcnt lgkmcnt(1)
	v_mfma_f32_32x32x16_bf16 v[66:81], v[212:215], v[228:231], v[66:81]
	s_waitcnt lgkmcnt(0)
	v_mfma_f32_32x32x16_bf16 v[82:97], v[212:215], v[232:235], v[82:97]
	s_waitcnt lgkmcnt(1)
	v_mfma_f32_32x32x16_bf16 v[98:113], v[216:219], v[228:231], v[98:113]
	s_waitcnt lgkmcnt(0)
	v_mfma_f32_32x32x16_bf16 v[114:129], v[216:219], v[232:235], v[114:129]
	s_waitcnt vmcnt(0)
	s_barrier
	ds_read_b128 v[130:133], v154 offset:24592
	ds_read_b128 v[138:141], v156 offset:32784
	ds_read_b128 v[142:145], v156 offset:34832
	ds_read_b128 v[134:137], v154 offset:26640
	ds_read_b128 v[146:149], v158 offset:32784
	ds_read_b128 v[150:153], v158 offset:34832
	s_waitcnt lgkmcnt(4)
	v_mfma_f32_32x32x16_bf16 v[2:17], v[130:133], v[138:141], v[2:17]
	ds_read_b128 v[212:215], v155 offset:24592
	s_waitcnt lgkmcnt(4)
	v_mfma_f32_32x32x16_bf16 v[18:33], v[130:133], v[142:145], v[18:33]
	ds_read_b128 v[220:223], v157 offset:32784
	s_waitcnt lgkmcnt(4)
	v_mfma_f32_32x32x16_bf16 v[34:49], v[134:137], v[138:141], v[34:49]
	ds_read_b128 v[224:227], v157 offset:34832
	s_waitcnt lgkmcnt(5)
	v_mfma_f32_32x32x16_bf16 v[50:65], v[134:137], v[142:145], v[50:65]
	ds_read_b128 v[216:219], v155 offset:26640
	s_waitcnt lgkmcnt(5)
	v_mfma_f32_32x32x16_bf16 v[66:81], v[130:133], v[146:149], v[66:81]
	ds_read_b128 v[228:231], v159 offset:32784
	s_waitcnt lgkmcnt(5)
	v_mfma_f32_32x32x16_bf16 v[82:97], v[130:133], v[150:153], v[82:97]
	ds_read_b128 v[232:235], v159 offset:34832
	s_waitcnt lgkmcnt(7)
	v_mfma_f32_32x32x16_bf16 v[98:113], v[134:137], v[146:149], v[98:113]
	s_waitcnt lgkmcnt(6)
	v_mfma_f32_32x32x16_bf16 v[114:129], v[134:137], v[150:153], v[114:129]
	s_waitcnt lgkmcnt(4)
	v_mfma_f32_32x32x16_bf16 v[2:17], v[212:215], v[220:223], v[2:17]
	s_waitcnt lgkmcnt(3)
	v_mfma_f32_32x32x16_bf16 v[18:33], v[212:215], v[224:227], v[18:33]
	s_waitcnt lgkmcnt(2)
	v_mfma_f32_32x32x16_bf16 v[34:49], v[216:219], v[220:223], v[34:49]
	s_waitcnt lgkmcnt(2)
	v_mfma_f32_32x32x16_bf16 v[50:65], v[216:219], v[224:227], v[50:65]
	s_waitcnt lgkmcnt(1)
	v_mfma_f32_32x32x16_bf16 v[66:81], v[212:215], v[228:231], v[66:81]
	s_waitcnt lgkmcnt(0)
	v_mfma_f32_32x32x16_bf16 v[82:97], v[212:215], v[232:235], v[82:97]
	s_waitcnt lgkmcnt(1)
	v_mfma_f32_32x32x16_bf16 v[98:113], v[216:219], v[228:231], v[98:113]
	s_waitcnt lgkmcnt(0)
	v_mfma_f32_32x32x16_bf16 v[114:129], v[216:219], v[232:235], v[114:129]
	s_nop 7
	s_nop 7
	s_sub_i32 s2, s6, 0x1000
	s_ashr_i32 s2, s2, 11
	s_add_i32 s2, s2, 1
	s_max_i32 s2, s2, 0
	v_readlane_b32 s17, v246, 28
	s_nop 0
	s_add_i32 s2, s2, s17
	s_mul_i32 s2, s2, 0x9000
	s_lshl_b32 s17, s15, 2
	s_add_u32 s2, s2, s17
	s_add_u32 s60, s8, s2
	s_addc_u32 s61, s9, 0
	s_lshr_b32 s2, s15, 7
	s_mul_i32 s2, s2, 0x18000
	s_lshl_b32 s20, s6, 2
	s_add_u32 s2, s2, s20
	s_add_u32 s10, s44, s2
	s_addc_u32 s11, s45, 0
	s_lshl_b32 s2, s6, 12
	s_add_u32 s2, s2, s17
	s_add_u32 s48, s40, s2
	s_addc_u32 s49, s41, 0
	global_load_dword v175, v166, s[60:61]
	global_load_dword v176, v166, s[60:61] offset:128
	global_load_dword v130, v162, s[48:49]
	global_load_dword v212, v162, s[48:49] offset:128
	global_load_dword v131, v163, s[48:49]
	global_load_dword v213, v163, s[48:49] offset:128
	global_load_dword v132, v164, s[48:49]
	global_load_dword v214, v164, s[48:49] offset:128
	global_load_dword v133, v165, s[48:49]
	global_load_dword v215, v165, s[48:49] offset:128
	s_add_u32 s48, s48, 0x8000
	s_addc_u32 s49, s49, 0
	global_load_dword v134, v162, s[48:49]
	global_load_dword v216, v162, s[48:49] offset:128
	global_load_dword v135, v163, s[48:49]
	global_load_dword v217, v163, s[48:49] offset:128
	global_load_dword v136, v164, s[48:49]
	global_load_dword v218, v164, s[48:49] offset:128
	global_load_dword v137, v165, s[48:49]
	global_load_dword v219, v165, s[48:49] offset:128
	s_add_u32 s48, s48, 0x8000
	s_addc_u32 s49, s49, 0
	global_load_dword v138, v162, s[48:49]
	global_load_dword v220, v162, s[48:49] offset:128
	global_load_dword v139, v163, s[48:49]
	global_load_dword v221, v163, s[48:49] offset:128
	global_load_dword v140, v164, s[48:49]
	global_load_dword v222, v164, s[48:49] offset:128
	global_load_dword v141, v165, s[48:49]
	global_load_dword v223, v165, s[48:49] offset:128
	s_add_u32 s48, s48, 0x8000
	s_addc_u32 s49, s49, 0
	global_load_dword v142, v162, s[48:49]
	global_load_dword v224, v162, s[48:49] offset:128
	global_load_dword v143, v163, s[48:49]
	global_load_dword v225, v163, s[48:49] offset:128
	global_load_dword v144, v164, s[48:49]
	global_load_dword v226, v164, s[48:49] offset:128
	global_load_dword v145, v165, s[48:49]
	global_load_dword v227, v165, s[48:49] offset:128
	s_sub_u32 s48, s48, 0x18000
	s_subb_u32 s49, s49, 0
	s_waitcnt vmcnt(32)
	s_waitcnt vmcnt(30)
	v_fmac_f32_e32 v130, v2, v175
	v_fmac_f32_e32 v212, v18, v176
	global_store_dword v162, v130, s[48:49]
	global_store_dword v162, v212, s[48:49] offset:128
	s_waitcnt vmcnt(30)
	v_fmac_f32_e32 v131, v3, v175
	v_fmac_f32_e32 v213, v19, v176
	global_store_dword v163, v131, s[48:49]
	global_store_dword v163, v213, s[48:49] offset:128
	s_waitcnt vmcnt(30)
	v_fmac_f32_e32 v132, v4, v175
	v_fmac_f32_e32 v214, v20, v176
	global_store_dword v164, v132, s[48:49]
	global_store_dword v164, v214, s[48:49] offset:128
	s_waitcnt vmcnt(30)
	v_fmac_f32_e32 v133, v5, v175
	v_fmac_f32_e32 v215, v21, v176
	global_store_dword v165, v133, s[48:49]
	global_store_dword v165, v215, s[48:49] offset:128
	s_add_u32 s48, s48, 0x8000
	s_addc_u32 s49, s49, 0
	s_waitcnt vmcnt(30)
	v_fmac_f32_e32 v134, v6, v175
	v_fmac_f32_e32 v216, v22, v176
	global_store_dword v162, v134, s[48:49]
	global_store_dword v162, v216, s[48:49] offset:128
	s_waitcnt vmcnt(30)
	v_fmac_f32_e32 v135, v7, v175
	v_fmac_f32_e32 v217, v23, v176
	global_store_dword v163, v135, s[48:49]
	global_store_dword v163, v217, s[48:49] offset:128
	s_waitcnt vmcnt(30)
	v_fmac_f32_e32 v136, v8, v175
	v_fmac_f32_e32 v218, v24, v176
	global_store_dword v164, v136, s[48:49]
	global_store_dword v164, v218, s[48:49] offset:128
	s_waitcnt vmcnt(30)
	v_fmac_f32_e32 v137, v9, v175
	v_fmac_f32_e32 v219, v25, v176
	global_store_dword v165, v137, s[48:49]
	global_store_dword v165, v219, s[48:49] offset:128
	s_add_u32 s48, s48, 0x8000
	s_addc_u32 s49, s49, 0
	s_waitcnt vmcnt(30)
	v_fmac_f32_e32 v138, v10, v175
	v_fmac_f32_e32 v220, v26, v176
	global_store_dword v162, v138, s[48:49]
	global_store_dword v162, v220, s[48:49] offset:128
	s_waitcnt vmcnt(30)
	v_fmac_f32_e32 v139, v11, v175
	v_fmac_f32_e32 v221, v27, v176
	global_store_dword v163, v139, s[48:49]
	global_store_dword v163, v221, s[48:49] offset:128
	s_waitcnt vmcnt(30)
	v_fmac_f32_e32 v140, v12, v175
	v_fmac_f32_e32 v222, v28, v176
	global_store_dword v164, v140, s[48:49]
	global_store_dword v164, v222, s[48:49] offset:128
	s_waitcnt vmcnt(30)
	v_fmac_f32_e32 v141, v13, v175
	v_fmac_f32_e32 v223, v29, v176
	global_store_dword v165, v141, s[48:49]
	global_store_dword v165, v223, s[48:49] offset:128
	s_add_u32 s48, s48, 0x8000
	s_addc_u32 s49, s49, 0
	s_waitcnt vmcnt(30)
	v_fmac_f32_e32 v142, v14, v175
	v_fmac_f32_e32 v224, v30, v176
	global_store_dword v162, v142, s[48:49]
	global_store_dword v162, v224, s[48:49] offset:128
	s_waitcnt vmcnt(30)
	v_fmac_f32_e32 v143, v15, v175
	v_fmac_f32_e32 v225, v31, v176
	global_store_dword v163, v143, s[48:49]
	global_store_dword v163, v225, s[48:49] offset:128
	s_waitcnt vmcnt(30)
	v_fmac_f32_e32 v144, v16, v175
	v_fmac_f32_e32 v226, v32, v176
	global_store_dword v164, v144, s[48:49]
	global_store_dword v164, v226, s[48:49] offset:128
	s_waitcnt vmcnt(30)
	v_fmac_f32_e32 v145, v17, v175
	v_fmac_f32_e32 v227, v33, v176
	global_store_dword v165, v145, s[48:49]
	global_store_dword v165, v227, s[48:49] offset:128
	s_sub_u32 s48, s48, 0x18000
	s_subb_u32 s49, s49, 0
	v_mul_f32_e32 v130, v130, v130
	v_fmac_f32_e32 v130, v212, v212
	v_mul_f32_e32 v131, v131, v131
	v_fmac_f32_e32 v131, v213, v213
	v_mul_f32_e32 v132, v132, v132
	v_fmac_f32_e32 v132, v214, v214
	v_mul_f32_e32 v133, v133, v133
	v_fmac_f32_e32 v133, v215, v215
	v_mul_f32_e32 v134, v134, v134
	v_fmac_f32_e32 v134, v216, v216
	v_mul_f32_e32 v135, v135, v135
	v_fmac_f32_e32 v135, v217, v217
	v_mul_f32_e32 v136, v136, v136
	v_fmac_f32_e32 v136, v218, v218
	v_mul_f32_e32 v137, v137, v137
	v_fmac_f32_e32 v137, v219, v219
	v_mul_f32_e32 v138, v138, v138
	v_fmac_f32_e32 v138, v220, v220
	v_mul_f32_e32 v139, v139, v139
	v_fmac_f32_e32 v139, v221, v221
	v_mul_f32_e32 v140, v140, v140
	v_fmac_f32_e32 v140, v222, v222
	v_mul_f32_e32 v141, v141, v141
	v_fmac_f32_e32 v141, v223, v223
	v_mul_f32_e32 v142, v142, v142
	v_fmac_f32_e32 v142, v224, v224
	v_mul_f32_e32 v143, v143, v143
	v_fmac_f32_e32 v143, v225, v225
	v_mul_f32_e32 v144, v144, v144
	v_fmac_f32_e32 v144, v226, v226
	v_mul_f32_e32 v145, v145, v145
	v_fmac_f32_e32 v145, v227, v227
	s_waitcnt lgkmcnt(0)
	ds_bpermute_b32 v212, v168, v130
	ds_bpermute_b32 v213, v168, v131
	ds_bpermute_b32 v214, v168, v132
	ds_bpermute_b32 v215, v168, v133
	ds_bpermute_b32 v216, v168, v134
	ds_bpermute_b32 v217, v168, v135
	ds_bpermute_b32 v218, v168, v136
	ds_bpermute_b32 v219, v168, v137
	s_waitcnt lgkmcnt(7)
	v_add_f32_e32 v130, v130, v212
	s_waitcnt lgkmcnt(6)
	v_add_f32_e32 v131, v131, v213
	s_waitcnt lgkmcnt(5)
	v_add_f32_e32 v132, v132, v214
	s_waitcnt lgkmcnt(4)
	v_add_f32_e32 v133, v133, v215
	s_waitcnt lgkmcnt(3)
	v_add_f32_e32 v134, v134, v216
	s_waitcnt lgkmcnt(2)
	v_add_f32_e32 v135, v135, v217
	s_waitcnt lgkmcnt(1)
	v_add_f32_e32 v136, v136, v218
	s_waitcnt lgkmcnt(0)
	v_add_f32_e32 v137, v137, v219
	ds_bpermute_b32 v212, v169, v130
	ds_bpermute_b32 v213, v169, v131
	ds_bpermute_b32 v214, v169, v132
	ds_bpermute_b32 v215, v169, v133
	ds_bpermute_b32 v216, v169, v134
	ds_bpermute_b32 v217, v169, v135
	ds_bpermute_b32 v218, v169, v136
	ds_bpermute_b32 v219, v169, v137
	s_waitcnt lgkmcnt(7)
	v_add_f32_e32 v130, v130, v212
	s_waitcnt lgkmcnt(6)
	v_add_f32_e32 v131, v131, v213
	s_waitcnt lgkmcnt(5)
	v_add_f32_e32 v132, v132, v214
	s_waitcnt lgkmcnt(4)
	v_add_f32_e32 v133, v133, v215
	s_waitcnt lgkmcnt(3)
	v_add_f32_e32 v134, v134, v216
	s_waitcnt lgkmcnt(2)
	v_add_f32_e32 v135, v135, v217
	s_waitcnt lgkmcnt(1)
	v_add_f32_e32 v136, v136, v218
	s_waitcnt lgkmcnt(0)
	v_add_f32_e32 v137, v137, v219
	ds_bpermute_b32 v212, v171, v130
	ds_bpermute_b32 v213, v171, v131
	ds_bpermute_b32 v214, v171, v132
	ds_bpermute_b32 v215, v171, v133
	ds_bpermute_b32 v216, v171, v134
	ds_bpermute_b32 v217, v171, v135
	ds_bpermute_b32 v218, v171, v136
	ds_bpermute_b32 v219, v171, v137
	s_waitcnt lgkmcnt(7)
	v_add_f32_e32 v130, v130, v212
	s_waitcnt lgkmcnt(6)
	v_add_f32_e32 v131, v131, v213
	s_waitcnt lgkmcnt(5)
	v_add_f32_e32 v132, v132, v214
	s_waitcnt lgkmcnt(4)
	v_add_f32_e32 v133, v133, v215
	s_waitcnt lgkmcnt(3)
	v_add_f32_e32 v134, v134, v216
	s_waitcnt lgkmcnt(2)
	v_add_f32_e32 v135, v135, v217
	s_waitcnt lgkmcnt(1)
	v_add_f32_e32 v136, v136, v218
	s_waitcnt lgkmcnt(0)
	v_add_f32_e32 v137, v137, v219
	ds_bpermute_b32 v212, v172, v130
	ds_bpermute_b32 v213, v172, v131
	ds_bpermute_b32 v214, v172, v132
	ds_bpermute_b32 v215, v172, v133
	ds_bpermute_b32 v216, v172, v134
	ds_bpermute_b32 v217, v172, v135
	ds_bpermute_b32 v218, v172, v136
	ds_bpermute_b32 v219, v172, v137
	s_waitcnt lgkmcnt(7)
	v_add_f32_e32 v130, v130, v212
	s_waitcnt lgkmcnt(6)
	v_add_f32_e32 v131, v131, v213
	s_waitcnt lgkmcnt(5)
	v_add_f32_e32 v132, v132, v214
	s_waitcnt lgkmcnt(4)
	v_add_f32_e32 v133, v133, v215
	s_waitcnt lgkmcnt(3)
	v_add_f32_e32 v134, v134, v216
	s_waitcnt lgkmcnt(2)
	v_add_f32_e32 v135, v135, v217
	s_waitcnt lgkmcnt(1)
	v_add_f32_e32 v136, v136, v218
	s_waitcnt lgkmcnt(0)
	v_add_f32_e32 v137, v137, v219
	ds_bpermute_b32 v212, v173, v130
	ds_bpermute_b32 v213, v173, v131
	ds_bpermute_b32 v214, v173, v132
	ds_bpermute_b32 v215, v173, v133
	ds_bpermute_b32 v216, v173, v134
	ds_bpermute_b32 v217, v173, v135
	ds_bpermute_b32 v218, v173, v136
	ds_bpermute_b32 v219, v173, v137
	s_waitcnt lgkmcnt(7)
	v_add_f32_e32 v130, v130, v212
	s_waitcnt lgkmcnt(6)
	v_add_f32_e32 v131, v131, v213
	s_waitcnt lgkmcnt(5)
	v_add_f32_e32 v132, v132, v214
	s_waitcnt lgkmcnt(4)
	v_add_f32_e32 v133, v133, v215
	s_waitcnt lgkmcnt(3)
	v_add_f32_e32 v134, v134, v216
	s_waitcnt lgkmcnt(2)
	v_add_f32_e32 v135, v135, v217
	s_waitcnt lgkmcnt(1)
	v_add_f32_e32 v136, v136, v218
	s_waitcnt lgkmcnt(0)
	v_add_f32_e32 v137, v137, v219
	ds_bpermute_b32 v220, v168, v138
	ds_bpermute_b32 v221, v168, v139
	ds_bpermute_b32 v222, v168, v140
	ds_bpermute_b32 v223, v168, v141
	ds_bpermute_b32 v224, v168, v142
	ds_bpermute_b32 v225, v168, v143
	ds_bpermute_b32 v226, v168, v144
	ds_bpermute_b32 v227, v168, v145
	s_waitcnt lgkmcnt(7)
	v_add_f32_e32 v138, v138, v220
	s_waitcnt lgkmcnt(6)
	v_add_f32_e32 v139, v139, v221
	s_waitcnt lgkmcnt(5)
	v_add_f32_e32 v140, v140, v222
	s_waitcnt lgkmcnt(4)
	v_add_f32_e32 v141, v141, v223
	s_waitcnt lgkmcnt(3)
	v_add_f32_e32 v142, v142, v224
	s_waitcnt lgkmcnt(2)
	v_add_f32_e32 v143, v143, v225
	s_waitcnt lgkmcnt(1)
	v_add_f32_e32 v144, v144, v226
	s_waitcnt lgkmcnt(0)
	v_add_f32_e32 v145, v145, v227
	ds_bpermute_b32 v220, v169, v138
	ds_bpermute_b32 v221, v169, v139
	ds_bpermute_b32 v222, v169, v140
	ds_bpermute_b32 v223, v169, v141
	ds_bpermute_b32 v224, v169, v142
	ds_bpermute_b32 v225, v169, v143
	ds_bpermute_b32 v226, v169, v144
	ds_bpermute_b32 v227, v169, v145
	s_waitcnt lgkmcnt(7)
	v_add_f32_e32 v138, v138, v220
	s_waitcnt lgkmcnt(6)
	v_add_f32_e32 v139, v139, v221
	s_waitcnt lgkmcnt(5)
	v_add_f32_e32 v140, v140, v222
	s_waitcnt lgkmcnt(4)
	v_add_f32_e32 v141, v141, v223
	s_waitcnt lgkmcnt(3)
	v_add_f32_e32 v142, v142, v224
	s_waitcnt lgkmcnt(2)
	v_add_f32_e32 v143, v143, v225
	s_waitcnt lgkmcnt(1)
	v_add_f32_e32 v144, v144, v226
	s_waitcnt lgkmcnt(0)
	v_add_f32_e32 v145, v145, v227
	ds_bpermute_b32 v220, v171, v138
	ds_bpermute_b32 v221, v171, v139
	ds_bpermute_b32 v222, v171, v140
	ds_bpermute_b32 v223, v171, v141
	ds_bpermute_b32 v224, v171, v142
	ds_bpermute_b32 v225, v171, v143
	ds_bpermute_b32 v226, v171, v144
	ds_bpermute_b32 v227, v171, v145
	s_waitcnt lgkmcnt(7)
	v_add_f32_e32 v138, v138, v220
	s_waitcnt lgkmcnt(6)
	v_add_f32_e32 v139, v139, v221
	s_waitcnt lgkmcnt(5)
	v_add_f32_e32 v140, v140, v222
	s_waitcnt lgkmcnt(4)
	v_add_f32_e32 v141, v141, v223
	s_waitcnt lgkmcnt(3)
	v_add_f32_e32 v142, v142, v224
	s_waitcnt lgkmcnt(2)
	v_add_f32_e32 v143, v143, v225
	s_waitcnt lgkmcnt(1)
	v_add_f32_e32 v144, v144, v226
	s_waitcnt lgkmcnt(0)
	v_add_f32_e32 v145, v145, v227
	ds_bpermute_b32 v220, v172, v138
	ds_bpermute_b32 v221, v172, v139
	ds_bpermute_b32 v222, v172, v140
	ds_bpermute_b32 v223, v172, v141
	ds_bpermute_b32 v224, v172, v142
	ds_bpermute_b32 v225, v172, v143
	ds_bpermute_b32 v226, v172, v144
	ds_bpermute_b32 v227, v172, v145
	s_waitcnt lgkmcnt(7)
	v_add_f32_e32 v138, v138, v220
	s_waitcnt lgkmcnt(6)
	v_add_f32_e32 v139, v139, v221
	s_waitcnt lgkmcnt(5)
	v_add_f32_e32 v140, v140, v222
	s_waitcnt lgkmcnt(4)
	v_add_f32_e32 v141, v141, v223
	s_waitcnt lgkmcnt(3)
	v_add_f32_e32 v142, v142, v224
	s_waitcnt lgkmcnt(2)
	v_add_f32_e32 v143, v143, v225
	s_waitcnt lgkmcnt(1)
	v_add_f32_e32 v144, v144, v226
	s_waitcnt lgkmcnt(0)
	v_add_f32_e32 v145, v145, v227
	ds_bpermute_b32 v220, v173, v138
	ds_bpermute_b32 v221, v173, v139
	ds_bpermute_b32 v222, v173, v140
	ds_bpermute_b32 v223, v173, v141
	ds_bpermute_b32 v224, v173, v142
	ds_bpermute_b32 v225, v173, v143
	ds_bpermute_b32 v226, v173, v144
	ds_bpermute_b32 v227, v173, v145
	s_waitcnt lgkmcnt(7)
	v_add_f32_e32 v138, v138, v220
	s_waitcnt lgkmcnt(6)
	v_add_f32_e32 v139, v139, v221
	s_waitcnt lgkmcnt(5)
	v_add_f32_e32 v140, v140, v222
	s_waitcnt lgkmcnt(4)
	v_add_f32_e32 v141, v141, v223
	s_waitcnt lgkmcnt(3)
	v_add_f32_e32 v142, v142, v224
	s_waitcnt lgkmcnt(2)
	v_add_f32_e32 v143, v143, v225
	s_waitcnt lgkmcnt(1)
	v_add_f32_e32 v144, v144, v226
	s_waitcnt lgkmcnt(0)
	v_add_f32_e32 v145, v145, v227
	v_cmp_eq_u32_e32 vcc, 0, v174
	s_and_saveexec_b64 s[58:59], vcc
	global_store_dword v167, v130, s[10:11]
	global_store_dword v167, v131, s[10:11] offset:4
	global_store_dword v167, v132, s[10:11] offset:8
	global_store_dword v167, v133, s[10:11] offset:12
	global_store_dword v167, v134, s[10:11] offset:32
	global_store_dword v167, v135, s[10:11] offset:36
	global_store_dword v167, v136, s[10:11] offset:40
	global_store_dword v167, v137, s[10:11] offset:44
	global_store_dword v167, v138, s[10:11] offset:64
	global_store_dword v167, v139, s[10:11] offset:68
	global_store_dword v167, v140, s[10:11] offset:72
	global_store_dword v167, v141, s[10:11] offset:76
	global_store_dword v167, v142, s[10:11] offset:96
	global_store_dword v167, v143, s[10:11] offset:100
	global_store_dword v167, v144, s[10:11] offset:104
	global_store_dword v167, v145, s[10:11] offset:108
	s_mov_b64 exec, -1
	s_add_u32 s48, s48, 0x20000
	s_addc_u32 s49, s49, 0
	global_load_dword v130, v162, s[48:49]
	global_load_dword v212, v162, s[48:49] offset:128
	global_load_dword v131, v163, s[48:49]
	global_load_dword v213, v163, s[48:49] offset:128
	global_load_dword v132, v164, s[48:49]
	global_load_dword v214, v164, s[48:49] offset:128
	global_load_dword v133, v165, s[48:49]
	global_load_dword v215, v165, s[48:49] offset:128
	s_add_u32 s48, s48, 0x8000
	s_addc_u32 s49, s49, 0
	global_load_dword v134, v162, s[48:49]
	global_load_dword v216, v162, s[48:49] offset:128
	global_load_dword v135, v163, s[48:49]
	global_load_dword v217, v163, s[48:49] offset:128
	global_load_dword v136, v164, s[48:49]
	global_load_dword v218, v164, s[48:49] offset:128
	global_load_dword v137, v165, s[48:49]
	global_load_dword v219, v165, s[48:49] offset:128
	s_add_u32 s48, s48, 0x8000
	s_addc_u32 s49, s49, 0
	global_load_dword v138, v162, s[48:49]
	global_load_dword v220, v162, s[48:49] offset:128
	global_load_dword v139, v163, s[48:49]
	global_load_dword v221, v163, s[48:49] offset:128
	global_load_dword v140, v164, s[48:49]
	global_load_dword v222, v164, s[48:49] offset:128
	global_load_dword v141, v165, s[48:49]
	global_load_dword v223, v165, s[48:49] offset:128
	s_add_u32 s48, s48, 0x8000
	s_addc_u32 s49, s49, 0
	global_load_dword v142, v162, s[48:49]
	global_load_dword v224, v162, s[48:49] offset:128
	global_load_dword v143, v163, s[48:49]
	global_load_dword v225, v163, s[48:49] offset:128
	global_load_dword v144, v164, s[48:49]
	global_load_dword v226, v164, s[48:49] offset:128
	global_load_dword v145, v165, s[48:49]
	global_load_dword v227, v165, s[48:49] offset:128
	s_sub_u32 s48, s48, 0x18000
	s_subb_u32 s49, s49, 0
	s_waitcnt vmcnt(30)
	v_fmac_f32_e32 v130, v34, v175
	v_fmac_f32_e32 v212, v50, v176
	global_store_dword v162, v130, s[48:49]
	global_store_dword v162, v212, s[48:49] offset:128
	s_waitcnt vmcnt(30)
	v_fmac_f32_e32 v131, v35, v175
	v_fmac_f32_e32 v213, v51, v176
	global_store_dword v163, v131, s[48:49]
	global_store_dword v163, v213, s[48:49] offset:128
	s_waitcnt vmcnt(30)
	v_fmac_f32_e32 v132, v36, v175
	v_fmac_f32_e32 v214, v52, v176
	global_store_dword v164, v132, s[48:49]
	global_store_dword v164, v214, s[48:49] offset:128
	s_waitcnt vmcnt(30)
	v_fmac_f32_e32 v133, v37, v175
	v_fmac_f32_e32 v215, v53, v176
	global_store_dword v165, v133, s[48:49]
	global_store_dword v165, v215, s[48:49] offset:128
	s_add_u32 s48, s48, 0x8000
	s_addc_u32 s49, s49, 0
	s_waitcnt vmcnt(30)
	v_fmac_f32_e32 v134, v38, v175
	v_fmac_f32_e32 v216, v54, v176
	global_store_dword v162, v134, s[48:49]
	global_store_dword v162, v216, s[48:49] offset:128
	s_waitcnt vmcnt(30)
	v_fmac_f32_e32 v135, v39, v175
	v_fmac_f32_e32 v217, v55, v176
	global_store_dword v163, v135, s[48:49]
	global_store_dword v163, v217, s[48:49] offset:128
	s_waitcnt vmcnt(30)
	v_fmac_f32_e32 v136, v40, v175
	v_fmac_f32_e32 v218, v56, v176
	global_store_dword v164, v136, s[48:49]
	global_store_dword v164, v218, s[48:49] offset:128
	s_waitcnt vmcnt(30)
	v_fmac_f32_e32 v137, v41, v175
	v_fmac_f32_e32 v219, v57, v176
	global_store_dword v165, v137, s[48:49]
	global_store_dword v165, v219, s[48:49] offset:128
	s_add_u32 s48, s48, 0x8000
	s_addc_u32 s49, s49, 0
	s_waitcnt vmcnt(30)
	v_fmac_f32_e32 v138, v42, v175
	v_fmac_f32_e32 v220, v58, v176
	global_store_dword v162, v138, s[48:49]
	global_store_dword v162, v220, s[48:49] offset:128
	s_waitcnt vmcnt(30)
	v_fmac_f32_e32 v139, v43, v175
	v_fmac_f32_e32 v221, v59, v176
	global_store_dword v163, v139, s[48:49]
	global_store_dword v163, v221, s[48:49] offset:128
	s_waitcnt vmcnt(30)
	v_fmac_f32_e32 v140, v44, v175
	v_fmac_f32_e32 v222, v60, v176
	global_store_dword v164, v140, s[48:49]
	global_store_dword v164, v222, s[48:49] offset:128
	s_waitcnt vmcnt(30)
	v_fmac_f32_e32 v141, v45, v175
	v_fmac_f32_e32 v223, v61, v176
	global_store_dword v165, v141, s[48:49]
	global_store_dword v165, v223, s[48:49] offset:128
	s_add_u32 s48, s48, 0x8000
	s_addc_u32 s49, s49, 0
	s_waitcnt vmcnt(30)
	v_fmac_f32_e32 v142, v46, v175
	v_fmac_f32_e32 v224, v62, v176
	global_store_dword v162, v142, s[48:49]
	global_store_dword v162, v224, s[48:49] offset:128
	s_waitcnt vmcnt(30)
	v_fmac_f32_e32 v143, v47, v175
	v_fmac_f32_e32 v225, v63, v176
	global_store_dword v163, v143, s[48:49]
	global_store_dword v163, v225, s[48:49] offset:128
	s_waitcnt vmcnt(30)
	v_fmac_f32_e32 v144, v48, v175
	v_fmac_f32_e32 v226, v64, v176
	global_store_dword v164, v144, s[48:49]
	global_store_dword v164, v226, s[48:49] offset:128
	s_waitcnt vmcnt(30)
	v_fmac_f32_e32 v145, v49, v175
	v_fmac_f32_e32 v227, v65, v176
	global_store_dword v165, v145, s[48:49]
	global_store_dword v165, v227, s[48:49] offset:128
	s_sub_u32 s48, s48, 0x18000
	s_subb_u32 s49, s49, 0
	v_mul_f32_e32 v130, v130, v130
	v_fmac_f32_e32 v130, v212, v212
	v_mul_f32_e32 v131, v131, v131
	v_fmac_f32_e32 v131, v213, v213
	v_mul_f32_e32 v132, v132, v132
	v_fmac_f32_e32 v132, v214, v214
	v_mul_f32_e32 v133, v133, v133
	v_fmac_f32_e32 v133, v215, v215
	v_mul_f32_e32 v134, v134, v134
	v_fmac_f32_e32 v134, v216, v216
	v_mul_f32_e32 v135, v135, v135
	v_fmac_f32_e32 v135, v217, v217
	v_mul_f32_e32 v136, v136, v136
	v_fmac_f32_e32 v136, v218, v218
	v_mul_f32_e32 v137, v137, v137
	v_fmac_f32_e32 v137, v219, v219
	v_mul_f32_e32 v138, v138, v138
	v_fmac_f32_e32 v138, v220, v220
	v_mul_f32_e32 v139, v139, v139
	v_fmac_f32_e32 v139, v221, v221
	v_mul_f32_e32 v140, v140, v140
	v_fmac_f32_e32 v140, v222, v222
	v_mul_f32_e32 v141, v141, v141
	v_fmac_f32_e32 v141, v223, v223
	v_mul_f32_e32 v142, v142, v142
	v_fmac_f32_e32 v142, v224, v224
	v_mul_f32_e32 v143, v143, v143
	v_fmac_f32_e32 v143, v225, v225
	v_mul_f32_e32 v144, v144, v144
	v_fmac_f32_e32 v144, v226, v226
	v_mul_f32_e32 v145, v145, v145
	v_fmac_f32_e32 v145, v227, v227
	s_waitcnt lgkmcnt(0)
	ds_bpermute_b32 v212, v168, v130
	ds_bpermute_b32 v213, v168, v131
	ds_bpermute_b32 v214, v168, v132
	ds_bpermute_b32 v215, v168, v133
	ds_bpermute_b32 v216, v168, v134
	ds_bpermute_b32 v217, v168, v135
	ds_bpermute_b32 v218, v168, v136
	ds_bpermute_b32 v219, v168, v137
	s_waitcnt lgkmcnt(7)
	v_add_f32_e32 v130, v130, v212
	s_waitcnt lgkmcnt(6)
	v_add_f32_e32 v131, v131, v213
	s_waitcnt lgkmcnt(5)
	v_add_f32_e32 v132, v132, v214
	s_waitcnt lgkmcnt(4)
	v_add_f32_e32 v133, v133, v215
	s_waitcnt lgkmcnt(3)
	v_add_f32_e32 v134, v134, v216
	s_waitcnt lgkmcnt(2)
	v_add_f32_e32 v135, v135, v217
	s_waitcnt lgkmcnt(1)
	v_add_f32_e32 v136, v136, v218
	s_waitcnt lgkmcnt(0)
	v_add_f32_e32 v137, v137, v219
	ds_bpermute_b32 v212, v169, v130
	ds_bpermute_b32 v213, v169, v131
	ds_bpermute_b32 v214, v169, v132
	ds_bpermute_b32 v215, v169, v133
	ds_bpermute_b32 v216, v169, v134
	ds_bpermute_b32 v217, v169, v135
	ds_bpermute_b32 v218, v169, v136
	ds_bpermute_b32 v219, v169, v137
	s_waitcnt lgkmcnt(7)
	v_add_f32_e32 v130, v130, v212
	s_waitcnt lgkmcnt(6)
	v_add_f32_e32 v131, v131, v213
	s_waitcnt lgkmcnt(5)
	v_add_f32_e32 v132, v132, v214
	s_waitcnt lgkmcnt(4)
	v_add_f32_e32 v133, v133, v215
	s_waitcnt lgkmcnt(3)
	v_add_f32_e32 v134, v134, v216
	s_waitcnt lgkmcnt(2)
	v_add_f32_e32 v135, v135, v217
	s_waitcnt lgkmcnt(1)
	v_add_f32_e32 v136, v136, v218
	s_waitcnt lgkmcnt(0)
	v_add_f32_e32 v137, v137, v219
	ds_bpermute_b32 v212, v171, v130
	ds_bpermute_b32 v213, v171, v131
	ds_bpermute_b32 v214, v171, v132
	ds_bpermute_b32 v215, v171, v133
	ds_bpermute_b32 v216, v171, v134
	ds_bpermute_b32 v217, v171, v135
	ds_bpermute_b32 v218, v171, v136
	ds_bpermute_b32 v219, v171, v137
	s_waitcnt lgkmcnt(7)
	v_add_f32_e32 v130, v130, v212
	s_waitcnt lgkmcnt(6)
	v_add_f32_e32 v131, v131, v213
	s_waitcnt lgkmcnt(5)
	v_add_f32_e32 v132, v132, v214
	s_waitcnt lgkmcnt(4)
	v_add_f32_e32 v133, v133, v215
	s_waitcnt lgkmcnt(3)
	v_add_f32_e32 v134, v134, v216
	s_waitcnt lgkmcnt(2)
	v_add_f32_e32 v135, v135, v217
	s_waitcnt lgkmcnt(1)
	v_add_f32_e32 v136, v136, v218
	s_waitcnt lgkmcnt(0)
	v_add_f32_e32 v137, v137, v219
	ds_bpermute_b32 v212, v172, v130
	ds_bpermute_b32 v213, v172, v131
	ds_bpermute_b32 v214, v172, v132
	ds_bpermute_b32 v215, v172, v133
	ds_bpermute_b32 v216, v172, v134
	ds_bpermute_b32 v217, v172, v135
	ds_bpermute_b32 v218, v172, v136
	ds_bpermute_b32 v219, v172, v137
	s_waitcnt lgkmcnt(7)
	v_add_f32_e32 v130, v130, v212
	s_waitcnt lgkmcnt(6)
	v_add_f32_e32 v131, v131, v213
	s_waitcnt lgkmcnt(5)
	v_add_f32_e32 v132, v132, v214
	s_waitcnt lgkmcnt(4)
	v_add_f32_e32 v133, v133, v215
	s_waitcnt lgkmcnt(3)
	v_add_f32_e32 v134, v134, v216
	s_waitcnt lgkmcnt(2)
	v_add_f32_e32 v135, v135, v217
	s_waitcnt lgkmcnt(1)
	v_add_f32_e32 v136, v136, v218
	s_waitcnt lgkmcnt(0)
	v_add_f32_e32 v137, v137, v219
	ds_bpermute_b32 v212, v173, v130
	ds_bpermute_b32 v213, v173, v131
	ds_bpermute_b32 v214, v173, v132
	ds_bpermute_b32 v215, v173, v133
	ds_bpermute_b32 v216, v173, v134
	ds_bpermute_b32 v217, v173, v135
	ds_bpermute_b32 v218, v173, v136
	ds_bpermute_b32 v219, v173, v137
	s_waitcnt lgkmcnt(7)
	v_add_f32_e32 v130, v130, v212
	s_waitcnt lgkmcnt(6)
	v_add_f32_e32 v131, v131, v213
	s_waitcnt lgkmcnt(5)
	v_add_f32_e32 v132, v132, v214
	s_waitcnt lgkmcnt(4)
	v_add_f32_e32 v133, v133, v215
	s_waitcnt lgkmcnt(3)
	v_add_f32_e32 v134, v134, v216
	s_waitcnt lgkmcnt(2)
	v_add_f32_e32 v135, v135, v217
	s_waitcnt lgkmcnt(1)
	v_add_f32_e32 v136, v136, v218
	s_waitcnt lgkmcnt(0)
	v_add_f32_e32 v137, v137, v219
	ds_bpermute_b32 v220, v168, v138
	ds_bpermute_b32 v221, v168, v139
	ds_bpermute_b32 v222, v168, v140
	ds_bpermute_b32 v223, v168, v141
	ds_bpermute_b32 v224, v168, v142
	ds_bpermute_b32 v225, v168, v143
	ds_bpermute_b32 v226, v168, v144
	ds_bpermute_b32 v227, v168, v145
	s_waitcnt lgkmcnt(7)
	v_add_f32_e32 v138, v138, v220
	s_waitcnt lgkmcnt(6)
	v_add_f32_e32 v139, v139, v221
	s_waitcnt lgkmcnt(5)
	v_add_f32_e32 v140, v140, v222
	s_waitcnt lgkmcnt(4)
	v_add_f32_e32 v141, v141, v223
	s_waitcnt lgkmcnt(3)
	v_add_f32_e32 v142, v142, v224
	s_waitcnt lgkmcnt(2)
	v_add_f32_e32 v143, v143, v225
	s_waitcnt lgkmcnt(1)
	v_add_f32_e32 v144, v144, v226
	s_waitcnt lgkmcnt(0)
	v_add_f32_e32 v145, v145, v227
	ds_bpermute_b32 v220, v169, v138
	ds_bpermute_b32 v221, v169, v139
	ds_bpermute_b32 v222, v169, v140
	ds_bpermute_b32 v223, v169, v141
	ds_bpermute_b32 v224, v169, v142
	ds_bpermute_b32 v225, v169, v143
	ds_bpermute_b32 v226, v169, v144
	ds_bpermute_b32 v227, v169, v145
	s_waitcnt lgkmcnt(7)
	v_add_f32_e32 v138, v138, v220
	s_waitcnt lgkmcnt(6)
	v_add_f32_e32 v139, v139, v221
	s_waitcnt lgkmcnt(5)
	v_add_f32_e32 v140, v140, v222
	s_waitcnt lgkmcnt(4)
	v_add_f32_e32 v141, v141, v223
	s_waitcnt lgkmcnt(3)
	v_add_f32_e32 v142, v142, v224
	s_waitcnt lgkmcnt(2)
	v_add_f32_e32 v143, v143, v225
	s_waitcnt lgkmcnt(1)
	v_add_f32_e32 v144, v144, v226
	s_waitcnt lgkmcnt(0)
	v_add_f32_e32 v145, v145, v227
	ds_bpermute_b32 v220, v171, v138
	ds_bpermute_b32 v221, v171, v139
	ds_bpermute_b32 v222, v171, v140
	ds_bpermute_b32 v223, v171, v141
	ds_bpermute_b32 v224, v171, v142
	ds_bpermute_b32 v225, v171, v143
	ds_bpermute_b32 v226, v171, v144
	ds_bpermute_b32 v227, v171, v145
	s_waitcnt lgkmcnt(7)
	v_add_f32_e32 v138, v138, v220
	s_waitcnt lgkmcnt(6)
	v_add_f32_e32 v139, v139, v221
	s_waitcnt lgkmcnt(5)
	v_add_f32_e32 v140, v140, v222
	s_waitcnt lgkmcnt(4)
	v_add_f32_e32 v141, v141, v223
	s_waitcnt lgkmcnt(3)
	v_add_f32_e32 v142, v142, v224
	s_waitcnt lgkmcnt(2)
	v_add_f32_e32 v143, v143, v225
	s_waitcnt lgkmcnt(1)
	v_add_f32_e32 v144, v144, v226
	s_waitcnt lgkmcnt(0)
	v_add_f32_e32 v145, v145, v227
	ds_bpermute_b32 v220, v172, v138
	ds_bpermute_b32 v221, v172, v139
	ds_bpermute_b32 v222, v172, v140
	ds_bpermute_b32 v223, v172, v141
	ds_bpermute_b32 v224, v172, v142
	ds_bpermute_b32 v225, v172, v143
	ds_bpermute_b32 v226, v172, v144
	ds_bpermute_b32 v227, v172, v145
	s_waitcnt lgkmcnt(7)
	v_add_f32_e32 v138, v138, v220
	s_waitcnt lgkmcnt(6)
	v_add_f32_e32 v139, v139, v221
	s_waitcnt lgkmcnt(5)
	v_add_f32_e32 v140, v140, v222
	s_waitcnt lgkmcnt(4)
	v_add_f32_e32 v141, v141, v223
	s_waitcnt lgkmcnt(3)
	v_add_f32_e32 v142, v142, v224
	s_waitcnt lgkmcnt(2)
	v_add_f32_e32 v143, v143, v225
	s_waitcnt lgkmcnt(1)
	v_add_f32_e32 v144, v144, v226
	s_waitcnt lgkmcnt(0)
	v_add_f32_e32 v145, v145, v227
	ds_bpermute_b32 v220, v173, v138
	ds_bpermute_b32 v221, v173, v139
	ds_bpermute_b32 v222, v173, v140
	ds_bpermute_b32 v223, v173, v141
	ds_bpermute_b32 v224, v173, v142
	ds_bpermute_b32 v225, v173, v143
	ds_bpermute_b32 v226, v173, v144
	ds_bpermute_b32 v227, v173, v145
	s_waitcnt lgkmcnt(7)
	v_add_f32_e32 v138, v138, v220
	s_waitcnt lgkmcnt(6)
	v_add_f32_e32 v139, v139, v221
	s_waitcnt lgkmcnt(5)
	v_add_f32_e32 v140, v140, v222
	s_waitcnt lgkmcnt(4)
	v_add_f32_e32 v141, v141, v223
	s_waitcnt lgkmcnt(3)
	v_add_f32_e32 v142, v142, v224
	s_waitcnt lgkmcnt(2)
	v_add_f32_e32 v143, v143, v225
	s_waitcnt lgkmcnt(1)
	v_add_f32_e32 v144, v144, v226
	s_waitcnt lgkmcnt(0)
	v_add_f32_e32 v145, v145, v227
	v_cmp_eq_u32_e32 vcc, 0, v174
	s_and_saveexec_b64 s[58:59], vcc
	global_store_dword v167, v130, s[10:11] offset:128
	global_store_dword v167, v131, s[10:11] offset:132
	global_store_dword v167, v132, s[10:11] offset:136
	global_store_dword v167, v133, s[10:11] offset:140
	global_store_dword v167, v134, s[10:11] offset:160
	global_store_dword v167, v135, s[10:11] offset:164
	global_store_dword v167, v136, s[10:11] offset:168
	global_store_dword v167, v137, s[10:11] offset:172
	global_store_dword v167, v138, s[10:11] offset:192
	global_store_dword v167, v139, s[10:11] offset:196
	global_store_dword v167, v140, s[10:11] offset:200
	global_store_dword v167, v141, s[10:11] offset:204
	global_store_dword v167, v142, s[10:11] offset:224
	global_store_dword v167, v143, s[10:11] offset:228
	global_store_dword v167, v144, s[10:11] offset:232
	global_store_dword v167, v145, s[10:11] offset:236
	s_mov_b64 exec, -1
	s_sub_u32 s48, s48, 0x20000
	s_subb_u32 s49, s49, 0
	s_add_u32 s60, s60, 0x200
	s_addc_u32 s61, s61, 0
	s_add_u32 s10, s10, 0x18000
	s_addc_u32 s11, s11, 0
	s_add_u32 s48, s48, 0x200
	s_addc_u32 s49, s49, 0
	global_load_dword v175, v166, s[60:61]
	global_load_dword v176, v166, s[60:61] offset:128
	global_load_dword v130, v162, s[48:49]
	global_load_dword v212, v162, s[48:49] offset:128
	global_load_dword v131, v163, s[48:49]
	global_load_dword v213, v163, s[48:49] offset:128
	global_load_dword v132, v164, s[48:49]
	global_load_dword v214, v164, s[48:49] offset:128
	global_load_dword v133, v165, s[48:49]
	global_load_dword v215, v165, s[48:49] offset:128
	s_add_u32 s48, s48, 0x8000
	s_addc_u32 s49, s49, 0
	global_load_dword v134, v162, s[48:49]
	global_load_dword v216, v162, s[48:49] offset:128
	global_load_dword v135, v163, s[48:49]
	global_load_dword v217, v163, s[48:49] offset:128
	global_load_dword v136, v164, s[48:49]
	global_load_dword v218, v164, s[48:49] offset:128
	global_load_dword v137, v165, s[48:49]
	global_load_dword v219, v165, s[48:49] offset:128
	s_add_u32 s48, s48, 0x8000
	s_addc_u32 s49, s49, 0
	global_load_dword v138, v162, s[48:49]
	global_load_dword v220, v162, s[48:49] offset:128
	global_load_dword v139, v163, s[48:49]
	global_load_dword v221, v163, s[48:49] offset:128
	global_load_dword v140, v164, s[48:49]
	global_load_dword v222, v164, s[48:49] offset:128
	global_load_dword v141, v165, s[48:49]
	global_load_dword v223, v165, s[48:49] offset:128
	s_add_u32 s48, s48, 0x8000
	s_addc_u32 s49, s49, 0
	global_load_dword v142, v162, s[48:49]
	global_load_dword v224, v162, s[48:49] offset:128
	global_load_dword v143, v163, s[48:49]
	global_load_dword v225, v163, s[48:49] offset:128
	global_load_dword v144, v164, s[48:49]
	global_load_dword v226, v164, s[48:49] offset:128
	global_load_dword v145, v165, s[48:49]
	global_load_dword v227, v165, s[48:49] offset:128
	s_sub_u32 s48, s48, 0x18000
	s_subb_u32 s49, s49, 0
	s_waitcnt vmcnt(32)
	s_waitcnt vmcnt(30)
	v_fmac_f32_e32 v130, v66, v175
	v_fmac_f32_e32 v212, v82, v176
	global_store_dword v162, v130, s[48:49]
	global_store_dword v162, v212, s[48:49] offset:128
	s_waitcnt vmcnt(30)
	v_fmac_f32_e32 v131, v67, v175
	v_fmac_f32_e32 v213, v83, v176
	global_store_dword v163, v131, s[48:49]
	global_store_dword v163, v213, s[48:49] offset:128
	s_waitcnt vmcnt(30)
	v_fmac_f32_e32 v132, v68, v175
	v_fmac_f32_e32 v214, v84, v176
	global_store_dword v164, v132, s[48:49]
	global_store_dword v164, v214, s[48:49] offset:128
	s_waitcnt vmcnt(30)
	v_fmac_f32_e32 v133, v69, v175
	v_fmac_f32_e32 v215, v85, v176
	global_store_dword v165, v133, s[48:49]
	global_store_dword v165, v215, s[48:49] offset:128
	s_add_u32 s48, s48, 0x8000
	s_addc_u32 s49, s49, 0
	s_waitcnt vmcnt(30)
	v_fmac_f32_e32 v134, v70, v175
	v_fmac_f32_e32 v216, v86, v176
	global_store_dword v162, v134, s[48:49]
	global_store_dword v162, v216, s[48:49] offset:128
	s_waitcnt vmcnt(30)
	v_fmac_f32_e32 v135, v71, v175
	v_fmac_f32_e32 v217, v87, v176
	global_store_dword v163, v135, s[48:49]
	global_store_dword v163, v217, s[48:49] offset:128
	s_waitcnt vmcnt(30)
	v_fmac_f32_e32 v136, v72, v175
	v_fmac_f32_e32 v218, v88, v176
	global_store_dword v164, v136, s[48:49]
	global_store_dword v164, v218, s[48:49] offset:128
	s_waitcnt vmcnt(30)
	v_fmac_f32_e32 v137, v73, v175
	v_fmac_f32_e32 v219, v89, v176
	global_store_dword v165, v137, s[48:49]
	global_store_dword v165, v219, s[48:49] offset:128
	s_add_u32 s48, s48, 0x8000
	s_addc_u32 s49, s49, 0
	s_waitcnt vmcnt(30)
	v_fmac_f32_e32 v138, v74, v175
	v_fmac_f32_e32 v220, v90, v176
	global_store_dword v162, v138, s[48:49]
	global_store_dword v162, v220, s[48:49] offset:128
	s_waitcnt vmcnt(30)
	v_fmac_f32_e32 v139, v75, v175
	v_fmac_f32_e32 v221, v91, v176
	global_store_dword v163, v139, s[48:49]
	global_store_dword v163, v221, s[48:49] offset:128
	s_waitcnt vmcnt(30)
	v_fmac_f32_e32 v140, v76, v175
	v_fmac_f32_e32 v222, v92, v176
	global_store_dword v164, v140, s[48:49]
	global_store_dword v164, v222, s[48:49] offset:128
	s_waitcnt vmcnt(30)
	v_fmac_f32_e32 v141, v77, v175
	v_fmac_f32_e32 v223, v93, v176
	global_store_dword v165, v141, s[48:49]
	global_store_dword v165, v223, s[48:49] offset:128
	s_add_u32 s48, s48, 0x8000
	s_addc_u32 s49, s49, 0
	s_waitcnt vmcnt(30)
	v_fmac_f32_e32 v142, v78, v175
	v_fmac_f32_e32 v224, v94, v176
	global_store_dword v162, v142, s[48:49]
	global_store_dword v162, v224, s[48:49] offset:128
	s_waitcnt vmcnt(30)
	v_fmac_f32_e32 v143, v79, v175
	v_fmac_f32_e32 v225, v95, v176
	global_store_dword v163, v143, s[48:49]
	global_store_dword v163, v225, s[48:49] offset:128
	s_waitcnt vmcnt(30)
	v_fmac_f32_e32 v144, v80, v175
	v_fmac_f32_e32 v226, v96, v176
	global_store_dword v164, v144, s[48:49]
	global_store_dword v164, v226, s[48:49] offset:128
	s_waitcnt vmcnt(30)
	v_fmac_f32_e32 v145, v81, v175
	v_fmac_f32_e32 v227, v97, v176
	global_store_dword v165, v145, s[48:49]
	global_store_dword v165, v227, s[48:49] offset:128
	s_sub_u32 s48, s48, 0x18000
	s_subb_u32 s49, s49, 0
	v_mul_f32_e32 v130, v130, v130
	v_fmac_f32_e32 v130, v212, v212
	v_mul_f32_e32 v131, v131, v131
	v_fmac_f32_e32 v131, v213, v213
	v_mul_f32_e32 v132, v132, v132
	v_fmac_f32_e32 v132, v214, v214
	v_mul_f32_e32 v133, v133, v133
	v_fmac_f32_e32 v133, v215, v215
	v_mul_f32_e32 v134, v134, v134
	v_fmac_f32_e32 v134, v216, v216
	v_mul_f32_e32 v135, v135, v135
	v_fmac_f32_e32 v135, v217, v217
	v_mul_f32_e32 v136, v136, v136
	v_fmac_f32_e32 v136, v218, v218
	v_mul_f32_e32 v137, v137, v137
	v_fmac_f32_e32 v137, v219, v219
	v_mul_f32_e32 v138, v138, v138
	v_fmac_f32_e32 v138, v220, v220
	v_mul_f32_e32 v139, v139, v139
	v_fmac_f32_e32 v139, v221, v221
	v_mul_f32_e32 v140, v140, v140
	v_fmac_f32_e32 v140, v222, v222
	v_mul_f32_e32 v141, v141, v141
	v_fmac_f32_e32 v141, v223, v223
	v_mul_f32_e32 v142, v142, v142
	v_fmac_f32_e32 v142, v224, v224
	v_mul_f32_e32 v143, v143, v143
	v_fmac_f32_e32 v143, v225, v225
	v_mul_f32_e32 v144, v144, v144
	v_fmac_f32_e32 v144, v226, v226
	v_mul_f32_e32 v145, v145, v145
	v_fmac_f32_e32 v145, v227, v227
	s_waitcnt lgkmcnt(0)
	ds_bpermute_b32 v212, v168, v130
	ds_bpermute_b32 v213, v168, v131
	ds_bpermute_b32 v214, v168, v132
	ds_bpermute_b32 v215, v168, v133
	ds_bpermute_b32 v216, v168, v134
	ds_bpermute_b32 v217, v168, v135
	ds_bpermute_b32 v218, v168, v136
	ds_bpermute_b32 v219, v168, v137
	s_waitcnt lgkmcnt(7)
	v_add_f32_e32 v130, v130, v212
	s_waitcnt lgkmcnt(6)
	v_add_f32_e32 v131, v131, v213
	s_waitcnt lgkmcnt(5)
	v_add_f32_e32 v132, v132, v214
	s_waitcnt lgkmcnt(4)
	v_add_f32_e32 v133, v133, v215
	s_waitcnt lgkmcnt(3)
	v_add_f32_e32 v134, v134, v216
	s_waitcnt lgkmcnt(2)
	v_add_f32_e32 v135, v135, v217
	s_waitcnt lgkmcnt(1)
	v_add_f32_e32 v136, v136, v218
	s_waitcnt lgkmcnt(0)
	v_add_f32_e32 v137, v137, v219
	ds_bpermute_b32 v212, v169, v130
	ds_bpermute_b32 v213, v169, v131
	ds_bpermute_b32 v214, v169, v132
	ds_bpermute_b32 v215, v169, v133
	ds_bpermute_b32 v216, v169, v134
	ds_bpermute_b32 v217, v169, v135
	ds_bpermute_b32 v218, v169, v136
	ds_bpermute_b32 v219, v169, v137
	s_waitcnt lgkmcnt(7)
	v_add_f32_e32 v130, v130, v212
	s_waitcnt lgkmcnt(6)
	v_add_f32_e32 v131, v131, v213
	s_waitcnt lgkmcnt(5)
	v_add_f32_e32 v132, v132, v214
	s_waitcnt lgkmcnt(4)
	v_add_f32_e32 v133, v133, v215
	s_waitcnt lgkmcnt(3)
	v_add_f32_e32 v134, v134, v216
	s_waitcnt lgkmcnt(2)
	v_add_f32_e32 v135, v135, v217
	s_waitcnt lgkmcnt(1)
	v_add_f32_e32 v136, v136, v218
	s_waitcnt lgkmcnt(0)
	v_add_f32_e32 v137, v137, v219
	ds_bpermute_b32 v212, v171, v130
	ds_bpermute_b32 v213, v171, v131
	ds_bpermute_b32 v214, v171, v132
	ds_bpermute_b32 v215, v171, v133
	ds_bpermute_b32 v216, v171, v134
	ds_bpermute_b32 v217, v171, v135
	ds_bpermute_b32 v218, v171, v136
	ds_bpermute_b32 v219, v171, v137
	s_waitcnt lgkmcnt(7)
	v_add_f32_e32 v130, v130, v212
	s_waitcnt lgkmcnt(6)
	v_add_f32_e32 v131, v131, v213
	s_waitcnt lgkmcnt(5)
	v_add_f32_e32 v132, v132, v214
	s_waitcnt lgkmcnt(4)
	v_add_f32_e32 v133, v133, v215
	s_waitcnt lgkmcnt(3)
	v_add_f32_e32 v134, v134, v216
	s_waitcnt lgkmcnt(2)
	v_add_f32_e32 v135, v135, v217
	s_waitcnt lgkmcnt(1)
	v_add_f32_e32 v136, v136, v218
	s_waitcnt lgkmcnt(0)
	v_add_f32_e32 v137, v137, v219
	ds_bpermute_b32 v212, v172, v130
	ds_bpermute_b32 v213, v172, v131
	ds_bpermute_b32 v214, v172, v132
	ds_bpermute_b32 v215, v172, v133
	ds_bpermute_b32 v216, v172, v134
	ds_bpermute_b32 v217, v172, v135
	ds_bpermute_b32 v218, v172, v136
	ds_bpermute_b32 v219, v172, v137
	s_waitcnt lgkmcnt(7)
	v_add_f32_e32 v130, v130, v212
	s_waitcnt lgkmcnt(6)
	v_add_f32_e32 v131, v131, v213
	s_waitcnt lgkmcnt(5)
	v_add_f32_e32 v132, v132, v214
	s_waitcnt lgkmcnt(4)
	v_add_f32_e32 v133, v133, v215
	s_waitcnt lgkmcnt(3)
	v_add_f32_e32 v134, v134, v216
	s_waitcnt lgkmcnt(2)
	v_add_f32_e32 v135, v135, v217
	s_waitcnt lgkmcnt(1)
	v_add_f32_e32 v136, v136, v218
	s_waitcnt lgkmcnt(0)
	v_add_f32_e32 v137, v137, v219
	ds_bpermute_b32 v212, v173, v130
	ds_bpermute_b32 v213, v173, v131
	ds_bpermute_b32 v214, v173, v132
	ds_bpermute_b32 v215, v173, v133
	ds_bpermute_b32 v216, v173, v134
	ds_bpermute_b32 v217, v173, v135
	ds_bpermute_b32 v218, v173, v136
	ds_bpermute_b32 v219, v173, v137
	s_waitcnt lgkmcnt(7)
	v_add_f32_e32 v130, v130, v212
	s_waitcnt lgkmcnt(6)
	v_add_f32_e32 v131, v131, v213
	s_waitcnt lgkmcnt(5)
	v_add_f32_e32 v132, v132, v214
	s_waitcnt lgkmcnt(4)
	v_add_f32_e32 v133, v133, v215
	s_waitcnt lgkmcnt(3)
	v_add_f32_e32 v134, v134, v216
	s_waitcnt lgkmcnt(2)
	v_add_f32_e32 v135, v135, v217
	s_waitcnt lgkmcnt(1)
	v_add_f32_e32 v136, v136, v218
	s_waitcnt lgkmcnt(0)
	v_add_f32_e32 v137, v137, v219
	ds_bpermute_b32 v220, v168, v138
	ds_bpermute_b32 v221, v168, v139
	ds_bpermute_b32 v222, v168, v140
	ds_bpermute_b32 v223, v168, v141
	ds_bpermute_b32 v224, v168, v142
	ds_bpermute_b32 v225, v168, v143
	ds_bpermute_b32 v226, v168, v144
	ds_bpermute_b32 v227, v168, v145
	s_waitcnt lgkmcnt(7)
	v_add_f32_e32 v138, v138, v220
	s_waitcnt lgkmcnt(6)
	v_add_f32_e32 v139, v139, v221
	s_waitcnt lgkmcnt(5)
	v_add_f32_e32 v140, v140, v222
	s_waitcnt lgkmcnt(4)
	v_add_f32_e32 v141, v141, v223
	s_waitcnt lgkmcnt(3)
	v_add_f32_e32 v142, v142, v224
	s_waitcnt lgkmcnt(2)
	v_add_f32_e32 v143, v143, v225
	s_waitcnt lgkmcnt(1)
	v_add_f32_e32 v144, v144, v226
	s_waitcnt lgkmcnt(0)
	v_add_f32_e32 v145, v145, v227
	ds_bpermute_b32 v220, v169, v138
	ds_bpermute_b32 v221, v169, v139
	ds_bpermute_b32 v222, v169, v140
	ds_bpermute_b32 v223, v169, v141
	ds_bpermute_b32 v224, v169, v142
	ds_bpermute_b32 v225, v169, v143
	ds_bpermute_b32 v226, v169, v144
	ds_bpermute_b32 v227, v169, v145
	s_waitcnt lgkmcnt(7)
	v_add_f32_e32 v138, v138, v220
	s_waitcnt lgkmcnt(6)
	v_add_f32_e32 v139, v139, v221
	s_waitcnt lgkmcnt(5)
	v_add_f32_e32 v140, v140, v222
	s_waitcnt lgkmcnt(4)
	v_add_f32_e32 v141, v141, v223
	s_waitcnt lgkmcnt(3)
	v_add_f32_e32 v142, v142, v224
	s_waitcnt lgkmcnt(2)
	v_add_f32_e32 v143, v143, v225
	s_waitcnt lgkmcnt(1)
	v_add_f32_e32 v144, v144, v226
	s_waitcnt lgkmcnt(0)
	v_add_f32_e32 v145, v145, v227
	ds_bpermute_b32 v220, v171, v138
	ds_bpermute_b32 v221, v171, v139
	ds_bpermute_b32 v222, v171, v140
	ds_bpermute_b32 v223, v171, v141
	ds_bpermute_b32 v224, v171, v142
	ds_bpermute_b32 v225, v171, v143
	ds_bpermute_b32 v226, v171, v144
	ds_bpermute_b32 v227, v171, v145
	s_waitcnt lgkmcnt(7)
	v_add_f32_e32 v138, v138, v220
	s_waitcnt lgkmcnt(6)
	v_add_f32_e32 v139, v139, v221
	s_waitcnt lgkmcnt(5)
	v_add_f32_e32 v140, v140, v222
	s_waitcnt lgkmcnt(4)
	v_add_f32_e32 v141, v141, v223
	s_waitcnt lgkmcnt(3)
	v_add_f32_e32 v142, v142, v224
	s_waitcnt lgkmcnt(2)
	v_add_f32_e32 v143, v143, v225
	s_waitcnt lgkmcnt(1)
	v_add_f32_e32 v144, v144, v226
	s_waitcnt lgkmcnt(0)
	v_add_f32_e32 v145, v145, v227
	ds_bpermute_b32 v220, v172, v138
	ds_bpermute_b32 v221, v172, v139
	ds_bpermute_b32 v222, v172, v140
	ds_bpermute_b32 v223, v172, v141
	ds_bpermute_b32 v224, v172, v142
	ds_bpermute_b32 v225, v172, v143
	ds_bpermute_b32 v226, v172, v144
	ds_bpermute_b32 v227, v172, v145
	s_waitcnt lgkmcnt(7)
	v_add_f32_e32 v138, v138, v220
	s_waitcnt lgkmcnt(6)
	v_add_f32_e32 v139, v139, v221
	s_waitcnt lgkmcnt(5)
	v_add_f32_e32 v140, v140, v222
	s_waitcnt lgkmcnt(4)
	v_add_f32_e32 v141, v141, v223
	s_waitcnt lgkmcnt(3)
	v_add_f32_e32 v142, v142, v224
	s_waitcnt lgkmcnt(2)
	v_add_f32_e32 v143, v143, v225
	s_waitcnt lgkmcnt(1)
	v_add_f32_e32 v144, v144, v226
	s_waitcnt lgkmcnt(0)
	v_add_f32_e32 v145, v145, v227
	ds_bpermute_b32 v220, v173, v138
	ds_bpermute_b32 v221, v173, v139
	ds_bpermute_b32 v222, v173, v140
	ds_bpermute_b32 v223, v173, v141
	ds_bpermute_b32 v224, v173, v142
	ds_bpermute_b32 v225, v173, v143
	ds_bpermute_b32 v226, v173, v144
	ds_bpermute_b32 v227, v173, v145
	s_waitcnt lgkmcnt(7)
	v_add_f32_e32 v138, v138, v220
	s_waitcnt lgkmcnt(6)
	v_add_f32_e32 v139, v139, v221
	s_waitcnt lgkmcnt(5)
	v_add_f32_e32 v140, v140, v222
	s_waitcnt lgkmcnt(4)
	v_add_f32_e32 v141, v141, v223
	s_waitcnt lgkmcnt(3)
	v_add_f32_e32 v142, v142, v224
	s_waitcnt lgkmcnt(2)
	v_add_f32_e32 v143, v143, v225
	s_waitcnt lgkmcnt(1)
	v_add_f32_e32 v144, v144, v226
	s_waitcnt lgkmcnt(0)
	v_add_f32_e32 v145, v145, v227
	v_cmp_eq_u32_e32 vcc, 0, v174
	s_and_saveexec_b64 s[58:59], vcc
	global_store_dword v167, v130, s[10:11]
	global_store_dword v167, v131, s[10:11] offset:4
	global_store_dword v167, v132, s[10:11] offset:8
	global_store_dword v167, v133, s[10:11] offset:12
	global_store_dword v167, v134, s[10:11] offset:32
	global_store_dword v167, v135, s[10:11] offset:36
	global_store_dword v167, v136, s[10:11] offset:40
	global_store_dword v167, v137, s[10:11] offset:44
	global_store_dword v167, v138, s[10:11] offset:64
	global_store_dword v167, v139, s[10:11] offset:68
	global_store_dword v167, v140, s[10:11] offset:72
	global_store_dword v167, v141, s[10:11] offset:76
	global_store_dword v167, v142, s[10:11] offset:96
	global_store_dword v167, v143, s[10:11] offset:100
	global_store_dword v167, v144, s[10:11] offset:104
	global_store_dword v167, v145, s[10:11] offset:108
	s_mov_b64 exec, -1
	s_add_u32 s48, s48, 0x20000
	s_addc_u32 s49, s49, 0
	global_load_dword v130, v162, s[48:49]
	global_load_dword v212, v162, s[48:49] offset:128
	global_load_dword v131, v163, s[48:49]
	global_load_dword v213, v163, s[48:49] offset:128
	global_load_dword v132, v164, s[48:49]
	global_load_dword v214, v164, s[48:49] offset:128
	global_load_dword v133, v165, s[48:49]
	global_load_dword v215, v165, s[48:49] offset:128
	s_add_u32 s48, s48, 0x8000
	s_addc_u32 s49, s49, 0
	global_load_dword v134, v162, s[48:49]
	global_load_dword v216, v162, s[48:49] offset:128
	global_load_dword v135, v163, s[48:49]
	global_load_dword v217, v163, s[48:49] offset:128
	global_load_dword v136, v164, s[48:49]
	global_load_dword v218, v164, s[48:49] offset:128
	global_load_dword v137, v165, s[48:49]
	global_load_dword v219, v165, s[48:49] offset:128
	s_add_u32 s48, s48, 0x8000
	s_addc_u32 s49, s49, 0
	global_load_dword v138, v162, s[48:49]
	global_load_dword v220, v162, s[48:49] offset:128
	global_load_dword v139, v163, s[48:49]
	global_load_dword v221, v163, s[48:49] offset:128
	global_load_dword v140, v164, s[48:49]
	global_load_dword v222, v164, s[48:49] offset:128
	global_load_dword v141, v165, s[48:49]
	global_load_dword v223, v165, s[48:49] offset:128
	s_add_u32 s48, s48, 0x8000
	s_addc_u32 s49, s49, 0
	global_load_dword v142, v162, s[48:49]
	global_load_dword v224, v162, s[48:49] offset:128
	global_load_dword v143, v163, s[48:49]
	global_load_dword v225, v163, s[48:49] offset:128
	global_load_dword v144, v164, s[48:49]
	global_load_dword v226, v164, s[48:49] offset:128
	global_load_dword v145, v165, s[48:49]
	global_load_dword v227, v165, s[48:49] offset:128
	s_sub_u32 s48, s48, 0x18000
	s_subb_u32 s49, s49, 0
	s_waitcnt vmcnt(30)
	v_fmac_f32_e32 v130, v98, v175
	v_fmac_f32_e32 v212, v114, v176
	global_store_dword v162, v130, s[48:49]
	global_store_dword v162, v212, s[48:49] offset:128
	s_waitcnt vmcnt(30)
	v_fmac_f32_e32 v131, v99, v175
	v_fmac_f32_e32 v213, v115, v176
	global_store_dword v163, v131, s[48:49]
	global_store_dword v163, v213, s[48:49] offset:128
	s_waitcnt vmcnt(30)
	v_fmac_f32_e32 v132, v100, v175
	v_fmac_f32_e32 v214, v116, v176
	global_store_dword v164, v132, s[48:49]
	global_store_dword v164, v214, s[48:49] offset:128
	s_waitcnt vmcnt(30)
	v_fmac_f32_e32 v133, v101, v175
	v_fmac_f32_e32 v215, v117, v176
	global_store_dword v165, v133, s[48:49]
	global_store_dword v165, v215, s[48:49] offset:128
	s_add_u32 s48, s48, 0x8000
	s_addc_u32 s49, s49, 0
	s_waitcnt vmcnt(30)
	v_fmac_f32_e32 v134, v102, v175
	v_fmac_f32_e32 v216, v118, v176
	global_store_dword v162, v134, s[48:49]
	global_store_dword v162, v216, s[48:49] offset:128
	s_waitcnt vmcnt(30)
	v_fmac_f32_e32 v135, v103, v175
	v_fmac_f32_e32 v217, v119, v176
	global_store_dword v163, v135, s[48:49]
	global_store_dword v163, v217, s[48:49] offset:128
	s_waitcnt vmcnt(30)
	v_fmac_f32_e32 v136, v104, v175
	v_fmac_f32_e32 v218, v120, v176
	global_store_dword v164, v136, s[48:49]
	global_store_dword v164, v218, s[48:49] offset:128
	s_waitcnt vmcnt(30)
	v_fmac_f32_e32 v137, v105, v175
	v_fmac_f32_e32 v219, v121, v176
	global_store_dword v165, v137, s[48:49]
	global_store_dword v165, v219, s[48:49] offset:128
	s_add_u32 s48, s48, 0x8000
	s_addc_u32 s49, s49, 0
	s_waitcnt vmcnt(30)
	v_fmac_f32_e32 v138, v106, v175
	v_fmac_f32_e32 v220, v122, v176
	global_store_dword v162, v138, s[48:49]
	global_store_dword v162, v220, s[48:49] offset:128
	s_waitcnt vmcnt(30)
	v_fmac_f32_e32 v139, v107, v175
	v_fmac_f32_e32 v221, v123, v176
	global_store_dword v163, v139, s[48:49]
	global_store_dword v163, v221, s[48:49] offset:128
	s_waitcnt vmcnt(30)
	v_fmac_f32_e32 v140, v108, v175
	v_fmac_f32_e32 v222, v124, v176
	global_store_dword v164, v140, s[48:49]
	global_store_dword v164, v222, s[48:49] offset:128
	s_waitcnt vmcnt(30)
	v_fmac_f32_e32 v141, v109, v175
	v_fmac_f32_e32 v223, v125, v176
	global_store_dword v165, v141, s[48:49]
	global_store_dword v165, v223, s[48:49] offset:128
	s_add_u32 s48, s48, 0x8000
	s_addc_u32 s49, s49, 0
	s_waitcnt vmcnt(30)
	v_fmac_f32_e32 v142, v110, v175
	v_fmac_f32_e32 v224, v126, v176
	global_store_dword v162, v142, s[48:49]
	global_store_dword v162, v224, s[48:49] offset:128
	s_waitcnt vmcnt(30)
	v_fmac_f32_e32 v143, v111, v175
	v_fmac_f32_e32 v225, v127, v176
	global_store_dword v163, v143, s[48:49]
	global_store_dword v163, v225, s[48:49] offset:128
	s_waitcnt vmcnt(30)
	v_fmac_f32_e32 v144, v112, v175
	v_fmac_f32_e32 v226, v128, v176
	global_store_dword v164, v144, s[48:49]
	global_store_dword v164, v226, s[48:49] offset:128
	s_waitcnt vmcnt(30)
	v_fmac_f32_e32 v145, v113, v175
	v_fmac_f32_e32 v227, v129, v176
	global_store_dword v165, v145, s[48:49]
	global_store_dword v165, v227, s[48:49] offset:128
	s_sub_u32 s48, s48, 0x18000
	s_subb_u32 s49, s49, 0
	v_mul_f32_e32 v130, v130, v130
	v_fmac_f32_e32 v130, v212, v212
	v_mul_f32_e32 v131, v131, v131
	v_fmac_f32_e32 v131, v213, v213
	v_mul_f32_e32 v132, v132, v132
	v_fmac_f32_e32 v132, v214, v214
	v_mul_f32_e32 v133, v133, v133
	v_fmac_f32_e32 v133, v215, v215
	v_mul_f32_e32 v134, v134, v134
	v_fmac_f32_e32 v134, v216, v216
	v_mul_f32_e32 v135, v135, v135
	v_fmac_f32_e32 v135, v217, v217
	v_mul_f32_e32 v136, v136, v136
	v_fmac_f32_e32 v136, v218, v218
	v_mul_f32_e32 v137, v137, v137
	v_fmac_f32_e32 v137, v219, v219
	v_mul_f32_e32 v138, v138, v138
	v_fmac_f32_e32 v138, v220, v220
	v_mul_f32_e32 v139, v139, v139
	v_fmac_f32_e32 v139, v221, v221
	v_mul_f32_e32 v140, v140, v140
	v_fmac_f32_e32 v140, v222, v222
	v_mul_f32_e32 v141, v141, v141
	v_fmac_f32_e32 v141, v223, v223
	v_mul_f32_e32 v142, v142, v142
	v_fmac_f32_e32 v142, v224, v224
	v_mul_f32_e32 v143, v143, v143
	v_fmac_f32_e32 v143, v225, v225
	v_mul_f32_e32 v144, v144, v144
	v_fmac_f32_e32 v144, v226, v226
	v_mul_f32_e32 v145, v145, v145
	v_fmac_f32_e32 v145, v227, v227
	s_waitcnt lgkmcnt(0)
	ds_bpermute_b32 v212, v168, v130
	ds_bpermute_b32 v213, v168, v131
	ds_bpermute_b32 v214, v168, v132
	ds_bpermute_b32 v215, v168, v133
	ds_bpermute_b32 v216, v168, v134
	ds_bpermute_b32 v217, v168, v135
	ds_bpermute_b32 v218, v168, v136
	ds_bpermute_b32 v219, v168, v137
	s_waitcnt lgkmcnt(7)
	v_add_f32_e32 v130, v130, v212
	s_waitcnt lgkmcnt(6)
	v_add_f32_e32 v131, v131, v213
	s_waitcnt lgkmcnt(5)
	v_add_f32_e32 v132, v132, v214
	s_waitcnt lgkmcnt(4)
	v_add_f32_e32 v133, v133, v215
	s_waitcnt lgkmcnt(3)
	v_add_f32_e32 v134, v134, v216
	s_waitcnt lgkmcnt(2)
	v_add_f32_e32 v135, v135, v217
	s_waitcnt lgkmcnt(1)
	v_add_f32_e32 v136, v136, v218
	s_waitcnt lgkmcnt(0)
	v_add_f32_e32 v137, v137, v219
	ds_bpermute_b32 v212, v169, v130
	ds_bpermute_b32 v213, v169, v131
	ds_bpermute_b32 v214, v169, v132
	ds_bpermute_b32 v215, v169, v133
	ds_bpermute_b32 v216, v169, v134
	ds_bpermute_b32 v217, v169, v135
	ds_bpermute_b32 v218, v169, v136
	ds_bpermute_b32 v219, v169, v137
	s_waitcnt lgkmcnt(7)
	v_add_f32_e32 v130, v130, v212
	s_waitcnt lgkmcnt(6)
	v_add_f32_e32 v131, v131, v213
	s_waitcnt lgkmcnt(5)
	v_add_f32_e32 v132, v132, v214
	s_waitcnt lgkmcnt(4)
	v_add_f32_e32 v133, v133, v215
	s_waitcnt lgkmcnt(3)
	v_add_f32_e32 v134, v134, v216
	s_waitcnt lgkmcnt(2)
	v_add_f32_e32 v135, v135, v217
	s_waitcnt lgkmcnt(1)
	v_add_f32_e32 v136, v136, v218
	s_waitcnt lgkmcnt(0)
	v_add_f32_e32 v137, v137, v219
	ds_bpermute_b32 v212, v171, v130
	ds_bpermute_b32 v213, v171, v131
	ds_bpermute_b32 v214, v171, v132
	ds_bpermute_b32 v215, v171, v133
	ds_bpermute_b32 v216, v171, v134
	ds_bpermute_b32 v217, v171, v135
	ds_bpermute_b32 v218, v171, v136
	ds_bpermute_b32 v219, v171, v137
	s_waitcnt lgkmcnt(7)
	v_add_f32_e32 v130, v130, v212
	s_waitcnt lgkmcnt(6)
	v_add_f32_e32 v131, v131, v213
	s_waitcnt lgkmcnt(5)
	v_add_f32_e32 v132, v132, v214
	s_waitcnt lgkmcnt(4)
	v_add_f32_e32 v133, v133, v215
	s_waitcnt lgkmcnt(3)
	v_add_f32_e32 v134, v134, v216
	s_waitcnt lgkmcnt(2)
	v_add_f32_e32 v135, v135, v217
	s_waitcnt lgkmcnt(1)
	v_add_f32_e32 v136, v136, v218
	s_waitcnt lgkmcnt(0)
	v_add_f32_e32 v137, v137, v219
	ds_bpermute_b32 v212, v172, v130
	ds_bpermute_b32 v213, v172, v131
	ds_bpermute_b32 v214, v172, v132
	ds_bpermute_b32 v215, v172, v133
	ds_bpermute_b32 v216, v172, v134
	ds_bpermute_b32 v217, v172, v135
	ds_bpermute_b32 v218, v172, v136
	ds_bpermute_b32 v219, v172, v137
	s_waitcnt lgkmcnt(7)
	v_add_f32_e32 v130, v130, v212
	s_waitcnt lgkmcnt(6)
	v_add_f32_e32 v131, v131, v213
	s_waitcnt lgkmcnt(5)
	v_add_f32_e32 v132, v132, v214
	s_waitcnt lgkmcnt(4)
	v_add_f32_e32 v133, v133, v215
	s_waitcnt lgkmcnt(3)
	v_add_f32_e32 v134, v134, v216
	s_waitcnt lgkmcnt(2)
	v_add_f32_e32 v135, v135, v217
	s_waitcnt lgkmcnt(1)
	v_add_f32_e32 v136, v136, v218
	s_waitcnt lgkmcnt(0)
	v_add_f32_e32 v137, v137, v219
	ds_bpermute_b32 v212, v173, v130
	ds_bpermute_b32 v213, v173, v131
	ds_bpermute_b32 v214, v173, v132
	ds_bpermute_b32 v215, v173, v133
	ds_bpermute_b32 v216, v173, v134
	ds_bpermute_b32 v217, v173, v135
	ds_bpermute_b32 v218, v173, v136
	ds_bpermute_b32 v219, v173, v137
	s_waitcnt lgkmcnt(7)
	v_add_f32_e32 v130, v130, v212
	s_waitcnt lgkmcnt(6)
	v_add_f32_e32 v131, v131, v213
	s_waitcnt lgkmcnt(5)
	v_add_f32_e32 v132, v132, v214
	s_waitcnt lgkmcnt(4)
	v_add_f32_e32 v133, v133, v215
	s_waitcnt lgkmcnt(3)
	v_add_f32_e32 v134, v134, v216
	s_waitcnt lgkmcnt(2)
	v_add_f32_e32 v135, v135, v217
	s_waitcnt lgkmcnt(1)
	v_add_f32_e32 v136, v136, v218
	s_waitcnt lgkmcnt(0)
	v_add_f32_e32 v137, v137, v219
	ds_bpermute_b32 v220, v168, v138
	ds_bpermute_b32 v221, v168, v139
	ds_bpermute_b32 v222, v168, v140
	ds_bpermute_b32 v223, v168, v141
	ds_bpermute_b32 v224, v168, v142
	ds_bpermute_b32 v225, v168, v143
	ds_bpermute_b32 v226, v168, v144
	ds_bpermute_b32 v227, v168, v145
	s_waitcnt lgkmcnt(7)
	v_add_f32_e32 v138, v138, v220
	s_waitcnt lgkmcnt(6)
	v_add_f32_e32 v139, v139, v221
	s_waitcnt lgkmcnt(5)
	v_add_f32_e32 v140, v140, v222
	s_waitcnt lgkmcnt(4)
	v_add_f32_e32 v141, v141, v223
	s_waitcnt lgkmcnt(3)
	v_add_f32_e32 v142, v142, v224
	s_waitcnt lgkmcnt(2)
	v_add_f32_e32 v143, v143, v225
	s_waitcnt lgkmcnt(1)
	v_add_f32_e32 v144, v144, v226
	s_waitcnt lgkmcnt(0)
	v_add_f32_e32 v145, v145, v227
	ds_bpermute_b32 v220, v169, v138
	ds_bpermute_b32 v221, v169, v139
	ds_bpermute_b32 v222, v169, v140
	ds_bpermute_b32 v223, v169, v141
	ds_bpermute_b32 v224, v169, v142
	ds_bpermute_b32 v225, v169, v143
	ds_bpermute_b32 v226, v169, v144
	ds_bpermute_b32 v227, v169, v145
	s_waitcnt lgkmcnt(7)
	v_add_f32_e32 v138, v138, v220
	s_waitcnt lgkmcnt(6)
	v_add_f32_e32 v139, v139, v221
	s_waitcnt lgkmcnt(5)
	v_add_f32_e32 v140, v140, v222
	s_waitcnt lgkmcnt(4)
	v_add_f32_e32 v141, v141, v223
	s_waitcnt lgkmcnt(3)
	v_add_f32_e32 v142, v142, v224
	s_waitcnt lgkmcnt(2)
	v_add_f32_e32 v143, v143, v225
	s_waitcnt lgkmcnt(1)
	v_add_f32_e32 v144, v144, v226
	s_waitcnt lgkmcnt(0)
	v_add_f32_e32 v145, v145, v227
	ds_bpermute_b32 v220, v171, v138
	ds_bpermute_b32 v221, v171, v139
	ds_bpermute_b32 v222, v171, v140
	ds_bpermute_b32 v223, v171, v141
	ds_bpermute_b32 v224, v171, v142
	ds_bpermute_b32 v225, v171, v143
	ds_bpermute_b32 v226, v171, v144
	ds_bpermute_b32 v227, v171, v145
	s_waitcnt lgkmcnt(7)
	v_add_f32_e32 v138, v138, v220
	s_waitcnt lgkmcnt(6)
	v_add_f32_e32 v139, v139, v221
	s_waitcnt lgkmcnt(5)
	v_add_f32_e32 v140, v140, v222
	s_waitcnt lgkmcnt(4)
	v_add_f32_e32 v141, v141, v223
	s_waitcnt lgkmcnt(3)
	v_add_f32_e32 v142, v142, v224
	s_waitcnt lgkmcnt(2)
	v_add_f32_e32 v143, v143, v225
	s_waitcnt lgkmcnt(1)
	v_add_f32_e32 v144, v144, v226
	s_waitcnt lgkmcnt(0)
	v_add_f32_e32 v145, v145, v227
	ds_bpermute_b32 v220, v172, v138
	ds_bpermute_b32 v221, v172, v139
	ds_bpermute_b32 v222, v172, v140
	ds_bpermute_b32 v223, v172, v141
	ds_bpermute_b32 v224, v172, v142
	ds_bpermute_b32 v225, v172, v143
	ds_bpermute_b32 v226, v172, v144
	ds_bpermute_b32 v227, v172, v145
	s_waitcnt lgkmcnt(7)
	v_add_f32_e32 v138, v138, v220
	s_waitcnt lgkmcnt(6)
	v_add_f32_e32 v139, v139, v221
	s_waitcnt lgkmcnt(5)
	v_add_f32_e32 v140, v140, v222
	s_waitcnt lgkmcnt(4)
	v_add_f32_e32 v141, v141, v223
	s_waitcnt lgkmcnt(3)
	v_add_f32_e32 v142, v142, v224
	s_waitcnt lgkmcnt(2)
	v_add_f32_e32 v143, v143, v225
	s_waitcnt lgkmcnt(1)
	v_add_f32_e32 v144, v144, v226
	s_waitcnt lgkmcnt(0)
	v_add_f32_e32 v145, v145, v227
	ds_bpermute_b32 v220, v173, v138
	ds_bpermute_b32 v221, v173, v139
	ds_bpermute_b32 v222, v173, v140
	ds_bpermute_b32 v223, v173, v141
	ds_bpermute_b32 v224, v173, v142
	ds_bpermute_b32 v225, v173, v143
	ds_bpermute_b32 v226, v173, v144
	ds_bpermute_b32 v227, v173, v145
	s_waitcnt lgkmcnt(7)
	v_add_f32_e32 v138, v138, v220
	s_waitcnt lgkmcnt(6)
	v_add_f32_e32 v139, v139, v221
	s_waitcnt lgkmcnt(5)
	v_add_f32_e32 v140, v140, v222
	s_waitcnt lgkmcnt(4)
	v_add_f32_e32 v141, v141, v223
	s_waitcnt lgkmcnt(3)
	v_add_f32_e32 v142, v142, v224
	s_waitcnt lgkmcnt(2)
	v_add_f32_e32 v143, v143, v225
	s_waitcnt lgkmcnt(1)
	v_add_f32_e32 v144, v144, v226
	s_waitcnt lgkmcnt(0)
	v_add_f32_e32 v145, v145, v227
	v_cmp_eq_u32_e32 vcc, 0, v174
	s_and_saveexec_b64 s[58:59], vcc
	global_store_dword v167, v130, s[10:11] offset:128
	global_store_dword v167, v131, s[10:11] offset:132
	global_store_dword v167, v132, s[10:11] offset:136
	global_store_dword v167, v133, s[10:11] offset:140
	global_store_dword v167, v134, s[10:11] offset:160
	global_store_dword v167, v135, s[10:11] offset:164
	global_store_dword v167, v136, s[10:11] offset:168
	global_store_dword v167, v137, s[10:11] offset:172
	global_store_dword v167, v138, s[10:11] offset:192
	global_store_dword v167, v139, s[10:11] offset:196
	global_store_dword v167, v140, s[10:11] offset:200
	global_store_dword v167, v141, s[10:11] offset:204
	global_store_dword v167, v142, s[10:11] offset:224
	global_store_dword v167, v143, s[10:11] offset:228
	global_store_dword v167, v144, s[10:11] offset:232
	global_store_dword v167, v145, s[10:11] offset:236
	s_mov_b64 exec, -1
	s_sub_u32 s48, s48, 0x20000
	s_subb_u32 s49, s49, 0
	v_readlane_b32 s2, v246, 14
	s_nop 0
	s_add_i32 s16, s16, s2
	s_branch .Lhw_outproj_tloop

.Lhw_ffndown_tloop:
	s_cmpk_gt_u32 s16, 47
	s_cbranch_scc1 .Lhw_ffndown_exit
	v_readlane_b32 s6, v246, 16
	s_lshr_b32 s2, s16, 2
	s_and_b32 s15, s16, 3
	s_add_i32 s6, s6, s2
	s_lshl_b32 s6, s6, 7
	s_lshl_b32 s15, s15, 8
	s_mul_i32 vcc_lo, s6, 0x1600
	s_add_u32 s66, s42, vcc_lo
	s_addc_u32 s67, s43, 0
	s_mul_i32 vcc_lo, s15, 0x1600
	s_add_u32 s62, s46, vcc_lo
	s_addc_u32 s63, s47, 0
	s_add_u32 s18, s62, 0xb0000
	s_addc_u32 s19, s63, 0
	s_barrier
	s_add_u32 m0, s65, 0x0
	s_nop 0
	global_load_lds_dwordx4 v160, s[66:67]
	s_add_u32 m0, s65, 0x1000
	s_nop 0
	global_load_lds_dwordx4 v161, s[66:67]
	s_add_u32 m0, s65, 0x2000
	s_nop 0
	global_load_lds_dwordx4 v160, s[62:63]
	s_add_u32 m0, s65, 0x3000
	s_nop 0
	global_load_lds_dwordx4 v161, s[62:63]
	s_add_u32 m0, s65, 0x4000
	s_nop 0
	global_load_lds_dwordx4 v160, s[18:19]
	s_add_u32 m0, s65, 0x5000
	s_nop 0
	global_load_lds_dwordx4 v161, s[18:19]
	s_add_u32 s66, s66, 64
	s_addc_u32 s67, s67, 0
	s_add_u32 s62, s62, 64
	s_addc_u32 s63, s63, 0
	s_add_u32 s18, s18, 64
	s_addc_u32 s19, s19, 0
	s_add_u32 m0, s65, 0x6000
	s_nop 0
	global_load_lds_dwordx4 v160, s[66:67]
	s_add_u32 m0, s65, 0x7000
	s_nop 0
	global_load_lds_dwordx4 v161, s[66:67]
	s_add_u32 m0, s65, 0x8000
	s_nop 0
	global_load_lds_dwordx4 v160, s[62:63]
	s_add_u32 m0, s65, 0x9000
	s_nop 0
	global_load_lds_dwordx4 v161, s[62:63]
	s_add_u32 m0, s65, 0xa000
	s_nop 0
	global_load_lds_dwordx4 v160, s[18:19]
	s_add_u32 m0, s65, 0xb000
	s_nop 0
	global_load_lds_dwordx4 v161, s[18:19]
	s_add_u32 s66, s66, 64
	s_addc_u32 s67, s67, 0
	s_add_u32 s62, s62, 64
	s_addc_u32 s63, s63, 0
	s_add_u32 s18, s18, 64
	s_addc_u32 s19, s19, 0
	v_mov_b32_e32 v2, 0
	v_mov_b32_e32 v3, 0
	v_mov_b32_e32 v4, 0
	v_mov_b32_e32 v5, 0
	v_mov_b32_e32 v6, 0
	v_mov_b32_e32 v7, 0
	v_mov_b32_e32 v8, 0
	v_mov_b32_e32 v9, 0
	v_mov_b32_e32 v10, 0
	v_mov_b32_e32 v11, 0
	v_mov_b32_e32 v12, 0
	v_mov_b32_e32 v13, 0
	v_mov_b32_e32 v14, 0
	v_mov_b32_e32 v15, 0
	v_mov_b32_e32 v16, 0
	v_mov_b32_e32 v17, 0
	v_mov_b32_e32 v18, 0
	v_mov_b32_e32 v19, 0
	v_mov_b32_e32 v20, 0
	v_mov_b32_e32 v21, 0
	v_mov_b32_e32 v22, 0
	v_mov_b32_e32 v23, 0
	v_mov_b32_e32 v24, 0
	v_mov_b32_e32 v25, 0
	v_mov_b32_e32 v26, 0
	v_mov_b32_e32 v27, 0
	v_mov_b32_e32 v28, 0
	v_mov_b32_e32 v29, 0
	v_mov_b32_e32 v30, 0
	v_mov_b32_e32 v31, 0
	v_mov_b32_e32 v32, 0
	v_mov_b32_e32 v33, 0
	v_mov_b32_e32 v34, 0
	v_mov_b32_e32 v35, 0
	v_mov_b32_e32 v36, 0
	v_mov_b32_e32 v37, 0
	v_mov_b32_e32 v38, 0
	v_mov_b32_e32 v39, 0
	v_mov_b32_e32 v40, 0
	v_mov_b32_e32 v41, 0
	v_mov_b32_e32 v42, 0
	v_mov_b32_e32 v43, 0
	v_mov_b32_e32 v44, 0
	v_mov_b32_e32 v45, 0
	v_mov_b32_e32 v46, 0
	v_mov_b32_e32 v47, 0
	v_mov_b32_e32 v48, 0
	v_mov_b32_e32 v49, 0
	v_mov_b32_e32 v50, 0
	v_mov_b32_e32 v51, 0
	v_mov_b32_e32 v52, 0
	v_mov_b32_e32 v53, 0
	v_mov_b32_e32 v54, 0
	v_mov_b32_e32 v55, 0
	v_mov_b32_e32 v56, 0
	v_mov_b32_e32 v57, 0
	v_mov_b32_e32 v58, 0
	v_mov_b32_e32 v59, 0
	v_mov_b32_e32 v60, 0
	v_mov_b32_e32 v61, 0
	v_mov_b32_e32 v62, 0
	v_mov_b32_e32 v63, 0
	v_mov_b32_e32 v64, 0
	v_mov_b32_e32 v65, 0
	v_mov_b32_e32 v66, 0
	v_mov_b32_e32 v67, 0
	v_mov_b32_e32 v68, 0
	v_mov_b32_e32 v69, 0
	v_mov_b32_e32 v70, 0
	v_mov_b32_e32 v71, 0
	v_mov_b32_e32 v72, 0
	v_mov_b32_e32 v73, 0
	v_mov_b32_e32 v74, 0
	v_mov_b32_e32 v75, 0
	v_mov_b32_e32 v76, 0
	v_mov_b32_e32 v77, 0
	v_mov_b32_e32 v78, 0
	v_mov_b32_e32 v79, 0
	v_mov_b32_e32 v80, 0
	v_mov_b32_e32 v81, 0
	v_mov_b32_e32 v82, 0
	v_mov_b32_e32 v83, 0
	v_mov_b32_e32 v84, 0
	v_mov_b32_e32 v85, 0
	v_mov_b32_e32 v86, 0
	v_mov_b32_e32 v87, 0
	v_mov_b32_e32 v88, 0
	v_mov_b32_e32 v89, 0
	v_mov_b32_e32 v90, 0
	v_mov_b32_e32 v91, 0
	v_mov_b32_e32 v92, 0
	v_mov_b32_e32 v93, 0
	v_mov_b32_e32 v94, 0
	v_mov_b32_e32 v95, 0
	v_mov_b32_e32 v96, 0
	v_mov_b32_e32 v97, 0
	v_mov_b32_e32 v98, 0
	v_mov_b32_e32 v99, 0
	v_mov_b32_e32 v100, 0
	v_mov_b32_e32 v101, 0
	v_mov_b32_e32 v102, 0
	v_mov_b32_e32 v103, 0
	v_mov_b32_e32 v104, 0
	v_mov_b32_e32 v105, 0
	v_mov_b32_e32 v106, 0
	v_mov_b32_e32 v107, 0
	v_mov_b32_e32 v108, 0
	v_mov_b32_e32 v109, 0
	v_mov_b32_e32 v110, 0
	v_mov_b32_e32 v111, 0
	v_mov_b32_e32 v112, 0
	v_mov_b32_e32 v113, 0
	v_mov_b32_e32 v114, 0
	v_mov_b32_e32 v115, 0
	v_mov_b32_e32 v116, 0
	v_mov_b32_e32 v117, 0
	v_mov_b32_e32 v118, 0
	v_mov_b32_e32 v119, 0
	v_mov_b32_e32 v120, 0
	v_mov_b32_e32 v121, 0
	v_mov_b32_e32 v122, 0
	v_mov_b32_e32 v123, 0
	v_mov_b32_e32 v124, 0
	v_mov_b32_e32 v125, 0
	v_mov_b32_e32 v126, 0
	v_mov_b32_e32 v127, 0
	v_mov_b32_e32 v128, 0
	v_mov_b32_e32 v129, 0
	s_mov_b32 s59, 28
.Lhw_ffndown_loop:
	s_waitcnt vmcnt(6)
	s_barrier
	ds_read_b128 v[130:133], v154 offset:16
	ds_read_b128 v[138:141], v156 offset:8208
	ds_read_b128 v[142:145], v156 offset:10256
	ds_read_b128 v[134:137], v154 offset:2064
	ds_read_b128 v[146:149], v158 offset:8208
	ds_read_b128 v[150:153], v158 offset:10256
	s_waitcnt lgkmcnt(4)
	v_mfma_f32_32x32x16_bf16 v[2:17], v[130:133], v[138:141], v[2:17]
	ds_read_b128 v[212:215], v155 offset:16
	s_add_u32 m0, s65, 0xc000
	s_waitcnt lgkmcnt(4)
	v_mfma_f32_32x32x16_bf16 v[18:33], v[130:133], v[142:145], v[18:33]
	ds_read_b128 v[220:223], v157 offset:8208
	global_load_lds_dwordx4 v160, s[66:67]
	s_waitcnt lgkmcnt(4)
	v_mfma_f32_32x32x16_bf16 v[34:49], v[134:137], v[138:141], v[34:49]
	ds_read_b128 v[224:227], v157 offset:10256
	s_add_u32 m0, s65, 0xd000
	s_waitcnt lgkmcnt(5)
	v_mfma_f32_32x32x16_bf16 v[50:65], v[134:137], v[142:145], v[50:65]
	ds_read_b128 v[216:219], v155 offset:2064
	global_load_lds_dwordx4 v161, s[66:67]
	s_waitcnt lgkmcnt(5)
	v_mfma_f32_32x32x16_bf16 v[66:81], v[130:133], v[146:149], v[66:81]
	ds_read_b128 v[228:231], v159 offset:8208
	s_add_u32 m0, s65, 0xe000
	s_waitcnt lgkmcnt(5)
	v_mfma_f32_32x32x16_bf16 v[82:97], v[130:133], v[150:153], v[82:97]
	ds_read_b128 v[232:235], v159 offset:10256
	global_load_lds_dwordx4 v160, s[62:63]
	s_waitcnt lgkmcnt(7)
	v_mfma_f32_32x32x16_bf16 v[98:113], v[134:137], v[146:149], v[98:113]
	s_add_u32 m0, s65, 0xf000
	s_waitcnt lgkmcnt(6)
	v_mfma_f32_32x32x16_bf16 v[114:129], v[134:137], v[150:153], v[114:129]
	global_load_lds_dwordx4 v161, s[62:63]
	s_waitcnt lgkmcnt(4)
	v_mfma_f32_32x32x16_bf16 v[2:17], v[212:215], v[220:223], v[2:17]
	s_add_u32 m0, s65, 0x10000
	s_waitcnt lgkmcnt(3)
	v_mfma_f32_32x32x16_bf16 v[18:33], v[212:215], v[224:227], v[18:33]
	global_load_lds_dwordx4 v160, s[18:19]
	s_waitcnt lgkmcnt(2)
	v_mfma_f32_32x32x16_bf16 v[34:49], v[216:219], v[220:223], v[34:49]
	s_add_u32 m0, s65, 0x11000
	s_waitcnt lgkmcnt(2)
	v_mfma_f32_32x32x16_bf16 v[50:65], v[216:219], v[224:227], v[50:65]
	global_load_lds_dwordx4 v161, s[18:19]
	s_waitcnt lgkmcnt(1)
	v_mfma_f32_32x32x16_bf16 v[66:81], v[212:215], v[228:231], v[66:81]
	s_add_u32 s66, s66, 64
	s_addc_u32 s67, s67, 0
	s_waitcnt lgkmcnt(0)
	v_mfma_f32_32x32x16_bf16 v[82:97], v[212:215], v[232:235], v[82:97]
	s_add_u32 s62, s62, 64
	s_addc_u32 s63, s63, 0
	s_waitcnt lgkmcnt(1)
	v_mfma_f32_32x32x16_bf16 v[98:113], v[216:219], v[228:231], v[98:113]
	s_add_u32 s18, s18, 64
	s_addc_u32 s19, s19, 0
	s_waitcnt lgkmcnt(0)
	v_mfma_f32_32x32x16_bf16 v[114:129], v[216:219], v[232:235], v[114:129]
	s_waitcnt vmcnt(6)
	s_barrier
	ds_read_b128 v[130:133], v154 offset:24592
	ds_read_b128 v[138:141], v156 offset:32784
	ds_read_b128 v[142:145], v156 offset:34832
	ds_read_b128 v[134:137], v154 offset:26640
	ds_read_b128 v[146:149], v158 offset:32784
	ds_read_b128 v[150:153], v158 offset:34832
	s_waitcnt lgkmcnt(4)
	v_mfma_f32_32x32x16_bf16 v[2:17], v[130:133], v[138:141], v[2:17]
	ds_read_b128 v[212:215], v155 offset:24592
	s_add_u32 m0, s65, 0x0
	s_waitcnt lgkmcnt(4)
	v_mfma_f32_32x32x16_bf16 v[18:33], v[130:133], v[142:145], v[18:33]
	ds_read_b128 v[220:223], v157 offset:32784
	global_load_lds_dwordx4 v160, s[66:67]
	s_waitcnt lgkmcnt(4)
	v_mfma_f32_32x32x16_bf16 v[34:49], v[134:137], v[138:141], v[34:49]
	ds_read_b128 v[224:227], v157 offset:34832
	s_add_u32 m0, s65, 0x1000
	s_waitcnt lgkmcnt(5)
	v_mfma_f32_32x32x16_bf16 v[50:65], v[134:137], v[142:145], v[50:65]
	ds_read_b128 v[216:219], v155 offset:26640
	global_load_lds_dwordx4 v161, s[66:67]
	s_waitcnt lgkmcnt(5)
	v_mfma_f32_32x32x16_bf16 v[66:81], v[130:133], v[146:149], v[66:81]
	ds_read_b128 v[228:231], v159 offset:32784
	s_add_u32 m0, s65, 0x2000
	s_waitcnt lgkmcnt(5)
	v_mfma_f32_32x32x16_bf16 v[82:97], v[130:133], v[150:153], v[82:97]
	ds_read_b128 v[232:235], v159 offset:34832
	global_load_lds_dwordx4 v160, s[62:63]
	s_waitcnt lgkmcnt(7)
	v_mfma_f32_32x32x16_bf16 v[98:113], v[134:137], v[146:149], v[98:113]
	s_add_u32 m0, s65, 0x3000
	s_waitcnt lgkmcnt(6)
	v_mfma_f32_32x32x16_bf16 v[114:129], v[134:137], v[150:153], v[114:129]
	global_load_lds_dwordx4 v161, s[62:63]
	s_waitcnt lgkmcnt(4)
	v_mfma_f32_32x32x16_bf16 v[2:17], v[212:215], v[220:223], v[2:17]
	s_add_u32 m0, s65, 0x4000
	s_waitcnt lgkmcnt(3)
	v_mfma_f32_32x32x16_bf16 v[18:33], v[212:215], v[224:227], v[18:33]
	global_load_lds_dwordx4 v160, s[18:19]
	s_waitcnt lgkmcnt(2)
	v_mfma_f32_32x32x16_bf16 v[34:49], v[216:219], v[220:223], v[34:49]
	s_add_u32 m0, s65, 0x5000
	s_waitcnt lgkmcnt(2)
	v_mfma_f32_32x32x16_bf16 v[50:65], v[216:219], v[224:227], v[50:65]
	global_load_lds_dwordx4 v161, s[18:19]
	s_waitcnt lgkmcnt(1)
	v_mfma_f32_32x32x16_bf16 v[66:81], v[212:215], v[228:231], v[66:81]
	s_add_u32 s66, s66, 64
	s_addc_u32 s67, s67, 0
	s_waitcnt lgkmcnt(0)
	v_mfma_f32_32x32x16_bf16 v[82:97], v[212:215], v[232:235], v[82:97]
	s_add_u32 s62, s62, 64
	s_addc_u32 s63, s63, 0
	s_waitcnt lgkmcnt(1)
	v_mfma_f32_32x32x16_bf16 v[98:113], v[216:219], v[228:231], v[98:113]
	s_add_u32 s18, s18, 64
	s_addc_u32 s19, s19, 0
	s_waitcnt lgkmcnt(0)
	v_mfma_f32_32x32x16_bf16 v[114:129], v[216:219], v[232:235], v[114:129]
	s_waitcnt vmcnt(6)
	s_barrier
	ds_read_b128 v[130:133], v154 offset:49168
	ds_read_b128 v[138:141], v156 offset:57360
	ds_read_b128 v[142:145], v156 offset:59408
	ds_read_b128 v[134:137], v154 offset:51216
	ds_read_b128 v[146:149], v158 offset:57360
	ds_read_b128 v[150:153], v158 offset:59408
	s_waitcnt lgkmcnt(4)
	v_mfma_f32_32x32x16_bf16 v[2:17], v[130:133], v[138:141], v[2:17]
	ds_read_b128 v[212:215], v155 offset:49168
	s_add_u32 m0, s65, 0x6000
	s_waitcnt lgkmcnt(4)
	v_mfma_f32_32x32x16_bf16 v[18:33], v[130:133], v[142:145], v[18:33]
	ds_read_b128 v[220:223], v157 offset:57360
	global_load_lds_dwordx4 v160, s[66:67]
	s_waitcnt lgkmcnt(4)
	v_mfma_f32_32x32x16_bf16 v[34:49], v[134:137], v[138:141], v[34:49]
	ds_read_b128 v[224:227], v157 offset:59408
	s_add_u32 m0, s65, 0x7000
	s_waitcnt lgkmcnt(5)
	v_mfma_f32_32x32x16_bf16 v[50:65], v[134:137], v[142:145], v[50:65]
	ds_read_b128 v[216:219], v155 offset:51216
	global_load_lds_dwordx4 v161, s[66:67]
	s_waitcnt lgkmcnt(5)
	v_mfma_f32_32x32x16_bf16 v[66:81], v[130:133], v[146:149], v[66:81]
	ds_read_b128 v[228:231], v159 offset:57360
	s_add_u32 m0, s65, 0x8000
	s_waitcnt lgkmcnt(5)
	v_mfma_f32_32x32x16_bf16 v[82:97], v[130:133], v[150:153], v[82:97]
	ds_read_b128 v[232:235], v159 offset:59408
	global_load_lds_dwordx4 v160, s[62:63]
	s_waitcnt lgkmcnt(7)
	v_mfma_f32_32x32x16_bf16 v[98:113], v[134:137], v[146:149], v[98:113]
	s_add_u32 m0, s65, 0x9000
	s_waitcnt lgkmcnt(6)
	v_mfma_f32_32x32x16_bf16 v[114:129], v[134:137], v[150:153], v[114:129]
	global_load_lds_dwordx4 v161, s[62:63]
	s_waitcnt lgkmcnt(4)
	v_mfma_f32_32x32x16_bf16 v[2:17], v[212:215], v[220:223], v[2:17]
	s_add_u32 m0, s65, 0xa000
	s_waitcnt lgkmcnt(3)
	v_mfma_f32_32x32x16_bf16 v[18:33], v[212:215], v[224:227], v[18:33]
	global_load_lds_dwordx4 v160, s[18:19]
	s_waitcnt lgkmcnt(2)
	v_mfma_f32_32x32x16_bf16 v[34:49], v[216:219], v[220:223], v[34:49]
	s_add_u32 m0, s65, 0xb000
	s_waitcnt lgkmcnt(2)
	v_mfma_f32_32x32x16_bf16 v[50:65], v[216:219], v[224:227], v[50:65]
	global_load_lds_dwordx4 v161, s[18:19]
	s_waitcnt lgkmcnt(1)
	v_mfma_f32_32x32x16_bf16 v[66:81], v[212:215], v[228:231], v[66:81]
	s_add_u32 s66, s66, 64
	s_addc_u32 s67, s67, 0
	s_waitcnt lgkmcnt(0)
	v_mfma_f32_32x32x16_bf16 v[82:97], v[212:215], v[232:235], v[82:97]
	s_add_u32 s62, s62, 64
	s_addc_u32 s63, s63, 0
	s_waitcnt lgkmcnt(1)
	v_mfma_f32_32x32x16_bf16 v[98:113], v[216:219], v[228:231], v[98:113]
	s_add_u32 s18, s18, 64
	s_addc_u32 s19, s19, 0
	s_waitcnt lgkmcnt(0)
	v_mfma_f32_32x32x16_bf16 v[114:129], v[216:219], v[232:235], v[114:129]
	s_sub_u32 s59, s59, 1
	s_cmp_lg_u32 s59, 0
	s_cbranch_scc1 .Lhw_ffndown_loop
	s_waitcnt vmcnt(6)
	s_barrier
	ds_read_b128 v[130:133], v154 offset:16
	ds_read_b128 v[138:141], v156 offset:8208
	ds_read_b128 v[142:145], v156 offset:10256
	ds_read_b128 v[134:137], v154 offset:2064
	ds_read_b128 v[146:149], v158 offset:8208
	ds_read_b128 v[150:153], v158 offset:10256
	s_waitcnt lgkmcnt(4)
	v_mfma_f32_32x32x16_bf16 v[2:17], v[130:133], v[138:141], v[2:17]
	ds_read_b128 v[212:215], v155 offset:16
	s_add_u32 m0, s65, 0xc000
	s_waitcnt lgkmcnt(4)
	v_mfma_f32_32x32x16_bf16 v[18:33], v[130:133], v[142:145], v[18:33]
	ds_read_b128 v[220:223], v157 offset:8208
	global_load_lds_dwordx4 v160, s[66:67]
	s_waitcnt lgkmcnt(4)
	v_mfma_f32_32x32x16_bf16 v[34:49], v[134:137], v[138:141], v[34:49]
	ds_read_b128 v[224:227], v157 offset:10256
	s_add_u32 m0, s65, 0xd000
	s_waitcnt lgkmcnt(5)
	v_mfma_f32_32x32x16_bf16 v[50:65], v[134:137], v[142:145], v[50:65]
	ds_read_b128 v[216:219], v155 offset:2064
	global_load_lds_dwordx4 v161, s[66:67]
	s_waitcnt lgkmcnt(5)
	v_mfma_f32_32x32x16_bf16 v[66:81], v[130:133], v[146:149], v[66:81]
	ds_read_b128 v[228:231], v159 offset:8208
	s_add_u32 m0, s65, 0xe000
	s_waitcnt lgkmcnt(5)
	v_mfma_f32_32x32x16_bf16 v[82:97], v[130:133], v[150:153], v[82:97]
	ds_read_b128 v[232:235], v159 offset:10256
	global_load_lds_dwordx4 v160, s[62:63]
	s_waitcnt lgkmcnt(7)
	v_mfma_f32_32x32x16_bf16 v[98:113], v[134:137], v[146:149], v[98:113]
	s_add_u32 m0, s65, 0xf000
	s_waitcnt lgkmcnt(6)
	v_mfma_f32_32x32x16_bf16 v[114:129], v[134:137], v[150:153], v[114:129]
	global_load_lds_dwordx4 v161, s[62:63]
	s_waitcnt lgkmcnt(4)
	v_mfma_f32_32x32x16_bf16 v[2:17], v[212:215], v[220:223], v[2:17]
	s_add_u32 m0, s65, 0x10000
	s_waitcnt lgkmcnt(3)
	v_mfma_f32_32x32x16_bf16 v[18:33], v[212:215], v[224:227], v[18:33]
	global_load_lds_dwordx4 v160, s[18:19]
	s_waitcnt lgkmcnt(2)
	v_mfma_f32_32x32x16_bf16 v[34:49], v[216:219], v[220:223], v[34:49]
	s_add_u32 m0, s65, 0x11000
	s_waitcnt lgkmcnt(2)
	v_mfma_f32_32x32x16_bf16 v[50:65], v[216:219], v[224:227], v[50:65]
	global_load_lds_dwordx4 v161, s[18:19]
	s_waitcnt lgkmcnt(1)
	v_mfma_f32_32x32x16_bf16 v[66:81], v[212:215], v[228:231], v[66:81]
	s_add_u32 s66, s66, 64
	s_addc_u32 s67, s67, 0
	s_waitcnt lgkmcnt(0)
	v_mfma_f32_32x32x16_bf16 v[82:97], v[212:215], v[232:235], v[82:97]
	s_add_u32 s62, s62, 64
	s_addc_u32 s63, s63, 0
	s_waitcnt lgkmcnt(1)
	v_mfma_f32_32x32x16_bf16 v[98:113], v[216:219], v[228:231], v[98:113]
	s_add_u32 s18, s18, 64
	s_addc_u32 s19, s19, 0
	s_waitcnt lgkmcnt(0)
	v_mfma_f32_32x32x16_bf16 v[114:129], v[216:219], v[232:235], v[114:129]
	s_waitcnt vmcnt(6)
	s_barrier
	ds_read_b128 v[130:133], v154 offset:24592
	ds_read_b128 v[138:141], v156 offset:32784
	ds_read_b128 v[142:145], v156 offset:34832
	ds_read_b128 v[134:137], v154 offset:26640
	ds_read_b128 v[146:149], v158 offset:32784
	ds_read_b128 v[150:153], v158 offset:34832
	s_waitcnt lgkmcnt(4)
	v_mfma_f32_32x32x16_bf16 v[2:17], v[130:133], v[138:141], v[2:17]
	ds_read_b128 v[212:215], v155 offset:24592
	s_add_u32 m0, s65, 0x0
	s_waitcnt lgkmcnt(4)
	v_mfma_f32_32x32x16_bf16 v[18:33], v[130:133], v[142:145], v[18:33]
	ds_read_b128 v[220:223], v157 offset:32784
	global_load_lds_dwordx4 v160, s[66:67]
	s_waitcnt lgkmcnt(4)
	v_mfma_f32_32x32x16_bf16 v[34:49], v[134:137], v[138:141], v[34:49]
	ds_read_b128 v[224:227], v157 offset:34832
	s_add_u32 m0, s65, 0x1000
	s_waitcnt lgkmcnt(5)
	v_mfma_f32_32x32x16_bf16 v[50:65], v[134:137], v[142:145], v[50:65]
	ds_read_b128 v[216:219], v155 offset:26640
	global_load_lds_dwordx4 v161, s[66:67]
	s_waitcnt lgkmcnt(5)
	v_mfma_f32_32x32x16_bf16 v[66:81], v[130:133], v[146:149], v[66:81]
	ds_read_b128 v[228:231], v159 offset:32784
	s_add_u32 m0, s65, 0x2000
	s_waitcnt lgkmcnt(5)
	v_mfma_f32_32x32x16_bf16 v[82:97], v[130:133], v[150:153], v[82:97]
	ds_read_b128 v[232:235], v159 offset:34832
	global_load_lds_dwordx4 v160, s[62:63]
	s_waitcnt lgkmcnt(7)
	v_mfma_f32_32x32x16_bf16 v[98:113], v[134:137], v[146:149], v[98:113]
	s_add_u32 m0, s65, 0x3000
	s_waitcnt lgkmcnt(6)
	v_mfma_f32_32x32x16_bf16 v[114:129], v[134:137], v[150:153], v[114:129]
	global_load_lds_dwordx4 v161, s[62:63]
	s_waitcnt lgkmcnt(4)
	v_mfma_f32_32x32x16_bf16 v[2:17], v[212:215], v[220:223], v[2:17]
	s_add_u32 m0, s65, 0x4000
	s_waitcnt lgkmcnt(3)
	v_mfma_f32_32x32x16_bf16 v[18:33], v[212:215], v[224:227], v[18:33]
	global_load_lds_dwordx4 v160, s[18:19]
	s_waitcnt lgkmcnt(2)
	v_mfma_f32_32x32x16_bf16 v[34:49], v[216:219], v[220:223], v[34:49]
	s_add_u32 m0, s65, 0x5000
	s_waitcnt lgkmcnt(2)
	v_mfma_f32_32x32x16_bf16 v[50:65], v[216:219], v[224:227], v[50:65]
	global_load_lds_dwordx4 v161, s[18:19]
	s_waitcnt lgkmcnt(1)
	v_mfma_f32_32x32x16_bf16 v[66:81], v[212:215], v[228:231], v[66:81]
	s_add_u32 s66, s66, 64
	s_addc_u32 s67, s67, 0
	s_waitcnt lgkmcnt(0)
	v_mfma_f32_32x32x16_bf16 v[82:97], v[212:215], v[232:235], v[82:97]
	s_add_u32 s62, s62, 64
	s_addc_u32 s63, s63, 0
	s_waitcnt lgkmcnt(1)
	v_mfma_f32_32x32x16_bf16 v[98:113], v[216:219], v[228:231], v[98:113]
	s_add_u32 s18, s18, 64
	s_addc_u32 s19, s19, 0
	s_waitcnt lgkmcnt(0)
	v_mfma_f32_32x32x16_bf16 v[114:129], v[216:219], v[232:235], v[114:129]
	s_waitcnt vmcnt(6)
	s_barrier
	ds_read_b128 v[130:133], v154 offset:49168
	ds_read_b128 v[138:141], v156 offset:57360
	ds_read_b128 v[142:145], v156 offset:59408
	ds_read_b128 v[134:137], v154 offset:51216
	ds_read_b128 v[146:149], v158 offset:57360
	ds_read_b128 v[150:153], v158 offset:59408
	s_waitcnt lgkmcnt(4)
	v_mfma_f32_32x32x16_bf16 v[2:17], v[130:133], v[138:141], v[2:17]
	ds_read_b128 v[212:215], v155 offset:49168
	s_waitcnt lgkmcnt(4)
	v_mfma_f32_32x32x16_bf16 v[18:33], v[130:133], v[142:145], v[18:33]
	ds_read_b128 v[220:223], v157 offset:57360
	s_waitcnt lgkmcnt(4)
	v_mfma_f32_32x32x16_bf16 v[34:49], v[134:137], v[138:141], v[34:49]
	ds_read_b128 v[224:227], v157 offset:59408
	s_waitcnt lgkmcnt(5)
	v_mfma_f32_32x32x16_bf16 v[50:65], v[134:137], v[142:145], v[50:65]
	ds_read_b128 v[216:219], v155 offset:51216
	s_waitcnt lgkmcnt(5)
	v_mfma_f32_32x32x16_bf16 v[66:81], v[130:133], v[146:149], v[66:81]
	ds_read_b128 v[228:231], v159 offset:57360
	s_waitcnt lgkmcnt(5)
	v_mfma_f32_32x32x16_bf16 v[82:97], v[130:133], v[150:153], v[82:97]
	ds_read_b128 v[232:235], v159 offset:59408
	s_waitcnt lgkmcnt(7)
	v_mfma_f32_32x32x16_bf16 v[98:113], v[134:137], v[146:149], v[98:113]
	s_waitcnt lgkmcnt(6)
	v_mfma_f32_32x32x16_bf16 v[114:129], v[134:137], v[150:153], v[114:129]
	s_waitcnt lgkmcnt(4)
	v_mfma_f32_32x32x16_bf16 v[2:17], v[212:215], v[220:223], v[2:17]
	s_waitcnt lgkmcnt(3)
	v_mfma_f32_32x32x16_bf16 v[18:33], v[212:215], v[224:227], v[18:33]
	s_waitcnt lgkmcnt(2)
	v_mfma_f32_32x32x16_bf16 v[34:49], v[216:219], v[220:223], v[34:49]
	s_waitcnt lgkmcnt(2)
	v_mfma_f32_32x32x16_bf16 v[50:65], v[216:219], v[224:227], v[50:65]
	s_waitcnt lgkmcnt(1)
	v_mfma_f32_32x32x16_bf16 v[66:81], v[212:215], v[228:231], v[66:81]
	s_waitcnt lgkmcnt(0)
	v_mfma_f32_32x32x16_bf16 v[82:97], v[212:215], v[232:235], v[82:97]
	s_waitcnt lgkmcnt(1)
	v_mfma_f32_32x32x16_bf16 v[98:113], v[216:219], v[228:231], v[98:113]
	s_waitcnt lgkmcnt(0)
	v_mfma_f32_32x32x16_bf16 v[114:129], v[216:219], v[232:235], v[114:129]
	s_waitcnt vmcnt(0)
	s_barrier
	ds_read_b128 v[130:133], v154 offset:16
	ds_read_b128 v[138:141], v156 offset:8208
	ds_read_b128 v[142:145], v156 offset:10256
	ds_read_b128 v[134:137], v154 offset:2064
	ds_read_b128 v[146:149], v158 offset:8208
	ds_read_b128 v[150:153], v158 offset:10256
	s_waitcnt lgkmcnt(4)
	v_mfma_f32_32x32x16_bf16 v[2:17], v[130:133], v[138:141], v[2:17]
	ds_read_b128 v[212:215], v155 offset:16
	s_waitcnt lgkmcnt(4)
	v_mfma_f32_32x32x16_bf16 v[18:33], v[130:133], v[142:145], v[18:33]
	ds_read_b128 v[220:223], v157 offset:8208
	s_waitcnt lgkmcnt(4)
	v_mfma_f32_32x32x16_bf16 v[34:49], v[134:137], v[138:141], v[34:49]
	ds_read_b128 v[224:227], v157 offset:10256
	s_waitcnt lgkmcnt(5)
	v_mfma_f32_32x32x16_bf16 v[50:65], v[134:137], v[142:145], v[50:65]
	ds_read_b128 v[216:219], v155 offset:2064
	s_waitcnt lgkmcnt(5)
	v_mfma_f32_32x32x16_bf16 v[66:81], v[130:133], v[146:149], v[66:81]
	ds_read_b128 v[228:231], v159 offset:8208
	s_waitcnt lgkmcnt(5)
	v_mfma_f32_32x32x16_bf16 v[82:97], v[130:133], v[150:153], v[82:97]
	ds_read_b128 v[232:235], v159 offset:10256
	s_waitcnt lgkmcnt(7)
	v_mfma_f32_32x32x16_bf16 v[98:113], v[134:137], v[146:149], v[98:113]
	s_waitcnt lgkmcnt(6)
	v_mfma_f32_32x32x16_bf16 v[114:129], v[134:137], v[150:153], v[114:129]
	s_waitcnt lgkmcnt(4)
	v_mfma_f32_32x32x16_bf16 v[2:17], v[212:215], v[220:223], v[2:17]
	s_waitcnt lgkmcnt(3)
	v_mfma_f32_32x32x16_bf16 v[18:33], v[212:215], v[224:227], v[18:33]
	s_waitcnt lgkmcnt(2)
	v_mfma_f32_32x32x16_bf16 v[34:49], v[216:219], v[220:223], v[34:49]
	s_waitcnt lgkmcnt(2)
	v_mfma_f32_32x32x16_bf16 v[50:65], v[216:219], v[224:227], v[50:65]
	s_waitcnt lgkmcnt(1)
	v_mfma_f32_32x32x16_bf16 v[66:81], v[212:215], v[228:231], v[66:81]
	s_waitcnt lgkmcnt(0)
	v_mfma_f32_32x32x16_bf16 v[82:97], v[212:215], v[232:235], v[82:97]
	s_waitcnt lgkmcnt(1)
	v_mfma_f32_32x32x16_bf16 v[98:113], v[216:219], v[228:231], v[98:113]
	s_waitcnt lgkmcnt(0)
	v_mfma_f32_32x32x16_bf16 v[114:129], v[216:219], v[232:235], v[114:129]
	s_nop 7
	s_nop 7
	s_sub_i32 s2, s6, 0x1000
	s_ashr_i32 s2, s2, 11
	s_add_i32 s2, s2, 1
	s_max_i32 s2, s2, 0
	v_readlane_b32 s17, v246, 28
	s_nop 0
	s_add_i32 s2, s2, s17
	s_mul_i32 s2, s2, 0x9000
	s_lshl_b32 s17, s15, 2
	s_add_u32 s2, s2, s17
	s_add_u32 s60, s12, s2
	s_addc_u32 s61, s13, 0
	s_lshr_b32 s2, s15, 7
	s_mul_i32 s2, s2, 0x18000
	s_lshl_b32 s20, s6, 2
	s_add_u32 s2, s2, s20
	s_add_u32 s10, s44, s2
	s_addc_u32 s11, s45, 0
	s_lshl_b32 s2, s6, 12
	s_add_u32 s2, s2, s17
	s_add_u32 s48, s40, s2
	s_addc_u32 s49, s41, 0
	global_load_dword v175, v166, s[60:61]
	global_load_dword v176, v166, s[60:61] offset:128
	global_load_dword v130, v162, s[48:49]
	global_load_dword v212, v162, s[48:49] offset:128
	global_load_dword v131, v163, s[48:49]
	global_load_dword v213, v163, s[48:49] offset:128
	global_load_dword v132, v164, s[48:49]
	global_load_dword v214, v164, s[48:49] offset:128
	global_load_dword v133, v165, s[48:49]
	global_load_dword v215, v165, s[48:49] offset:128
	s_add_u32 s48, s48, 0x8000
	s_addc_u32 s49, s49, 0
	global_load_dword v134, v162, s[48:49]
	global_load_dword v216, v162, s[48:49] offset:128
	global_load_dword v135, v163, s[48:49]
	global_load_dword v217, v163, s[48:49] offset:128
	global_load_dword v136, v164, s[48:49]
	global_load_dword v218, v164, s[48:49] offset:128
	global_load_dword v137, v165, s[48:49]
	global_load_dword v219, v165, s[48:49] offset:128
	s_add_u32 s48, s48, 0x8000
	s_addc_u32 s49, s49, 0
	global_load_dword v138, v162, s[48:49]
	global_load_dword v220, v162, s[48:49] offset:128
	global_load_dword v139, v163, s[48:49]
	global_load_dword v221, v163, s[48:49] offset:128
	global_load_dword v140, v164, s[48:49]
	global_load_dword v222, v164, s[48:49] offset:128
	global_load_dword v141, v165, s[48:49]
	global_load_dword v223, v165, s[48:49] offset:128
	s_add_u32 s48, s48, 0x8000
	s_addc_u32 s49, s49, 0
	global_load_dword v142, v162, s[48:49]
	global_load_dword v224, v162, s[48:49] offset:128
	global_load_dword v143, v163, s[48:49]
	global_load_dword v225, v163, s[48:49] offset:128
	global_load_dword v144, v164, s[48:49]
	global_load_dword v226, v164, s[48:49] offset:128
	global_load_dword v145, v165, s[48:49]
	global_load_dword v227, v165, s[48:49] offset:128
	s_sub_u32 s48, s48, 0x18000
	s_subb_u32 s49, s49, 0
	s_waitcnt vmcnt(32)
	v_mul_f32_e32 v175, 0.5, v175
	v_mul_f32_e32 v176, 0.5, v176
	s_waitcnt vmcnt(30)
	v_fmac_f32_e32 v130, v2, v175
	v_fmac_f32_e32 v212, v18, v176
	global_store_dword v162, v130, s[48:49]
	global_store_dword v162, v212, s[48:49] offset:128
	s_waitcnt vmcnt(30)
	v_fmac_f32_e32 v131, v3, v175
	v_fmac_f32_e32 v213, v19, v176
	global_store_dword v163, v131, s[48:49]
	global_store_dword v163, v213, s[48:49] offset:128
	s_waitcnt vmcnt(30)
	v_fmac_f32_e32 v132, v4, v175
	v_fmac_f32_e32 v214, v20, v176
	global_store_dword v164, v132, s[48:49]
	global_store_dword v164, v214, s[48:49] offset:128
	s_waitcnt vmcnt(30)
	v_fmac_f32_e32 v133, v5, v175
	v_fmac_f32_e32 v215, v21, v176
	global_store_dword v165, v133, s[48:49]
	global_store_dword v165, v215, s[48:49] offset:128
	s_add_u32 s48, s48, 0x8000
	s_addc_u32 s49, s49, 0
	s_waitcnt vmcnt(30)
	v_fmac_f32_e32 v134, v6, v175
	v_fmac_f32_e32 v216, v22, v176
	global_store_dword v162, v134, s[48:49]
	global_store_dword v162, v216, s[48:49] offset:128
	s_waitcnt vmcnt(30)
	v_fmac_f32_e32 v135, v7, v175
	v_fmac_f32_e32 v217, v23, v176
	global_store_dword v163, v135, s[48:49]
	global_store_dword v163, v217, s[48:49] offset:128
	s_waitcnt vmcnt(30)
	v_fmac_f32_e32 v136, v8, v175
	v_fmac_f32_e32 v218, v24, v176
	global_store_dword v164, v136, s[48:49]
	global_store_dword v164, v218, s[48:49] offset:128
	s_waitcnt vmcnt(30)
	v_fmac_f32_e32 v137, v9, v175
	v_fmac_f32_e32 v219, v25, v176
	global_store_dword v165, v137, s[48:49]
	global_store_dword v165, v219, s[48:49] offset:128
	s_add_u32 s48, s48, 0x8000
	s_addc_u32 s49, s49, 0
	s_waitcnt vmcnt(30)
	v_fmac_f32_e32 v138, v10, v175
	v_fmac_f32_e32 v220, v26, v176
	global_store_dword v162, v138, s[48:49]
	global_store_dword v162, v220, s[48:49] offset:128
	s_waitcnt vmcnt(30)
	v_fmac_f32_e32 v139, v11, v175
	v_fmac_f32_e32 v221, v27, v176
	global_store_dword v163, v139, s[48:49]
	global_store_dword v163, v221, s[48:49] offset:128
	s_waitcnt vmcnt(30)
	v_fmac_f32_e32 v140, v12, v175
	v_fmac_f32_e32 v222, v28, v176
	global_store_dword v164, v140, s[48:49]
	global_store_dword v164, v222, s[48:49] offset:128
	s_waitcnt vmcnt(30)
	v_fmac_f32_e32 v141, v13, v175
	v_fmac_f32_e32 v223, v29, v176
	global_store_dword v165, v141, s[48:49]
	global_store_dword v165, v223, s[48:49] offset:128
	s_add_u32 s48, s48, 0x8000
	s_addc_u32 s49, s49, 0
	s_waitcnt vmcnt(30)
	v_fmac_f32_e32 v142, v14, v175
	v_fmac_f32_e32 v224, v30, v176
	global_store_dword v162, v142, s[48:49]
	global_store_dword v162, v224, s[48:49] offset:128
	s_waitcnt vmcnt(30)
	v_fmac_f32_e32 v143, v15, v175
	v_fmac_f32_e32 v225, v31, v176
	global_store_dword v163, v143, s[48:49]
	global_store_dword v163, v225, s[48:49] offset:128
	s_waitcnt vmcnt(30)
	v_fmac_f32_e32 v144, v16, v175
	v_fmac_f32_e32 v226, v32, v176
	global_store_dword v164, v144, s[48:49]
	global_store_dword v164, v226, s[48:49] offset:128
	s_waitcnt vmcnt(30)
	v_fmac_f32_e32 v145, v17, v175
	v_fmac_f32_e32 v227, v33, v176
	global_store_dword v165, v145, s[48:49]
	global_store_dword v165, v227, s[48:49] offset:128
	s_sub_u32 s48, s48, 0x18000
	s_subb_u32 s49, s49, 0
	v_mul_f32_e32 v130, v130, v130
	v_fmac_f32_e32 v130, v212, v212
	v_mul_f32_e32 v131, v131, v131
	v_fmac_f32_e32 v131, v213, v213
	v_mul_f32_e32 v132, v132, v132
	v_fmac_f32_e32 v132, v214, v214
	v_mul_f32_e32 v133, v133, v133
	v_fmac_f32_e32 v133, v215, v215
	v_mul_f32_e32 v134, v134, v134
	v_fmac_f32_e32 v134, v216, v216
	v_mul_f32_e32 v135, v135, v135
	v_fmac_f32_e32 v135, v217, v217
	v_mul_f32_e32 v136, v136, v136
	v_fmac_f32_e32 v136, v218, v218
	v_mul_f32_e32 v137, v137, v137
	v_fmac_f32_e32 v137, v219, v219
	v_mul_f32_e32 v138, v138, v138
	v_fmac_f32_e32 v138, v220, v220
	v_mul_f32_e32 v139, v139, v139
	v_fmac_f32_e32 v139, v221, v221
	v_mul_f32_e32 v140, v140, v140
	v_fmac_f32_e32 v140, v222, v222
	v_mul_f32_e32 v141, v141, v141
	v_fmac_f32_e32 v141, v223, v223
	v_mul_f32_e32 v142, v142, v142
	v_fmac_f32_e32 v142, v224, v224
	v_mul_f32_e32 v143, v143, v143
	v_fmac_f32_e32 v143, v225, v225
	v_mul_f32_e32 v144, v144, v144
	v_fmac_f32_e32 v144, v226, v226
	v_mul_f32_e32 v145, v145, v145
	v_fmac_f32_e32 v145, v227, v227
	s_waitcnt lgkmcnt(0)
	ds_bpermute_b32 v212, v168, v130
	ds_bpermute_b32 v213, v168, v131
	ds_bpermute_b32 v214, v168, v132
	ds_bpermute_b32 v215, v168, v133
	ds_bpermute_b32 v216, v168, v134
	ds_bpermute_b32 v217, v168, v135
	ds_bpermute_b32 v218, v168, v136
	ds_bpermute_b32 v219, v168, v137
	s_waitcnt lgkmcnt(7)
	v_add_f32_e32 v130, v130, v212
	s_waitcnt lgkmcnt(6)
	v_add_f32_e32 v131, v131, v213
	s_waitcnt lgkmcnt(5)
	v_add_f32_e32 v132, v132, v214
	s_waitcnt lgkmcnt(4)
	v_add_f32_e32 v133, v133, v215
	s_waitcnt lgkmcnt(3)
	v_add_f32_e32 v134, v134, v216
	s_waitcnt lgkmcnt(2)
	v_add_f32_e32 v135, v135, v217
	s_waitcnt lgkmcnt(1)
	v_add_f32_e32 v136, v136, v218
	s_waitcnt lgkmcnt(0)
	v_add_f32_e32 v137, v137, v219
	ds_bpermute_b32 v212, v169, v130
	ds_bpermute_b32 v213, v169, v131
	ds_bpermute_b32 v214, v169, v132
	ds_bpermute_b32 v215, v169, v133
	ds_bpermute_b32 v216, v169, v134
	ds_bpermute_b32 v217, v169, v135
	ds_bpermute_b32 v218, v169, v136
	ds_bpermute_b32 v219, v169, v137
	s_waitcnt lgkmcnt(7)
	v_add_f32_e32 v130, v130, v212
	s_waitcnt lgkmcnt(6)
	v_add_f32_e32 v131, v131, v213
	s_waitcnt lgkmcnt(5)
	v_add_f32_e32 v132, v132, v214
	s_waitcnt lgkmcnt(4)
	v_add_f32_e32 v133, v133, v215
	s_waitcnt lgkmcnt(3)
	v_add_f32_e32 v134, v134, v216
	s_waitcnt lgkmcnt(2)
	v_add_f32_e32 v135, v135, v217
	s_waitcnt lgkmcnt(1)
	v_add_f32_e32 v136, v136, v218
	s_waitcnt lgkmcnt(0)
	v_add_f32_e32 v137, v137, v219
	ds_bpermute_b32 v212, v171, v130
	ds_bpermute_b32 v213, v171, v131
	ds_bpermute_b32 v214, v171, v132
	ds_bpermute_b32 v215, v171, v133
	ds_bpermute_b32 v216, v171, v134
	ds_bpermute_b32 v217, v171, v135
	ds_bpermute_b32 v218, v171, v136
	ds_bpermute_b32 v219, v171, v137
	s_waitcnt lgkmcnt(7)
	v_add_f32_e32 v130, v130, v212
	s_waitcnt lgkmcnt(6)
	v_add_f32_e32 v131, v131, v213
	s_waitcnt lgkmcnt(5)
	v_add_f32_e32 v132, v132, v214
	s_waitcnt lgkmcnt(4)
	v_add_f32_e32 v133, v133, v215
	s_waitcnt lgkmcnt(3)
	v_add_f32_e32 v134, v134, v216
	s_waitcnt lgkmcnt(2)
	v_add_f32_e32 v135, v135, v217
	s_waitcnt lgkmcnt(1)
	v_add_f32_e32 v136, v136, v218
	s_waitcnt lgkmcnt(0)
	v_add_f32_e32 v137, v137, v219
	ds_bpermute_b32 v212, v172, v130
	ds_bpermute_b32 v213, v172, v131
	ds_bpermute_b32 v214, v172, v132
	ds_bpermute_b32 v215, v172, v133
	ds_bpermute_b32 v216, v172, v134
	ds_bpermute_b32 v217, v172, v135
	ds_bpermute_b32 v218, v172, v136
	ds_bpermute_b32 v219, v172, v137
	s_waitcnt lgkmcnt(7)
	v_add_f32_e32 v130, v130, v212
	s_waitcnt lgkmcnt(6)
	v_add_f32_e32 v131, v131, v213
	s_waitcnt lgkmcnt(5)
	v_add_f32_e32 v132, v132, v214
	s_waitcnt lgkmcnt(4)
	v_add_f32_e32 v133, v133, v215
	s_waitcnt lgkmcnt(3)
	v_add_f32_e32 v134, v134, v216
	s_waitcnt lgkmcnt(2)
	v_add_f32_e32 v135, v135, v217
	s_waitcnt lgkmcnt(1)
	v_add_f32_e32 v136, v136, v218
	s_waitcnt lgkmcnt(0)
	v_add_f32_e32 v137, v137, v219
	ds_bpermute_b32 v212, v173, v130
	ds_bpermute_b32 v213, v173, v131
	ds_bpermute_b32 v214, v173, v132
	ds_bpermute_b32 v215, v173, v133
	ds_bpermute_b32 v216, v173, v134
	ds_bpermute_b32 v217, v173, v135
	ds_bpermute_b32 v218, v173, v136
	ds_bpermute_b32 v219, v173, v137
	s_waitcnt lgkmcnt(7)
	v_add_f32_e32 v130, v130, v212
	s_waitcnt lgkmcnt(6)
	v_add_f32_e32 v131, v131, v213
	s_waitcnt lgkmcnt(5)
	v_add_f32_e32 v132, v132, v214
	s_waitcnt lgkmcnt(4)
	v_add_f32_e32 v133, v133, v215
	s_waitcnt lgkmcnt(3)
	v_add_f32_e32 v134, v134, v216
	s_waitcnt lgkmcnt(2)
	v_add_f32_e32 v135, v135, v217
	s_waitcnt lgkmcnt(1)
	v_add_f32_e32 v136, v136, v218
	s_waitcnt lgkmcnt(0)
	v_add_f32_e32 v137, v137, v219
	ds_bpermute_b32 v220, v168, v138
	ds_bpermute_b32 v221, v168, v139
	ds_bpermute_b32 v222, v168, v140
	ds_bpermute_b32 v223, v168, v141
	ds_bpermute_b32 v224, v168, v142
	ds_bpermute_b32 v225, v168, v143
	ds_bpermute_b32 v226, v168, v144
	ds_bpermute_b32 v227, v168, v145
	s_waitcnt lgkmcnt(7)
	v_add_f32_e32 v138, v138, v220
	s_waitcnt lgkmcnt(6)
	v_add_f32_e32 v139, v139, v221
	s_waitcnt lgkmcnt(5)
	v_add_f32_e32 v140, v140, v222
	s_waitcnt lgkmcnt(4)
	v_add_f32_e32 v141, v141, v223
	s_waitcnt lgkmcnt(3)
	v_add_f32_e32 v142, v142, v224
	s_waitcnt lgkmcnt(2)
	v_add_f32_e32 v143, v143, v225
	s_waitcnt lgkmcnt(1)
	v_add_f32_e32 v144, v144, v226
	s_waitcnt lgkmcnt(0)
	v_add_f32_e32 v145, v145, v227
	ds_bpermute_b32 v220, v169, v138
	ds_bpermute_b32 v221, v169, v139
	ds_bpermute_b32 v222, v169, v140
	ds_bpermute_b32 v223, v169, v141
	ds_bpermute_b32 v224, v169, v142
	ds_bpermute_b32 v225, v169, v143
	ds_bpermute_b32 v226, v169, v144
	ds_bpermute_b32 v227, v169, v145
	s_waitcnt lgkmcnt(7)
	v_add_f32_e32 v138, v138, v220
	s_waitcnt lgkmcnt(6)
	v_add_f32_e32 v139, v139, v221
	s_waitcnt lgkmcnt(5)
	v_add_f32_e32 v140, v140, v222
	s_waitcnt lgkmcnt(4)
	v_add_f32_e32 v141, v141, v223
	s_waitcnt lgkmcnt(3)
	v_add_f32_e32 v142, v142, v224
	s_waitcnt lgkmcnt(2)
	v_add_f32_e32 v143, v143, v225
	s_waitcnt lgkmcnt(1)
	v_add_f32_e32 v144, v144, v226
	s_waitcnt lgkmcnt(0)
	v_add_f32_e32 v145, v145, v227
	ds_bpermute_b32 v220, v171, v138
	ds_bpermute_b32 v221, v171, v139
	ds_bpermute_b32 v222, v171, v140
	ds_bpermute_b32 v223, v171, v141
	ds_bpermute_b32 v224, v171, v142
	ds_bpermute_b32 v225, v171, v143
	ds_bpermute_b32 v226, v171, v144
	ds_bpermute_b32 v227, v171, v145
	s_waitcnt lgkmcnt(7)
	v_add_f32_e32 v138, v138, v220
	s_waitcnt lgkmcnt(6)
	v_add_f32_e32 v139, v139, v221
	s_waitcnt lgkmcnt(5)
	v_add_f32_e32 v140, v140, v222
	s_waitcnt lgkmcnt(4)
	v_add_f32_e32 v141, v141, v223
	s_waitcnt lgkmcnt(3)
	v_add_f32_e32 v142, v142, v224
	s_waitcnt lgkmcnt(2)
	v_add_f32_e32 v143, v143, v225
	s_waitcnt lgkmcnt(1)
	v_add_f32_e32 v144, v144, v226
	s_waitcnt lgkmcnt(0)
	v_add_f32_e32 v145, v145, v227
	ds_bpermute_b32 v220, v172, v138
	ds_bpermute_b32 v221, v172, v139
	ds_bpermute_b32 v222, v172, v140
	ds_bpermute_b32 v223, v172, v141
	ds_bpermute_b32 v224, v172, v142
	ds_bpermute_b32 v225, v172, v143
	ds_bpermute_b32 v226, v172, v144
	ds_bpermute_b32 v227, v172, v145
	s_waitcnt lgkmcnt(7)
	v_add_f32_e32 v138, v138, v220
	s_waitcnt lgkmcnt(6)
	v_add_f32_e32 v139, v139, v221
	s_waitcnt lgkmcnt(5)
	v_add_f32_e32 v140, v140, v222
	s_waitcnt lgkmcnt(4)
	v_add_f32_e32 v141, v141, v223
	s_waitcnt lgkmcnt(3)
	v_add_f32_e32 v142, v142, v224
	s_waitcnt lgkmcnt(2)
	v_add_f32_e32 v143, v143, v225
	s_waitcnt lgkmcnt(1)
	v_add_f32_e32 v144, v144, v226
	s_waitcnt lgkmcnt(0)
	v_add_f32_e32 v145, v145, v227
	ds_bpermute_b32 v220, v173, v138
	ds_bpermute_b32 v221, v173, v139
	ds_bpermute_b32 v222, v173, v140
	ds_bpermute_b32 v223, v173, v141
	ds_bpermute_b32 v224, v173, v142
	ds_bpermute_b32 v225, v173, v143
	ds_bpermute_b32 v226, v173, v144
	ds_bpermute_b32 v227, v173, v145
	s_waitcnt lgkmcnt(7)
	v_add_f32_e32 v138, v138, v220
	s_waitcnt lgkmcnt(6)
	v_add_f32_e32 v139, v139, v221
	s_waitcnt lgkmcnt(5)
	v_add_f32_e32 v140, v140, v222
	s_waitcnt lgkmcnt(4)
	v_add_f32_e32 v141, v141, v223
	s_waitcnt lgkmcnt(3)
	v_add_f32_e32 v142, v142, v224
	s_waitcnt lgkmcnt(2)
	v_add_f32_e32 v143, v143, v225
	s_waitcnt lgkmcnt(1)
	v_add_f32_e32 v144, v144, v226
	s_waitcnt lgkmcnt(0)
	v_add_f32_e32 v145, v145, v227
	v_cmp_eq_u32_e32 vcc, 0, v174
	s_and_saveexec_b64 s[58:59], vcc
	global_store_dword v167, v130, s[10:11]
	global_store_dword v167, v131, s[10:11] offset:4
	global_store_dword v167, v132, s[10:11] offset:8
	global_store_dword v167, v133, s[10:11] offset:12
	global_store_dword v167, v134, s[10:11] offset:32
	global_store_dword v167, v135, s[10:11] offset:36
	global_store_dword v167, v136, s[10:11] offset:40
	global_store_dword v167, v137, s[10:11] offset:44
	global_store_dword v167, v138, s[10:11] offset:64
	global_store_dword v167, v139, s[10:11] offset:68
	global_store_dword v167, v140, s[10:11] offset:72
	global_store_dword v167, v141, s[10:11] offset:76
	global_store_dword v167, v142, s[10:11] offset:96
	global_store_dword v167, v143, s[10:11] offset:100
	global_store_dword v167, v144, s[10:11] offset:104
	global_store_dword v167, v145, s[10:11] offset:108
	s_mov_b64 exec, -1
	s_add_u32 s48, s48, 0x20000
	s_addc_u32 s49, s49, 0
	global_load_dword v130, v162, s[48:49]
	global_load_dword v212, v162, s[48:49] offset:128
	global_load_dword v131, v163, s[48:49]
	global_load_dword v213, v163, s[48:49] offset:128
	global_load_dword v132, v164, s[48:49]
	global_load_dword v214, v164, s[48:49] offset:128
	global_load_dword v133, v165, s[48:49]
	global_load_dword v215, v165, s[48:49] offset:128
	s_add_u32 s48, s48, 0x8000
	s_addc_u32 s49, s49, 0
	global_load_dword v134, v162, s[48:49]
	global_load_dword v216, v162, s[48:49] offset:128
	global_load_dword v135, v163, s[48:49]
	global_load_dword v217, v163, s[48:49] offset:128
	global_load_dword v136, v164, s[48:49]
	global_load_dword v218, v164, s[48:49] offset:128
	global_load_dword v137, v165, s[48:49]
	global_load_dword v219, v165, s[48:49] offset:128
	s_add_u32 s48, s48, 0x8000
	s_addc_u32 s49, s49, 0
	global_load_dword v138, v162, s[48:49]
	global_load_dword v220, v162, s[48:49] offset:128
	global_load_dword v139, v163, s[48:49]
	global_load_dword v221, v163, s[48:49] offset:128
	global_load_dword v140, v164, s[48:49]
	global_load_dword v222, v164, s[48:49] offset:128
	global_load_dword v141, v165, s[48:49]
	global_load_dword v223, v165, s[48:49] offset:128
	s_add_u32 s48, s48, 0x8000
	s_addc_u32 s49, s49, 0
	global_load_dword v142, v162, s[48:49]
	global_load_dword v224, v162, s[48:49] offset:128
	global_load_dword v143, v163, s[48:49]
	global_load_dword v225, v163, s[48:49] offset:128
	global_load_dword v144, v164, s[48:49]
	global_load_dword v226, v164, s[48:49] offset:128
	global_load_dword v145, v165, s[48:49]
	global_load_dword v227, v165, s[48:49] offset:128
	s_sub_u32 s48, s48, 0x18000
	s_subb_u32 s49, s49, 0
	s_waitcnt vmcnt(30)
	v_fmac_f32_e32 v130, v34, v175
	v_fmac_f32_e32 v212, v50, v176
	global_store_dword v162, v130, s[48:49]
	global_store_dword v162, v212, s[48:49] offset:128
	s_waitcnt vmcnt(30)
	v_fmac_f32_e32 v131, v35, v175
	v_fmac_f32_e32 v213, v51, v176
	global_store_dword v163, v131, s[48:49]
	global_store_dword v163, v213, s[48:49] offset:128
	s_waitcnt vmcnt(30)
	v_fmac_f32_e32 v132, v36, v175
	v_fmac_f32_e32 v214, v52, v176
	global_store_dword v164, v132, s[48:49]
	global_store_dword v164, v214, s[48:49] offset:128
	s_waitcnt vmcnt(30)
	v_fmac_f32_e32 v133, v37, v175
	v_fmac_f32_e32 v215, v53, v176
	global_store_dword v165, v133, s[48:49]
	global_store_dword v165, v215, s[48:49] offset:128
	s_add_u32 s48, s48, 0x8000
	s_addc_u32 s49, s49, 0
	s_waitcnt vmcnt(30)
	v_fmac_f32_e32 v134, v38, v175
	v_fmac_f32_e32 v216, v54, v176
	global_store_dword v162, v134, s[48:49]
	global_store_dword v162, v216, s[48:49] offset:128
	s_waitcnt vmcnt(30)
	v_fmac_f32_e32 v135, v39, v175
	v_fmac_f32_e32 v217, v55, v176
	global_store_dword v163, v135, s[48:49]
	global_store_dword v163, v217, s[48:49] offset:128
	s_waitcnt vmcnt(30)
	v_fmac_f32_e32 v136, v40, v175
	v_fmac_f32_e32 v218, v56, v176
	global_store_dword v164, v136, s[48:49]
	global_store_dword v164, v218, s[48:49] offset:128
	s_waitcnt vmcnt(30)
	v_fmac_f32_e32 v137, v41, v175
	v_fmac_f32_e32 v219, v57, v176
	global_store_dword v165, v137, s[48:49]
	global_store_dword v165, v219, s[48:49] offset:128
	s_add_u32 s48, s48, 0x8000
	s_addc_u32 s49, s49, 0
	s_waitcnt vmcnt(30)
	v_fmac_f32_e32 v138, v42, v175
	v_fmac_f32_e32 v220, v58, v176
	global_store_dword v162, v138, s[48:49]
	global_store_dword v162, v220, s[48:49] offset:128
	s_waitcnt vmcnt(30)
	v_fmac_f32_e32 v139, v43, v175
	v_fmac_f32_e32 v221, v59, v176
	global_store_dword v163, v139, s[48:49]
	global_store_dword v163, v221, s[48:49] offset:128
	s_waitcnt vmcnt(30)
	v_fmac_f32_e32 v140, v44, v175
	v_fmac_f32_e32 v222, v60, v176
	global_store_dword v164, v140, s[48:49]
	global_store_dword v164, v222, s[48:49] offset:128
	s_waitcnt vmcnt(30)
	v_fmac_f32_e32 v141, v45, v175
	v_fmac_f32_e32 v223, v61, v176
	global_store_dword v165, v141, s[48:49]
	global_store_dword v165, v223, s[48:49] offset:128
	s_add_u32 s48, s48, 0x8000
	s_addc_u32 s49, s49, 0
	s_waitcnt vmcnt(30)
	v_fmac_f32_e32 v142, v46, v175
	v_fmac_f32_e32 v224, v62, v176
	global_store_dword v162, v142, s[48:49]
	global_store_dword v162, v224, s[48:49] offset:128
	s_waitcnt vmcnt(30)
	v_fmac_f32_e32 v143, v47, v175
	v_fmac_f32_e32 v225, v63, v176
	global_store_dword v163, v143, s[48:49]
	global_store_dword v163, v225, s[48:49] offset:128
	s_waitcnt vmcnt(30)
	v_fmac_f32_e32 v144, v48, v175
	v_fmac_f32_e32 v226, v64, v176
	global_store_dword v164, v144, s[48:49]
	global_store_dword v164, v226, s[48:49] offset:128
	s_waitcnt vmcnt(30)
	v_fmac_f32_e32 v145, v49, v175
	v_fmac_f32_e32 v227, v65, v176
	global_store_dword v165, v145, s[48:49]
	global_store_dword v165, v227, s[48:49] offset:128
	s_sub_u32 s48, s48, 0x18000
	s_subb_u32 s49, s49, 0
	v_mul_f32_e32 v130, v130, v130
	v_fmac_f32_e32 v130, v212, v212
	v_mul_f32_e32 v131, v131, v131
	v_fmac_f32_e32 v131, v213, v213
	v_mul_f32_e32 v132, v132, v132
	v_fmac_f32_e32 v132, v214, v214
	v_mul_f32_e32 v133, v133, v133
	v_fmac_f32_e32 v133, v215, v215
	v_mul_f32_e32 v134, v134, v134
	v_fmac_f32_e32 v134, v216, v216
	v_mul_f32_e32 v135, v135, v135
	v_fmac_f32_e32 v135, v217, v217
	v_mul_f32_e32 v136, v136, v136
	v_fmac_f32_e32 v136, v218, v218
	v_mul_f32_e32 v137, v137, v137
	v_fmac_f32_e32 v137, v219, v219
	v_mul_f32_e32 v138, v138, v138
	v_fmac_f32_e32 v138, v220, v220
	v_mul_f32_e32 v139, v139, v139
	v_fmac_f32_e32 v139, v221, v221
	v_mul_f32_e32 v140, v140, v140
	v_fmac_f32_e32 v140, v222, v222
	v_mul_f32_e32 v141, v141, v141
	v_fmac_f32_e32 v141, v223, v223
	v_mul_f32_e32 v142, v142, v142
	v_fmac_f32_e32 v142, v224, v224
	v_mul_f32_e32 v143, v143, v143
	v_fmac_f32_e32 v143, v225, v225
	v_mul_f32_e32 v144, v144, v144
	v_fmac_f32_e32 v144, v226, v226
	v_mul_f32_e32 v145, v145, v145
	v_fmac_f32_e32 v145, v227, v227
	s_waitcnt lgkmcnt(0)
	ds_bpermute_b32 v212, v168, v130
	ds_bpermute_b32 v213, v168, v131
	ds_bpermute_b32 v214, v168, v132
	ds_bpermute_b32 v215, v168, v133
	ds_bpermute_b32 v216, v168, v134
	ds_bpermute_b32 v217, v168, v135
	ds_bpermute_b32 v218, v168, v136
	ds_bpermute_b32 v219, v168, v137
	s_waitcnt lgkmcnt(7)
	v_add_f32_e32 v130, v130, v212
	s_waitcnt lgkmcnt(6)
	v_add_f32_e32 v131, v131, v213
	s_waitcnt lgkmcnt(5)
	v_add_f32_e32 v132, v132, v214
	s_waitcnt lgkmcnt(4)
	v_add_f32_e32 v133, v133, v215
	s_waitcnt lgkmcnt(3)
	v_add_f32_e32 v134, v134, v216
	s_waitcnt lgkmcnt(2)
	v_add_f32_e32 v135, v135, v217
	s_waitcnt lgkmcnt(1)
	v_add_f32_e32 v136, v136, v218
	s_waitcnt lgkmcnt(0)
	v_add_f32_e32 v137, v137, v219
	ds_bpermute_b32 v212, v169, v130
	ds_bpermute_b32 v213, v169, v131
	ds_bpermute_b32 v214, v169, v132
	ds_bpermute_b32 v215, v169, v133
	ds_bpermute_b32 v216, v169, v134
	ds_bpermute_b32 v217, v169, v135
	ds_bpermute_b32 v218, v169, v136
	ds_bpermute_b32 v219, v169, v137
	s_waitcnt lgkmcnt(7)
	v_add_f32_e32 v130, v130, v212
	s_waitcnt lgkmcnt(6)
	v_add_f32_e32 v131, v131, v213
	s_waitcnt lgkmcnt(5)
	v_add_f32_e32 v132, v132, v214
	s_waitcnt lgkmcnt(4)
	v_add_f32_e32 v133, v133, v215
	s_waitcnt lgkmcnt(3)
	v_add_f32_e32 v134, v134, v216
	s_waitcnt lgkmcnt(2)
	v_add_f32_e32 v135, v135, v217
	s_waitcnt lgkmcnt(1)
	v_add_f32_e32 v136, v136, v218
	s_waitcnt lgkmcnt(0)
	v_add_f32_e32 v137, v137, v219
	ds_bpermute_b32 v212, v171, v130
	ds_bpermute_b32 v213, v171, v131
	ds_bpermute_b32 v214, v171, v132
	ds_bpermute_b32 v215, v171, v133
	ds_bpermute_b32 v216, v171, v134
	ds_bpermute_b32 v217, v171, v135
	ds_bpermute_b32 v218, v171, v136
	ds_bpermute_b32 v219, v171, v137
	s_waitcnt lgkmcnt(7)
	v_add_f32_e32 v130, v130, v212
	s_waitcnt lgkmcnt(6)
	v_add_f32_e32 v131, v131, v213
	s_waitcnt lgkmcnt(5)
	v_add_f32_e32 v132, v132, v214
	s_waitcnt lgkmcnt(4)
	v_add_f32_e32 v133, v133, v215
	s_waitcnt lgkmcnt(3)
	v_add_f32_e32 v134, v134, v216
	s_waitcnt lgkmcnt(2)
	v_add_f32_e32 v135, v135, v217
	s_waitcnt lgkmcnt(1)
	v_add_f32_e32 v136, v136, v218
	s_waitcnt lgkmcnt(0)
	v_add_f32_e32 v137, v137, v219
	ds_bpermute_b32 v212, v172, v130
	ds_bpermute_b32 v213, v172, v131
	ds_bpermute_b32 v214, v172, v132
	ds_bpermute_b32 v215, v172, v133
	ds_bpermute_b32 v216, v172, v134
	ds_bpermute_b32 v217, v172, v135
	ds_bpermute_b32 v218, v172, v136
	ds_bpermute_b32 v219, v172, v137
	s_waitcnt lgkmcnt(7)
	v_add_f32_e32 v130, v130, v212
	s_waitcnt lgkmcnt(6)
	v_add_f32_e32 v131, v131, v213
	s_waitcnt lgkmcnt(5)
	v_add_f32_e32 v132, v132, v214
	s_waitcnt lgkmcnt(4)
	v_add_f32_e32 v133, v133, v215
	s_waitcnt lgkmcnt(3)
	v_add_f32_e32 v134, v134, v216
	s_waitcnt lgkmcnt(2)
	v_add_f32_e32 v135, v135, v217
	s_waitcnt lgkmcnt(1)
	v_add_f32_e32 v136, v136, v218
	s_waitcnt lgkmcnt(0)
	v_add_f32_e32 v137, v137, v219
	ds_bpermute_b32 v212, v173, v130
	ds_bpermute_b32 v213, v173, v131
	ds_bpermute_b32 v214, v173, v132
	ds_bpermute_b32 v215, v173, v133
	ds_bpermute_b32 v216, v173, v134
	ds_bpermute_b32 v217, v173, v135
	ds_bpermute_b32 v218, v173, v136
	ds_bpermute_b32 v219, v173, v137
	s_waitcnt lgkmcnt(7)
	v_add_f32_e32 v130, v130, v212
	s_waitcnt lgkmcnt(6)
	v_add_f32_e32 v131, v131, v213
	s_waitcnt lgkmcnt(5)
	v_add_f32_e32 v132, v132, v214
	s_waitcnt lgkmcnt(4)
	v_add_f32_e32 v133, v133, v215
	s_waitcnt lgkmcnt(3)
	v_add_f32_e32 v134, v134, v216
	s_waitcnt lgkmcnt(2)
	v_add_f32_e32 v135, v135, v217
	s_waitcnt lgkmcnt(1)
	v_add_f32_e32 v136, v136, v218
	s_waitcnt lgkmcnt(0)
	v_add_f32_e32 v137, v137, v219
	ds_bpermute_b32 v220, v168, v138
	ds_bpermute_b32 v221, v168, v139
	ds_bpermute_b32 v222, v168, v140
	ds_bpermute_b32 v223, v168, v141
	ds_bpermute_b32 v224, v168, v142
	ds_bpermute_b32 v225, v168, v143
	ds_bpermute_b32 v226, v168, v144
	ds_bpermute_b32 v227, v168, v145
	s_waitcnt lgkmcnt(7)
	v_add_f32_e32 v138, v138, v220
	s_waitcnt lgkmcnt(6)
	v_add_f32_e32 v139, v139, v221
	s_waitcnt lgkmcnt(5)
	v_add_f32_e32 v140, v140, v222
	s_waitcnt lgkmcnt(4)
	v_add_f32_e32 v141, v141, v223
	s_waitcnt lgkmcnt(3)
	v_add_f32_e32 v142, v142, v224
	s_waitcnt lgkmcnt(2)
	v_add_f32_e32 v143, v143, v225
	s_waitcnt lgkmcnt(1)
	v_add_f32_e32 v144, v144, v226
	s_waitcnt lgkmcnt(0)
	v_add_f32_e32 v145, v145, v227
	ds_bpermute_b32 v220, v169, v138
	ds_bpermute_b32 v221, v169, v139
	ds_bpermute_b32 v222, v169, v140
	ds_bpermute_b32 v223, v169, v141
	ds_bpermute_b32 v224, v169, v142
	ds_bpermute_b32 v225, v169, v143
	ds_bpermute_b32 v226, v169, v144
	ds_bpermute_b32 v227, v169, v145
	s_waitcnt lgkmcnt(7)
	v_add_f32_e32 v138, v138, v220
	s_waitcnt lgkmcnt(6)
	v_add_f32_e32 v139, v139, v221
	s_waitcnt lgkmcnt(5)
	v_add_f32_e32 v140, v140, v222
	s_waitcnt lgkmcnt(4)
	v_add_f32_e32 v141, v141, v223
	s_waitcnt lgkmcnt(3)
	v_add_f32_e32 v142, v142, v224
	s_waitcnt lgkmcnt(2)
	v_add_f32_e32 v143, v143, v225
	s_waitcnt lgkmcnt(1)
	v_add_f32_e32 v144, v144, v226
	s_waitcnt lgkmcnt(0)
	v_add_f32_e32 v145, v145, v227
	ds_bpermute_b32 v220, v171, v138
	ds_bpermute_b32 v221, v171, v139
	ds_bpermute_b32 v222, v171, v140
	ds_bpermute_b32 v223, v171, v141
	ds_bpermute_b32 v224, v171, v142
	ds_bpermute_b32 v225, v171, v143
	ds_bpermute_b32 v226, v171, v144
	ds_bpermute_b32 v227, v171, v145
	s_waitcnt lgkmcnt(7)
	v_add_f32_e32 v138, v138, v220
	s_waitcnt lgkmcnt(6)
	v_add_f32_e32 v139, v139, v221
	s_waitcnt lgkmcnt(5)
	v_add_f32_e32 v140, v140, v222
	s_waitcnt lgkmcnt(4)
	v_add_f32_e32 v141, v141, v223
	s_waitcnt lgkmcnt(3)
	v_add_f32_e32 v142, v142, v224
	s_waitcnt lgkmcnt(2)
	v_add_f32_e32 v143, v143, v225
	s_waitcnt lgkmcnt(1)
	v_add_f32_e32 v144, v144, v226
	s_waitcnt lgkmcnt(0)
	v_add_f32_e32 v145, v145, v227
	ds_bpermute_b32 v220, v172, v138
	ds_bpermute_b32 v221, v172, v139
	ds_bpermute_b32 v222, v172, v140
	ds_bpermute_b32 v223, v172, v141
	ds_bpermute_b32 v224, v172, v142
	ds_bpermute_b32 v225, v172, v143
	ds_bpermute_b32 v226, v172, v144
	ds_bpermute_b32 v227, v172, v145
	s_waitcnt lgkmcnt(7)
	v_add_f32_e32 v138, v138, v220
	s_waitcnt lgkmcnt(6)
	v_add_f32_e32 v139, v139, v221
	s_waitcnt lgkmcnt(5)
	v_add_f32_e32 v140, v140, v222
	s_waitcnt lgkmcnt(4)
	v_add_f32_e32 v141, v141, v223
	s_waitcnt lgkmcnt(3)
	v_add_f32_e32 v142, v142, v224
	s_waitcnt lgkmcnt(2)
	v_add_f32_e32 v143, v143, v225
	s_waitcnt lgkmcnt(1)
	v_add_f32_e32 v144, v144, v226
	s_waitcnt lgkmcnt(0)
	v_add_f32_e32 v145, v145, v227
	ds_bpermute_b32 v220, v173, v138
	ds_bpermute_b32 v221, v173, v139
	ds_bpermute_b32 v222, v173, v140
	ds_bpermute_b32 v223, v173, v141
	ds_bpermute_b32 v224, v173, v142
	ds_bpermute_b32 v225, v173, v143
	ds_bpermute_b32 v226, v173, v144
	ds_bpermute_b32 v227, v173, v145
	s_waitcnt lgkmcnt(7)
	v_add_f32_e32 v138, v138, v220
	s_waitcnt lgkmcnt(6)
	v_add_f32_e32 v139, v139, v221
	s_waitcnt lgkmcnt(5)
	v_add_f32_e32 v140, v140, v222
	s_waitcnt lgkmcnt(4)
	v_add_f32_e32 v141, v141, v223
	s_waitcnt lgkmcnt(3)
	v_add_f32_e32 v142, v142, v224
	s_waitcnt lgkmcnt(2)
	v_add_f32_e32 v143, v143, v225
	s_waitcnt lgkmcnt(1)
	v_add_f32_e32 v144, v144, v226
	s_waitcnt lgkmcnt(0)
	v_add_f32_e32 v145, v145, v227
	v_cmp_eq_u32_e32 vcc, 0, v174
	s_and_saveexec_b64 s[58:59], vcc
	global_store_dword v167, v130, s[10:11] offset:128
	global_store_dword v167, v131, s[10:11] offset:132
	global_store_dword v167, v132, s[10:11] offset:136
	global_store_dword v167, v133, s[10:11] offset:140
	global_store_dword v167, v134, s[10:11] offset:160
	global_store_dword v167, v135, s[10:11] offset:164
	global_store_dword v167, v136, s[10:11] offset:168
	global_store_dword v167, v137, s[10:11] offset:172
	global_store_dword v167, v138, s[10:11] offset:192
	global_store_dword v167, v139, s[10:11] offset:196
	global_store_dword v167, v140, s[10:11] offset:200
	global_store_dword v167, v141, s[10:11] offset:204
	global_store_dword v167, v142, s[10:11] offset:224
	global_store_dword v167, v143, s[10:11] offset:228
	global_store_dword v167, v144, s[10:11] offset:232
	global_store_dword v167, v145, s[10:11] offset:236
	s_mov_b64 exec, -1
	s_sub_u32 s48, s48, 0x20000
	s_subb_u32 s49, s49, 0
	s_add_u32 s60, s60, 0x200
	s_addc_u32 s61, s61, 0
	s_add_u32 s10, s10, 0x18000
	s_addc_u32 s11, s11, 0
	s_add_u32 s48, s48, 0x200
	s_addc_u32 s49, s49, 0
	global_load_dword v175, v166, s[60:61]
	global_load_dword v176, v166, s[60:61] offset:128
	global_load_dword v130, v162, s[48:49]
	global_load_dword v212, v162, s[48:49] offset:128
	global_load_dword v131, v163, s[48:49]
	global_load_dword v213, v163, s[48:49] offset:128
	global_load_dword v132, v164, s[48:49]
	global_load_dword v214, v164, s[48:49] offset:128
	global_load_dword v133, v165, s[48:49]
	global_load_dword v215, v165, s[48:49] offset:128
	s_add_u32 s48, s48, 0x8000
	s_addc_u32 s49, s49, 0
	global_load_dword v134, v162, s[48:49]
	global_load_dword v216, v162, s[48:49] offset:128
	global_load_dword v135, v163, s[48:49]
	global_load_dword v217, v163, s[48:49] offset:128
	global_load_dword v136, v164, s[48:49]
	global_load_dword v218, v164, s[48:49] offset:128
	global_load_dword v137, v165, s[48:49]
	global_load_dword v219, v165, s[48:49] offset:128
	s_add_u32 s48, s48, 0x8000
	s_addc_u32 s49, s49, 0
	global_load_dword v138, v162, s[48:49]
	global_load_dword v220, v162, s[48:49] offset:128
	global_load_dword v139, v163, s[48:49]
	global_load_dword v221, v163, s[48:49] offset:128
	global_load_dword v140, v164, s[48:49]
	global_load_dword v222, v164, s[48:49] offset:128
	global_load_dword v141, v165, s[48:49]
	global_load_dword v223, v165, s[48:49] offset:128
	s_add_u32 s48, s48, 0x8000
	s_addc_u32 s49, s49, 0
	global_load_dword v142, v162, s[48:49]
	global_load_dword v224, v162, s[48:49] offset:128
	global_load_dword v143, v163, s[48:49]
	global_load_dword v225, v163, s[48:49] offset:128
	global_load_dword v144, v164, s[48:49]
	global_load_dword v226, v164, s[48:49] offset:128
	global_load_dword v145, v165, s[48:49]
	global_load_dword v227, v165, s[48:49] offset:128
	s_sub_u32 s48, s48, 0x18000
	s_subb_u32 s49, s49, 0
	s_waitcnt vmcnt(32)
	v_mul_f32_e32 v175, 0.5, v175
	v_mul_f32_e32 v176, 0.5, v176
	s_waitcnt vmcnt(30)
	v_fmac_f32_e32 v130, v66, v175
	v_fmac_f32_e32 v212, v82, v176
	global_store_dword v162, v130, s[48:49]
	global_store_dword v162, v212, s[48:49] offset:128
	s_waitcnt vmcnt(30)
	v_fmac_f32_e32 v131, v67, v175
	v_fmac_f32_e32 v213, v83, v176
	global_store_dword v163, v131, s[48:49]
	global_store_dword v163, v213, s[48:49] offset:128
	s_waitcnt vmcnt(30)
	v_fmac_f32_e32 v132, v68, v175
	v_fmac_f32_e32 v214, v84, v176
	global_store_dword v164, v132, s[48:49]
	global_store_dword v164, v214, s[48:49] offset:128
	s_waitcnt vmcnt(30)
	v_fmac_f32_e32 v133, v69, v175
	v_fmac_f32_e32 v215, v85, v176
	global_store_dword v165, v133, s[48:49]
	global_store_dword v165, v215, s[48:49] offset:128
	s_add_u32 s48, s48, 0x8000
	s_addc_u32 s49, s49, 0
	s_waitcnt vmcnt(30)
	v_fmac_f32_e32 v134, v70, v175
	v_fmac_f32_e32 v216, v86, v176
	global_store_dword v162, v134, s[48:49]
	global_store_dword v162, v216, s[48:49] offset:128
	s_waitcnt vmcnt(30)
	v_fmac_f32_e32 v135, v71, v175
	v_fmac_f32_e32 v217, v87, v176
	global_store_dword v163, v135, s[48:49]
	global_store_dword v163, v217, s[48:49] offset:128
	s_waitcnt vmcnt(30)
	v_fmac_f32_e32 v136, v72, v175
	v_fmac_f32_e32 v218, v88, v176
	global_store_dword v164, v136, s[48:49]
	global_store_dword v164, v218, s[48:49] offset:128
	s_waitcnt vmcnt(30)
	v_fmac_f32_e32 v137, v73, v175
	v_fmac_f32_e32 v219, v89, v176
	global_store_dword v165, v137, s[48:49]
	global_store_dword v165, v219, s[48:49] offset:128
	s_add_u32 s48, s48, 0x8000
	s_addc_u32 s49, s49, 0
	s_waitcnt vmcnt(30)
	v_fmac_f32_e32 v138, v74, v175
	v_fmac_f32_e32 v220, v90, v176
	global_store_dword v162, v138, s[48:49]
	global_store_dword v162, v220, s[48:49] offset:128
	s_waitcnt vmcnt(30)
	v_fmac_f32_e32 v139, v75, v175
	v_fmac_f32_e32 v221, v91, v176
	global_store_dword v163, v139, s[48:49]
	global_store_dword v163, v221, s[48:49] offset:128
	s_waitcnt vmcnt(30)
	v_fmac_f32_e32 v140, v76, v175
	v_fmac_f32_e32 v222, v92, v176
	global_store_dword v164, v140, s[48:49]
	global_store_dword v164, v222, s[48:49] offset:128
	s_waitcnt vmcnt(30)
	v_fmac_f32_e32 v141, v77, v175
	v_fmac_f32_e32 v223, v93, v176
	global_store_dword v165, v141, s[48:49]
	global_store_dword v165, v223, s[48:49] offset:128
	s_add_u32 s48, s48, 0x8000
	s_addc_u32 s49, s49, 0
	s_waitcnt vmcnt(30)
	v_fmac_f32_e32 v142, v78, v175
	v_fmac_f32_e32 v224, v94, v176
	global_store_dword v162, v142, s[48:49]
	global_store_dword v162, v224, s[48:49] offset:128
	s_waitcnt vmcnt(30)
	v_fmac_f32_e32 v143, v79, v175
	v_fmac_f32_e32 v225, v95, v176
	global_store_dword v163, v143, s[48:49]
	global_store_dword v163, v225, s[48:49] offset:128
	s_waitcnt vmcnt(30)
	v_fmac_f32_e32 v144, v80, v175
	v_fmac_f32_e32 v226, v96, v176
	global_store_dword v164, v144, s[48:49]
	global_store_dword v164, v226, s[48:49] offset:128
	s_waitcnt vmcnt(30)
	v_fmac_f32_e32 v145, v81, v175
	v_fmac_f32_e32 v227, v97, v176
	global_store_dword v165, v145, s[48:49]
	global_store_dword v165, v227, s[48:49] offset:128
	s_sub_u32 s48, s48, 0x18000
	s_subb_u32 s49, s49, 0
	v_mul_f32_e32 v130, v130, v130
	v_fmac_f32_e32 v130, v212, v212
	v_mul_f32_e32 v131, v131, v131
	v_fmac_f32_e32 v131, v213, v213
	v_mul_f32_e32 v132, v132, v132
	v_fmac_f32_e32 v132, v214, v214
	v_mul_f32_e32 v133, v133, v133
	v_fmac_f32_e32 v133, v215, v215
	v_mul_f32_e32 v134, v134, v134
	v_fmac_f32_e32 v134, v216, v216
	v_mul_f32_e32 v135, v135, v135
	v_fmac_f32_e32 v135, v217, v217
	v_mul_f32_e32 v136, v136, v136
	v_fmac_f32_e32 v136, v218, v218
	v_mul_f32_e32 v137, v137, v137
	v_fmac_f32_e32 v137, v219, v219
	v_mul_f32_e32 v138, v138, v138
	v_fmac_f32_e32 v138, v220, v220
	v_mul_f32_e32 v139, v139, v139
	v_fmac_f32_e32 v139, v221, v221
	v_mul_f32_e32 v140, v140, v140
	v_fmac_f32_e32 v140, v222, v222
	v_mul_f32_e32 v141, v141, v141
	v_fmac_f32_e32 v141, v223, v223
	v_mul_f32_e32 v142, v142, v142
	v_fmac_f32_e32 v142, v224, v224
	v_mul_f32_e32 v143, v143, v143
	v_fmac_f32_e32 v143, v225, v225
	v_mul_f32_e32 v144, v144, v144
	v_fmac_f32_e32 v144, v226, v226
	v_mul_f32_e32 v145, v145, v145
	v_fmac_f32_e32 v145, v227, v227
	s_waitcnt lgkmcnt(0)
	ds_bpermute_b32 v212, v168, v130
	ds_bpermute_b32 v213, v168, v131
	ds_bpermute_b32 v214, v168, v132
	ds_bpermute_b32 v215, v168, v133
	ds_bpermute_b32 v216, v168, v134
	ds_bpermute_b32 v217, v168, v135
	ds_bpermute_b32 v218, v168, v136
	ds_bpermute_b32 v219, v168, v137
	s_waitcnt lgkmcnt(7)
	v_add_f32_e32 v130, v130, v212
	s_waitcnt lgkmcnt(6)
	v_add_f32_e32 v131, v131, v213
	s_waitcnt lgkmcnt(5)
	v_add_f32_e32 v132, v132, v214
	s_waitcnt lgkmcnt(4)
	v_add_f32_e32 v133, v133, v215
	s_waitcnt lgkmcnt(3)
	v_add_f32_e32 v134, v134, v216
	s_waitcnt lgkmcnt(2)
	v_add_f32_e32 v135, v135, v217
	s_waitcnt lgkmcnt(1)
	v_add_f32_e32 v136, v136, v218
	s_waitcnt lgkmcnt(0)
	v_add_f32_e32 v137, v137, v219
	ds_bpermute_b32 v212, v169, v130
	ds_bpermute_b32 v213, v169, v131
	ds_bpermute_b32 v214, v169, v132
	ds_bpermute_b32 v215, v169, v133
	ds_bpermute_b32 v216, v169, v134
	ds_bpermute_b32 v217, v169, v135
	ds_bpermute_b32 v218, v169, v136
	ds_bpermute_b32 v219, v169, v137
	s_waitcnt lgkmcnt(7)
	v_add_f32_e32 v130, v130, v212
	s_waitcnt lgkmcnt(6)
	v_add_f32_e32 v131, v131, v213
	s_waitcnt lgkmcnt(5)
	v_add_f32_e32 v132, v132, v214
	s_waitcnt lgkmcnt(4)
	v_add_f32_e32 v133, v133, v215
	s_waitcnt lgkmcnt(3)
	v_add_f32_e32 v134, v134, v216
	s_waitcnt lgkmcnt(2)
	v_add_f32_e32 v135, v135, v217
	s_waitcnt lgkmcnt(1)
	v_add_f32_e32 v136, v136, v218
	s_waitcnt lgkmcnt(0)
	v_add_f32_e32 v137, v137, v219
	ds_bpermute_b32 v212, v171, v130
	ds_bpermute_b32 v213, v171, v131
	ds_bpermute_b32 v214, v171, v132
	ds_bpermute_b32 v215, v171, v133
	ds_bpermute_b32 v216, v171, v134
	ds_bpermute_b32 v217, v171, v135
	ds_bpermute_b32 v218, v171, v136
	ds_bpermute_b32 v219, v171, v137
	s_waitcnt lgkmcnt(7)
	v_add_f32_e32 v130, v130, v212
	s_waitcnt lgkmcnt(6)
	v_add_f32_e32 v131, v131, v213
	s_waitcnt lgkmcnt(5)
	v_add_f32_e32 v132, v132, v214
	s_waitcnt lgkmcnt(4)
	v_add_f32_e32 v133, v133, v215
	s_waitcnt lgkmcnt(3)
	v_add_f32_e32 v134, v134, v216
	s_waitcnt lgkmcnt(2)
	v_add_f32_e32 v135, v135, v217
	s_waitcnt lgkmcnt(1)
	v_add_f32_e32 v136, v136, v218
	s_waitcnt lgkmcnt(0)
	v_add_f32_e32 v137, v137, v219
	ds_bpermute_b32 v212, v172, v130
	ds_bpermute_b32 v213, v172, v131
	ds_bpermute_b32 v214, v172, v132
	ds_bpermute_b32 v215, v172, v133
	ds_bpermute_b32 v216, v172, v134
	ds_bpermute_b32 v217, v172, v135
	ds_bpermute_b32 v218, v172, v136
	ds_bpermute_b32 v219, v172, v137
	s_waitcnt lgkmcnt(7)
	v_add_f32_e32 v130, v130, v212
	s_waitcnt lgkmcnt(6)
	v_add_f32_e32 v131, v131, v213
	s_waitcnt lgkmcnt(5)
	v_add_f32_e32 v132, v132, v214
	s_waitcnt lgkmcnt(4)
	v_add_f32_e32 v133, v133, v215
	s_waitcnt lgkmcnt(3)
	v_add_f32_e32 v134, v134, v216
	s_waitcnt lgkmcnt(2)
	v_add_f32_e32 v135, v135, v217
	s_waitcnt lgkmcnt(1)
	v_add_f32_e32 v136, v136, v218
	s_waitcnt lgkmcnt(0)
	v_add_f32_e32 v137, v137, v219
	ds_bpermute_b32 v212, v173, v130
	ds_bpermute_b32 v213, v173, v131
	ds_bpermute_b32 v214, v173, v132
	ds_bpermute_b32 v215, v173, v133
	ds_bpermute_b32 v216, v173, v134
	ds_bpermute_b32 v217, v173, v135
	ds_bpermute_b32 v218, v173, v136
	ds_bpermute_b32 v219, v173, v137
	s_waitcnt lgkmcnt(7)
	v_add_f32_e32 v130, v130, v212
	s_waitcnt lgkmcnt(6)
	v_add_f32_e32 v131, v131, v213
	s_waitcnt lgkmcnt(5)
	v_add_f32_e32 v132, v132, v214
	s_waitcnt lgkmcnt(4)
	v_add_f32_e32 v133, v133, v215
	s_waitcnt lgkmcnt(3)
	v_add_f32_e32 v134, v134, v216
	s_waitcnt lgkmcnt(2)
	v_add_f32_e32 v135, v135, v217
	s_waitcnt lgkmcnt(1)
	v_add_f32_e32 v136, v136, v218
	s_waitcnt lgkmcnt(0)
	v_add_f32_e32 v137, v137, v219
	ds_bpermute_b32 v220, v168, v138
	ds_bpermute_b32 v221, v168, v139
	ds_bpermute_b32 v222, v168, v140
	ds_bpermute_b32 v223, v168, v141
	ds_bpermute_b32 v224, v168, v142
	ds_bpermute_b32 v225, v168, v143
	ds_bpermute_b32 v226, v168, v144
	ds_bpermute_b32 v227, v168, v145
	s_waitcnt lgkmcnt(7)
	v_add_f32_e32 v138, v138, v220
	s_waitcnt lgkmcnt(6)
	v_add_f32_e32 v139, v139, v221
	s_waitcnt lgkmcnt(5)
	v_add_f32_e32 v140, v140, v222
	s_waitcnt lgkmcnt(4)
	v_add_f32_e32 v141, v141, v223
	s_waitcnt lgkmcnt(3)
	v_add_f32_e32 v142, v142, v224
	s_waitcnt lgkmcnt(2)
	v_add_f32_e32 v143, v143, v225
	s_waitcnt lgkmcnt(1)
	v_add_f32_e32 v144, v144, v226
	s_waitcnt lgkmcnt(0)
	v_add_f32_e32 v145, v145, v227
	ds_bpermute_b32 v220, v169, v138
	ds_bpermute_b32 v221, v169, v139
	ds_bpermute_b32 v222, v169, v140
	ds_bpermute_b32 v223, v169, v141
	ds_bpermute_b32 v224, v169, v142
	ds_bpermute_b32 v225, v169, v143
	ds_bpermute_b32 v226, v169, v144
	ds_bpermute_b32 v227, v169, v145
	s_waitcnt lgkmcnt(7)
	v_add_f32_e32 v138, v138, v220
	s_waitcnt lgkmcnt(6)
	v_add_f32_e32 v139, v139, v221
	s_waitcnt lgkmcnt(5)
	v_add_f32_e32 v140, v140, v222
	s_waitcnt lgkmcnt(4)
	v_add_f32_e32 v141, v141, v223
	s_waitcnt lgkmcnt(3)
	v_add_f32_e32 v142, v142, v224
	s_waitcnt lgkmcnt(2)
	v_add_f32_e32 v143, v143, v225
	s_waitcnt lgkmcnt(1)
	v_add_f32_e32 v144, v144, v226
	s_waitcnt lgkmcnt(0)
	v_add_f32_e32 v145, v145, v227
	ds_bpermute_b32 v220, v171, v138
	ds_bpermute_b32 v221, v171, v139
	ds_bpermute_b32 v222, v171, v140
	ds_bpermute_b32 v223, v171, v141
	ds_bpermute_b32 v224, v171, v142
	ds_bpermute_b32 v225, v171, v143
	ds_bpermute_b32 v226, v171, v144
	ds_bpermute_b32 v227, v171, v145
	s_waitcnt lgkmcnt(7)
	v_add_f32_e32 v138, v138, v220
	s_waitcnt lgkmcnt(6)
	v_add_f32_e32 v139, v139, v221
	s_waitcnt lgkmcnt(5)
	v_add_f32_e32 v140, v140, v222
	s_waitcnt lgkmcnt(4)
	v_add_f32_e32 v141, v141, v223
	s_waitcnt lgkmcnt(3)
	v_add_f32_e32 v142, v142, v224
	s_waitcnt lgkmcnt(2)
	v_add_f32_e32 v143, v143, v225
	s_waitcnt lgkmcnt(1)
	v_add_f32_e32 v144, v144, v226
	s_waitcnt lgkmcnt(0)
	v_add_f32_e32 v145, v145, v227
	ds_bpermute_b32 v220, v172, v138
	ds_bpermute_b32 v221, v172, v139
	ds_bpermute_b32 v222, v172, v140
	ds_bpermute_b32 v223, v172, v141
	ds_bpermute_b32 v224, v172, v142
	ds_bpermute_b32 v225, v172, v143
	ds_bpermute_b32 v226, v172, v144
	ds_bpermute_b32 v227, v172, v145
	s_waitcnt lgkmcnt(7)
	v_add_f32_e32 v138, v138, v220
	s_waitcnt lgkmcnt(6)
	v_add_f32_e32 v139, v139, v221
	s_waitcnt lgkmcnt(5)
	v_add_f32_e32 v140, v140, v222
	s_waitcnt lgkmcnt(4)
	v_add_f32_e32 v141, v141, v223
	s_waitcnt lgkmcnt(3)
	v_add_f32_e32 v142, v142, v224
	s_waitcnt lgkmcnt(2)
	v_add_f32_e32 v143, v143, v225
	s_waitcnt lgkmcnt(1)
	v_add_f32_e32 v144, v144, v226
	s_waitcnt lgkmcnt(0)
	v_add_f32_e32 v145, v145, v227
	ds_bpermute_b32 v220, v173, v138
	ds_bpermute_b32 v221, v173, v139
	ds_bpermute_b32 v222, v173, v140
	ds_bpermute_b32 v223, v173, v141
	ds_bpermute_b32 v224, v173, v142
	ds_bpermute_b32 v225, v173, v143
	ds_bpermute_b32 v226, v173, v144
	ds_bpermute_b32 v227, v173, v145
	s_waitcnt lgkmcnt(7)
	v_add_f32_e32 v138, v138, v220
	s_waitcnt lgkmcnt(6)
	v_add_f32_e32 v139, v139, v221
	s_waitcnt lgkmcnt(5)
	v_add_f32_e32 v140, v140, v222
	s_waitcnt lgkmcnt(4)
	v_add_f32_e32 v141, v141, v223
	s_waitcnt lgkmcnt(3)
	v_add_f32_e32 v142, v142, v224
	s_waitcnt lgkmcnt(2)
	v_add_f32_e32 v143, v143, v225
	s_waitcnt lgkmcnt(1)
	v_add_f32_e32 v144, v144, v226
	s_waitcnt lgkmcnt(0)
	v_add_f32_e32 v145, v145, v227
	v_cmp_eq_u32_e32 vcc, 0, v174
	s_and_saveexec_b64 s[58:59], vcc
	global_store_dword v167, v130, s[10:11]
	global_store_dword v167, v131, s[10:11] offset:4
	global_store_dword v167, v132, s[10:11] offset:8
	global_store_dword v167, v133, s[10:11] offset:12
	global_store_dword v167, v134, s[10:11] offset:32
	global_store_dword v167, v135, s[10:11] offset:36
	global_store_dword v167, v136, s[10:11] offset:40
	global_store_dword v167, v137, s[10:11] offset:44
	global_store_dword v167, v138, s[10:11] offset:64
	global_store_dword v167, v139, s[10:11] offset:68
	global_store_dword v167, v140, s[10:11] offset:72
	global_store_dword v167, v141, s[10:11] offset:76
	global_store_dword v167, v142, s[10:11] offset:96
	global_store_dword v167, v143, s[10:11] offset:100
	global_store_dword v167, v144, s[10:11] offset:104
	global_store_dword v167, v145, s[10:11] offset:108
	s_mov_b64 exec, -1
	s_add_u32 s48, s48, 0x20000
	s_addc_u32 s49, s49, 0
	global_load_dword v130, v162, s[48:49]
	global_load_dword v212, v162, s[48:49] offset:128
	global_load_dword v131, v163, s[48:49]
	global_load_dword v213, v163, s[48:49] offset:128
	global_load_dword v132, v164, s[48:49]
	global_load_dword v214, v164, s[48:49] offset:128
	global_load_dword v133, v165, s[48:49]
	global_load_dword v215, v165, s[48:49] offset:128
	s_add_u32 s48, s48, 0x8000
	s_addc_u32 s49, s49, 0
	global_load_dword v134, v162, s[48:49]
	global_load_dword v216, v162, s[48:49] offset:128
	global_load_dword v135, v163, s[48:49]
	global_load_dword v217, v163, s[48:49] offset:128
	global_load_dword v136, v164, s[48:49]
	global_load_dword v218, v164, s[48:49] offset:128
	global_load_dword v137, v165, s[48:49]
	global_load_dword v219, v165, s[48:49] offset:128
	s_add_u32 s48, s48, 0x8000
	s_addc_u32 s49, s49, 0
	global_load_dword v138, v162, s[48:49]
	global_load_dword v220, v162, s[48:49] offset:128
	global_load_dword v139, v163, s[48:49]
	global_load_dword v221, v163, s[48:49] offset:128
	global_load_dword v140, v164, s[48:49]
	global_load_dword v222, v164, s[48:49] offset:128
	global_load_dword v141, v165, s[48:49]
	global_load_dword v223, v165, s[48:49] offset:128
	s_add_u32 s48, s48, 0x8000
	s_addc_u32 s49, s49, 0
	global_load_dword v142, v162, s[48:49]
	global_load_dword v224, v162, s[48:49] offset:128
	global_load_dword v143, v163, s[48:49]
	global_load_dword v225, v163, s[48:49] offset:128
	global_load_dword v144, v164, s[48:49]
	global_load_dword v226, v164, s[48:49] offset:128
	global_load_dword v145, v165, s[48:49]
	global_load_dword v227, v165, s[48:49] offset:128
	s_sub_u32 s48, s48, 0x18000
	s_subb_u32 s49, s49, 0
	s_waitcnt vmcnt(30)
	v_fmac_f32_e32 v130, v98, v175
	v_fmac_f32_e32 v212, v114, v176
	global_store_dword v162, v130, s[48:49]
	global_store_dword v162, v212, s[48:49] offset:128
	s_waitcnt vmcnt(30)
	v_fmac_f32_e32 v131, v99, v175
	v_fmac_f32_e32 v213, v115, v176
	global_store_dword v163, v131, s[48:49]
	global_store_dword v163, v213, s[48:49] offset:128
	s_waitcnt vmcnt(30)
	v_fmac_f32_e32 v132, v100, v175
	v_fmac_f32_e32 v214, v116, v176
	global_store_dword v164, v132, s[48:49]
	global_store_dword v164, v214, s[48:49] offset:128
	s_waitcnt vmcnt(30)
	v_fmac_f32_e32 v133, v101, v175
	v_fmac_f32_e32 v215, v117, v176
	global_store_dword v165, v133, s[48:49]
	global_store_dword v165, v215, s[48:49] offset:128
	s_add_u32 s48, s48, 0x8000
	s_addc_u32 s49, s49, 0
	s_waitcnt vmcnt(30)
	v_fmac_f32_e32 v134, v102, v175
	v_fmac_f32_e32 v216, v118, v176
	global_store_dword v162, v134, s[48:49]
	global_store_dword v162, v216, s[48:49] offset:128
	s_waitcnt vmcnt(30)
	v_fmac_f32_e32 v135, v103, v175
	v_fmac_f32_e32 v217, v119, v176
	global_store_dword v163, v135, s[48:49]
	global_store_dword v163, v217, s[48:49] offset:128
	s_waitcnt vmcnt(30)
	v_fmac_f32_e32 v136, v104, v175
	v_fmac_f32_e32 v218, v120, v176
	global_store_dword v164, v136, s[48:49]
	global_store_dword v164, v218, s[48:49] offset:128
	s_waitcnt vmcnt(30)
	v_fmac_f32_e32 v137, v105, v175
	v_fmac_f32_e32 v219, v121, v176
	global_store_dword v165, v137, s[48:49]
	global_store_dword v165, v219, s[48:49] offset:128
	s_add_u32 s48, s48, 0x8000
	s_addc_u32 s49, s49, 0
	s_waitcnt vmcnt(30)
	v_fmac_f32_e32 v138, v106, v175
	v_fmac_f32_e32 v220, v122, v176
	global_store_dword v162, v138, s[48:49]
	global_store_dword v162, v220, s[48:49] offset:128
	s_waitcnt vmcnt(30)
	v_fmac_f32_e32 v139, v107, v175
	v_fmac_f32_e32 v221, v123, v176
	global_store_dword v163, v139, s[48:49]
	global_store_dword v163, v221, s[48:49] offset:128
	s_waitcnt vmcnt(30)
	v_fmac_f32_e32 v140, v108, v175
	v_fmac_f32_e32 v222, v124, v176
	global_store_dword v164, v140, s[48:49]
	global_store_dword v164, v222, s[48:49] offset:128
	s_waitcnt vmcnt(30)
	v_fmac_f32_e32 v141, v109, v175
	v_fmac_f32_e32 v223, v125, v176
	global_store_dword v165, v141, s[48:49]
	global_store_dword v165, v223, s[48:49] offset:128
	s_add_u32 s48, s48, 0x8000
	s_addc_u32 s49, s49, 0
	s_waitcnt vmcnt(30)
	v_fmac_f32_e32 v142, v110, v175
	v_fmac_f32_e32 v224, v126, v176
	global_store_dword v162, v142, s[48:49]
	global_store_dword v162, v224, s[48:49] offset:128
	s_waitcnt vmcnt(30)
	v_fmac_f32_e32 v143, v111, v175
	v_fmac_f32_e32 v225, v127, v176
	global_store_dword v163, v143, s[48:49]
	global_store_dword v163, v225, s[48:49] offset:128
	s_waitcnt vmcnt(30)
	v_fmac_f32_e32 v144, v112, v175
	v_fmac_f32_e32 v226, v128, v176
	global_store_dword v164, v144, s[48:49]
	global_store_dword v164, v226, s[48:49] offset:128
	s_waitcnt vmcnt(30)
	v_fmac_f32_e32 v145, v113, v175
	v_fmac_f32_e32 v227, v129, v176
	global_store_dword v165, v145, s[48:49]
	global_store_dword v165, v227, s[48:49] offset:128
	s_sub_u32 s48, s48, 0x18000
	s_subb_u32 s49, s49, 0
	v_mul_f32_e32 v130, v130, v130
	v_fmac_f32_e32 v130, v212, v212
	v_mul_f32_e32 v131, v131, v131
	v_fmac_f32_e32 v131, v213, v213
	v_mul_f32_e32 v132, v132, v132
	v_fmac_f32_e32 v132, v214, v214
	v_mul_f32_e32 v133, v133, v133
	v_fmac_f32_e32 v133, v215, v215
	v_mul_f32_e32 v134, v134, v134
	v_fmac_f32_e32 v134, v216, v216
	v_mul_f32_e32 v135, v135, v135
	v_fmac_f32_e32 v135, v217, v217
	v_mul_f32_e32 v136, v136, v136
	v_fmac_f32_e32 v136, v218, v218
	v_mul_f32_e32 v137, v137, v137
	v_fmac_f32_e32 v137, v219, v219
	v_mul_f32_e32 v138, v138, v138
	v_fmac_f32_e32 v138, v220, v220
	v_mul_f32_e32 v139, v139, v139
	v_fmac_f32_e32 v139, v221, v221
	v_mul_f32_e32 v140, v140, v140
	v_fmac_f32_e32 v140, v222, v222
	v_mul_f32_e32 v141, v141, v141
	v_fmac_f32_e32 v141, v223, v223
	v_mul_f32_e32 v142, v142, v142
	v_fmac_f32_e32 v142, v224, v224
	v_mul_f32_e32 v143, v143, v143
	v_fmac_f32_e32 v143, v225, v225
	v_mul_f32_e32 v144, v144, v144
	v_fmac_f32_e32 v144, v226, v226
	v_mul_f32_e32 v145, v145, v145
	v_fmac_f32_e32 v145, v227, v227
	s_waitcnt lgkmcnt(0)
	ds_bpermute_b32 v212, v168, v130
	ds_bpermute_b32 v213, v168, v131
	ds_bpermute_b32 v214, v168, v132
	ds_bpermute_b32 v215, v168, v133
	ds_bpermute_b32 v216, v168, v134
	ds_bpermute_b32 v217, v168, v135
	ds_bpermute_b32 v218, v168, v136
	ds_bpermute_b32 v219, v168, v137
	s_waitcnt lgkmcnt(7)
	v_add_f32_e32 v130, v130, v212
	s_waitcnt lgkmcnt(6)
	v_add_f32_e32 v131, v131, v213
	s_waitcnt lgkmcnt(5)
	v_add_f32_e32 v132, v132, v214
	s_waitcnt lgkmcnt(4)
	v_add_f32_e32 v133, v133, v215
	s_waitcnt lgkmcnt(3)
	v_add_f32_e32 v134, v134, v216
	s_waitcnt lgkmcnt(2)
	v_add_f32_e32 v135, v135, v217
	s_waitcnt lgkmcnt(1)
	v_add_f32_e32 v136, v136, v218
	s_waitcnt lgkmcnt(0)
	v_add_f32_e32 v137, v137, v219
	ds_bpermute_b32 v212, v169, v130
	ds_bpermute_b32 v213, v169, v131
	ds_bpermute_b32 v214, v169, v132
	ds_bpermute_b32 v215, v169, v133
	ds_bpermute_b32 v216, v169, v134
	ds_bpermute_b32 v217, v169, v135
	ds_bpermute_b32 v218, v169, v136
	ds_bpermute_b32 v219, v169, v137
	s_waitcnt lgkmcnt(7)
	v_add_f32_e32 v130, v130, v212
	s_waitcnt lgkmcnt(6)
	v_add_f32_e32 v131, v131, v213
	s_waitcnt lgkmcnt(5)
	v_add_f32_e32 v132, v132, v214
	s_waitcnt lgkmcnt(4)
	v_add_f32_e32 v133, v133, v215
	s_waitcnt lgkmcnt(3)
	v_add_f32_e32 v134, v134, v216
	s_waitcnt lgkmcnt(2)
	v_add_f32_e32 v135, v135, v217
	s_waitcnt lgkmcnt(1)
	v_add_f32_e32 v136, v136, v218
	s_waitcnt lgkmcnt(0)
	v_add_f32_e32 v137, v137, v219
	ds_bpermute_b32 v212, v171, v130
	ds_bpermute_b32 v213, v171, v131
	ds_bpermute_b32 v214, v171, v132
	ds_bpermute_b32 v215, v171, v133
	ds_bpermute_b32 v216, v171, v134
	ds_bpermute_b32 v217, v171, v135
	ds_bpermute_b32 v218, v171, v136
	ds_bpermute_b32 v219, v171, v137
	s_waitcnt lgkmcnt(7)
	v_add_f32_e32 v130, v130, v212
	s_waitcnt lgkmcnt(6)
	v_add_f32_e32 v131, v131, v213
	s_waitcnt lgkmcnt(5)
	v_add_f32_e32 v132, v132, v214
	s_waitcnt lgkmcnt(4)
	v_add_f32_e32 v133, v133, v215
	s_waitcnt lgkmcnt(3)
	v_add_f32_e32 v134, v134, v216
	s_waitcnt lgkmcnt(2)
	v_add_f32_e32 v135, v135, v217
	s_waitcnt lgkmcnt(1)
	v_add_f32_e32 v136, v136, v218
	s_waitcnt lgkmcnt(0)
	v_add_f32_e32 v137, v137, v219
	ds_bpermute_b32 v212, v172, v130
	ds_bpermute_b32 v213, v172, v131
	ds_bpermute_b32 v214, v172, v132
	ds_bpermute_b32 v215, v172, v133
	ds_bpermute_b32 v216, v172, v134
	ds_bpermute_b32 v217, v172, v135
	ds_bpermute_b32 v218, v172, v136
	ds_bpermute_b32 v219, v172, v137
	s_waitcnt lgkmcnt(7)
	v_add_f32_e32 v130, v130, v212
	s_waitcnt lgkmcnt(6)
	v_add_f32_e32 v131, v131, v213
	s_waitcnt lgkmcnt(5)
	v_add_f32_e32 v132, v132, v214
	s_waitcnt lgkmcnt(4)
	v_add_f32_e32 v133, v133, v215
	s_waitcnt lgkmcnt(3)
	v_add_f32_e32 v134, v134, v216
	s_waitcnt lgkmcnt(2)
	v_add_f32_e32 v135, v135, v217
	s_waitcnt lgkmcnt(1)
	v_add_f32_e32 v136, v136, v218
	s_waitcnt lgkmcnt(0)
	v_add_f32_e32 v137, v137, v219
	ds_bpermute_b32 v212, v173, v130
	ds_bpermute_b32 v213, v173, v131
	ds_bpermute_b32 v214, v173, v132
	ds_bpermute_b32 v215, v173, v133
	ds_bpermute_b32 v216, v173, v134
	ds_bpermute_b32 v217, v173, v135
	ds_bpermute_b32 v218, v173, v136
	ds_bpermute_b32 v219, v173, v137
	s_waitcnt lgkmcnt(7)
	v_add_f32_e32 v130, v130, v212
	s_waitcnt lgkmcnt(6)
	v_add_f32_e32 v131, v131, v213
	s_waitcnt lgkmcnt(5)
	v_add_f32_e32 v132, v132, v214
	s_waitcnt lgkmcnt(4)
	v_add_f32_e32 v133, v133, v215
	s_waitcnt lgkmcnt(3)
	v_add_f32_e32 v134, v134, v216
	s_waitcnt lgkmcnt(2)
	v_add_f32_e32 v135, v135, v217
	s_waitcnt lgkmcnt(1)
	v_add_f32_e32 v136, v136, v218
	s_waitcnt lgkmcnt(0)
	v_add_f32_e32 v137, v137, v219
	ds_bpermute_b32 v220, v168, v138
	ds_bpermute_b32 v221, v168, v139
	ds_bpermute_b32 v222, v168, v140
	ds_bpermute_b32 v223, v168, v141
	ds_bpermute_b32 v224, v168, v142
	ds_bpermute_b32 v225, v168, v143
	ds_bpermute_b32 v226, v168, v144
	ds_bpermute_b32 v227, v168, v145
	s_waitcnt lgkmcnt(7)
	v_add_f32_e32 v138, v138, v220
	s_waitcnt lgkmcnt(6)
	v_add_f32_e32 v139, v139, v221
	s_waitcnt lgkmcnt(5)
	v_add_f32_e32 v140, v140, v222
	s_waitcnt lgkmcnt(4)
	v_add_f32_e32 v141, v141, v223
	s_waitcnt lgkmcnt(3)
	v_add_f32_e32 v142, v142, v224
	s_waitcnt lgkmcnt(2)
	v_add_f32_e32 v143, v143, v225
	s_waitcnt lgkmcnt(1)
	v_add_f32_e32 v144, v144, v226
	s_waitcnt lgkmcnt(0)
	v_add_f32_e32 v145, v145, v227
	ds_bpermute_b32 v220, v169, v138
	ds_bpermute_b32 v221, v169, v139
	ds_bpermute_b32 v222, v169, v140
	ds_bpermute_b32 v223, v169, v141
	ds_bpermute_b32 v224, v169, v142
	ds_bpermute_b32 v225, v169, v143
	ds_bpermute_b32 v226, v169, v144
	ds_bpermute_b32 v227, v169, v145
	s_waitcnt lgkmcnt(7)
	v_add_f32_e32 v138, v138, v220
	s_waitcnt lgkmcnt(6)
	v_add_f32_e32 v139, v139, v221
	s_waitcnt lgkmcnt(5)
	v_add_f32_e32 v140, v140, v222
	s_waitcnt lgkmcnt(4)
	v_add_f32_e32 v141, v141, v223
	s_waitcnt lgkmcnt(3)
	v_add_f32_e32 v142, v142, v224
	s_waitcnt lgkmcnt(2)
	v_add_f32_e32 v143, v143, v225
	s_waitcnt lgkmcnt(1)
	v_add_f32_e32 v144, v144, v226
	s_waitcnt lgkmcnt(0)
	v_add_f32_e32 v145, v145, v227
	ds_bpermute_b32 v220, v171, v138
	ds_bpermute_b32 v221, v171, v139
	ds_bpermute_b32 v222, v171, v140
	ds_bpermute_b32 v223, v171, v141
	ds_bpermute_b32 v224, v171, v142
	ds_bpermute_b32 v225, v171, v143
	ds_bpermute_b32 v226, v171, v144
	ds_bpermute_b32 v227, v171, v145
	s_waitcnt lgkmcnt(7)
	v_add_f32_e32 v138, v138, v220
	s_waitcnt lgkmcnt(6)
	v_add_f32_e32 v139, v139, v221
	s_waitcnt lgkmcnt(5)
	v_add_f32_e32 v140, v140, v222
	s_waitcnt lgkmcnt(4)
	v_add_f32_e32 v141, v141, v223
	s_waitcnt lgkmcnt(3)
	v_add_f32_e32 v142, v142, v224
	s_waitcnt lgkmcnt(2)
	v_add_f32_e32 v143, v143, v225
	s_waitcnt lgkmcnt(1)
	v_add_f32_e32 v144, v144, v226
	s_waitcnt lgkmcnt(0)
	v_add_f32_e32 v145, v145, v227
	ds_bpermute_b32 v220, v172, v138
	ds_bpermute_b32 v221, v172, v139
	ds_bpermute_b32 v222, v172, v140
	ds_bpermute_b32 v223, v172, v141
	ds_bpermute_b32 v224, v172, v142
	ds_bpermute_b32 v225, v172, v143
	ds_bpermute_b32 v226, v172, v144
	ds_bpermute_b32 v227, v172, v145
	s_waitcnt lgkmcnt(7)
	v_add_f32_e32 v138, v138, v220
	s_waitcnt lgkmcnt(6)
	v_add_f32_e32 v139, v139, v221
	s_waitcnt lgkmcnt(5)
	v_add_f32_e32 v140, v140, v222
	s_waitcnt lgkmcnt(4)
	v_add_f32_e32 v141, v141, v223
	s_waitcnt lgkmcnt(3)
	v_add_f32_e32 v142, v142, v224
	s_waitcnt lgkmcnt(2)
	v_add_f32_e32 v143, v143, v225
	s_waitcnt lgkmcnt(1)
	v_add_f32_e32 v144, v144, v226
	s_waitcnt lgkmcnt(0)
	v_add_f32_e32 v145, v145, v227
	ds_bpermute_b32 v220, v173, v138
	ds_bpermute_b32 v221, v173, v139
	ds_bpermute_b32 v222, v173, v140
	ds_bpermute_b32 v223, v173, v141
	ds_bpermute_b32 v224, v173, v142
	ds_bpermute_b32 v225, v173, v143
	ds_bpermute_b32 v226, v173, v144
	ds_bpermute_b32 v227, v173, v145
	s_waitcnt lgkmcnt(7)
	v_add_f32_e32 v138, v138, v220
	s_waitcnt lgkmcnt(6)
	v_add_f32_e32 v139, v139, v221
	s_waitcnt lgkmcnt(5)
	v_add_f32_e32 v140, v140, v222
	s_waitcnt lgkmcnt(4)
	v_add_f32_e32 v141, v141, v223
	s_waitcnt lgkmcnt(3)
	v_add_f32_e32 v142, v142, v224
	s_waitcnt lgkmcnt(2)
	v_add_f32_e32 v143, v143, v225
	s_waitcnt lgkmcnt(1)
	v_add_f32_e32 v144, v144, v226
	s_waitcnt lgkmcnt(0)
	v_add_f32_e32 v145, v145, v227
	v_cmp_eq_u32_e32 vcc, 0, v174
	s_and_saveexec_b64 s[58:59], vcc
	global_store_dword v167, v130, s[10:11] offset:128
	global_store_dword v167, v131, s[10:11] offset:132
	global_store_dword v167, v132, s[10:11] offset:136
	global_store_dword v167, v133, s[10:11] offset:140
	global_store_dword v167, v134, s[10:11] offset:160
	global_store_dword v167, v135, s[10:11] offset:164
	global_store_dword v167, v136, s[10:11] offset:168
	global_store_dword v167, v137, s[10:11] offset:172
	global_store_dword v167, v138, s[10:11] offset:192
	global_store_dword v167, v139, s[10:11] offset:196
	global_store_dword v167, v140, s[10:11] offset:200
	global_store_dword v167, v141, s[10:11] offset:204
	global_store_dword v167, v142, s[10:11] offset:224
	global_store_dword v167, v143, s[10:11] offset:228
	global_store_dword v167, v144, s[10:11] offset:232
	global_store_dword v167, v145, s[10:11] offset:236
	s_mov_b64 exec, -1
	s_sub_u32 s48, s48, 0x20000
	s_subb_u32 s49, s49, 0
	v_readlane_b32 s2, v246, 14
	s_nop 0
	s_add_i32 s16, s16, s2
	s_branch .Lhw_ffndown_tloop
